# stack: mods-GEMV loop fully unrolled with all 32 weight-row loads issued up front; MLP weight transposes issue both tile loads before waiting; attention/GEMM-relu canonicalize v_max removed; LN wave r
# speedup vs baseline: 1.0160x; 1.0070x over previous
.LBB0_25:
	s_mov_b32 s10, 0x6000
	s_mov_b32 s11, 0
	v_lshl_add_u64 v[222:223], v[42:43], 0, s[10:11]
	global_load_dwordx4 v[72:75], v[42:43], off
	global_load_dwordx4 v[76:79], v[222:223], off
	v_lshl_add_u64 v[224:225], v[222:223], 0, s[10:11]
	global_load_dwordx4 v[80:83], v[224:225], off
	v_lshl_add_u64 v[222:223], v[224:225], 0, s[10:11]
	global_load_dwordx4 v[84:87], v[222:223], off
	v_lshl_add_u64 v[224:225], v[222:223], 0, s[10:11]
	global_load_dwordx4 v[88:91], v[224:225], off
	v_lshl_add_u64 v[222:223], v[224:225], 0, s[10:11]
	global_load_dwordx4 v[92:95], v[222:223], off
	v_lshl_add_u64 v[224:225], v[222:223], 0, s[10:11]
	global_load_dwordx4 v[96:99], v[224:225], off
	v_lshl_add_u64 v[222:223], v[224:225], 0, s[10:11]
	global_load_dwordx4 v[100:103], v[222:223], off
	v_lshl_add_u64 v[224:225], v[222:223], 0, s[10:11]
	global_load_dwordx4 v[104:107], v[224:225], off
	v_lshl_add_u64 v[222:223], v[224:225], 0, s[10:11]
	global_load_dwordx4 v[108:111], v[222:223], off
	v_lshl_add_u64 v[224:225], v[222:223], 0, s[10:11]
	global_load_dwordx4 v[112:115], v[224:225], off
	v_lshl_add_u64 v[222:223], v[224:225], 0, s[10:11]
	global_load_dwordx4 v[116:119], v[222:223], off
	v_lshl_add_u64 v[224:225], v[222:223], 0, s[10:11]
	global_load_dwordx4 v[120:123], v[224:225], off
	v_lshl_add_u64 v[222:223], v[224:225], 0, s[10:11]
	global_load_dwordx4 v[124:127], v[222:223], off
	v_lshl_add_u64 v[224:225], v[222:223], 0, s[10:11]
	global_load_dwordx4 v[128:131], v[224:225], off
	v_lshl_add_u64 v[222:223], v[224:225], 0, s[10:11]
	global_load_dwordx4 v[132:135], v[222:223], off
	v_lshl_add_u64 v[224:225], v[222:223], 0, s[10:11]
	global_load_dwordx4 v[136:139], v[224:225], off
	v_lshl_add_u64 v[222:223], v[224:225], 0, s[10:11]
	global_load_dwordx4 v[148:151], v[222:223], off
	v_lshl_add_u64 v[224:225], v[222:223], 0, s[10:11]
	global_load_dwordx4 v[152:155], v[224:225], off
	v_lshl_add_u64 v[222:223], v[224:225], 0, s[10:11]
	global_load_dwordx4 v[156:159], v[222:223], off
	v_lshl_add_u64 v[224:225], v[222:223], 0, s[10:11]
	global_load_dwordx4 v[160:163], v[224:225], off
	v_lshl_add_u64 v[222:223], v[224:225], 0, s[10:11]
	global_load_dwordx4 v[164:167], v[222:223], off
	v_lshl_add_u64 v[224:225], v[222:223], 0, s[10:11]
	global_load_dwordx4 v[168:171], v[224:225], off
	v_lshl_add_u64 v[222:223], v[224:225], 0, s[10:11]
	global_load_dwordx4 v[172:175], v[222:223], off
	v_lshl_add_u64 v[224:225], v[222:223], 0, s[10:11]
	global_load_dwordx4 v[176:179], v[224:225], off
	v_lshl_add_u64 v[222:223], v[224:225], 0, s[10:11]
	global_load_dwordx4 v[180:183], v[222:223], off
	v_lshl_add_u64 v[224:225], v[222:223], 0, s[10:11]
	global_load_dwordx4 v[184:187], v[224:225], off
	v_lshl_add_u64 v[222:223], v[224:225], 0, s[10:11]
	global_load_dwordx4 v[188:191], v[222:223], off
	v_lshl_add_u64 v[224:225], v[222:223], 0, s[10:11]
	global_load_dwordx4 v[206:209], v[224:225], off
	v_lshl_add_u64 v[222:223], v[224:225], 0, s[10:11]
	global_load_dwordx4 v[210:213], v[222:223], off
	v_lshl_add_u64 v[224:225], v[222:223], 0, s[10:11]
	global_load_dwordx4 v[214:217], v[224:225], off
	v_lshl_add_u64 v[222:223], v[224:225], 0, s[10:11]
	global_load_dwordx4 v[218:221], v[222:223], off
	ds_read2st64_b64 v[54:57], v41 offset1:8
	ds_read2st64_b64 v[58:61], v41 offset0:16 offset1:24
	ds_read2st64_b64 v[62:65], v41 offset0:32 offset1:40
	ds_read2st64_b64 v[66:69], v41 offset0:48 offset1:56
	ds_read_b64 v[70:71], v41 offset:32768
	v_add_u32_e32 v41, 8, v41
	s_waitcnt vmcnt(31) lgkmcnt(4)
	v_pk_fma_f32 v[22:23], v[72:73], v[54:55], v[22:23] op_sel_hi:[1,0,1]
	v_pk_fma_f32 v[24:25], v[74:75], v[54:55], v[24:25] op_sel_hi:[1,0,1]
	v_pk_fma_f32 v[34:35], v[72:73], v[56:57], v[34:35] op_sel_hi:[1,0,1]
	v_pk_fma_f32 v[36:37], v[74:75], v[56:57], v[36:37] op_sel_hi:[1,0,1]
	s_waitcnt lgkmcnt(3)
	v_pk_fma_f32 v[30:31], v[72:73], v[58:59], v[30:31] op_sel_hi:[1,0,1]
	v_pk_fma_f32 v[32:33], v[74:75], v[58:59], v[32:33] op_sel_hi:[1,0,1]
	v_pk_fma_f32 v[26:27], v[72:73], v[60:61], v[26:27] op_sel_hi:[1,0,1]
	v_pk_fma_f32 v[28:29], v[74:75], v[60:61], v[28:29] op_sel_hi:[1,0,1]
	s_waitcnt lgkmcnt(2)
	v_pk_fma_f32 v[18:19], v[72:73], v[62:63], v[18:19] op_sel_hi:[1,0,1]
	v_pk_fma_f32 v[20:21], v[74:75], v[62:63], v[20:21] op_sel_hi:[1,0,1]
	v_pk_fma_f32 v[14:15], v[72:73], v[64:65], v[14:15] op_sel_hi:[1,0,1]
	v_pk_fma_f32 v[16:17], v[74:75], v[64:65], v[16:17] op_sel_hi:[1,0,1]
	s_waitcnt lgkmcnt(1)
	v_pk_fma_f32 v[10:11], v[72:73], v[66:67], v[10:11] op_sel_hi:[1,0,1]
	v_pk_fma_f32 v[12:13], v[74:75], v[66:67], v[12:13] op_sel_hi:[1,0,1]
	v_pk_fma_f32 v[6:7], v[72:73], v[68:69], v[6:7] op_sel_hi:[1,0,1]
	v_pk_fma_f32 v[8:9], v[74:75], v[68:69], v[8:9] op_sel_hi:[1,0,1]
	s_waitcnt lgkmcnt(0)
	v_pk_fma_f32 v[2:3], v[72:73], v[70:71], v[2:3] op_sel_hi:[1,0,1]
	v_pk_fma_f32 v[4:5], v[74:75], v[70:71], v[4:5] op_sel_hi:[1,0,1]
	s_waitcnt vmcnt(30)
	v_pk_fma_f32 v[22:23], v[76:77], v[54:55], v[22:23] op_sel:[0,1,0]
	v_pk_fma_f32 v[24:25], v[78:79], v[54:55], v[24:25] op_sel:[0,1,0]
	v_pk_fma_f32 v[34:35], v[76:77], v[56:57], v[34:35] op_sel:[0,1,0]
	v_pk_fma_f32 v[36:37], v[78:79], v[56:57], v[36:37] op_sel:[0,1,0]
	v_pk_fma_f32 v[30:31], v[76:77], v[58:59], v[30:31] op_sel:[0,1,0]
	v_pk_fma_f32 v[32:33], v[78:79], v[58:59], v[32:33] op_sel:[0,1,0]
	v_pk_fma_f32 v[26:27], v[76:77], v[60:61], v[26:27] op_sel:[0,1,0]
	v_pk_fma_f32 v[28:29], v[78:79], v[60:61], v[28:29] op_sel:[0,1,0]
	v_pk_fma_f32 v[18:19], v[76:77], v[62:63], v[18:19] op_sel:[0,1,0]
	v_pk_fma_f32 v[20:21], v[78:79], v[62:63], v[20:21] op_sel:[0,1,0]
	v_pk_fma_f32 v[14:15], v[76:77], v[64:65], v[14:15] op_sel:[0,1,0]
	v_pk_fma_f32 v[16:17], v[78:79], v[64:65], v[16:17] op_sel:[0,1,0]
	v_pk_fma_f32 v[10:11], v[76:77], v[66:67], v[10:11] op_sel:[0,1,0]
	v_pk_fma_f32 v[12:13], v[78:79], v[66:67], v[12:13] op_sel:[0,1,0]
	v_pk_fma_f32 v[6:7], v[76:77], v[68:69], v[6:7] op_sel:[0,1,0]
	v_pk_fma_f32 v[8:9], v[78:79], v[68:69], v[8:9] op_sel:[0,1,0]
	v_pk_fma_f32 v[2:3], v[76:77], v[70:71], v[2:3] op_sel:[0,1,0]
	v_pk_fma_f32 v[4:5], v[78:79], v[70:71], v[4:5] op_sel:[0,1,0]
	ds_read2st64_b64 v[54:57], v41 offset1:8
	ds_read2st64_b64 v[58:61], v41 offset0:16 offset1:24
	ds_read2st64_b64 v[62:65], v41 offset0:32 offset1:40
	ds_read2st64_b64 v[66:69], v41 offset0:48 offset1:56
	ds_read_b64 v[70:71], v41 offset:32768
	v_add_u32_e32 v41, 8, v41
	s_waitcnt vmcnt(29) lgkmcnt(4)
	v_pk_fma_f32 v[22:23], v[80:81], v[54:55], v[22:23] op_sel_hi:[1,0,1]
	v_pk_fma_f32 v[24:25], v[82:83], v[54:55], v[24:25] op_sel_hi:[1,0,1]
	v_pk_fma_f32 v[34:35], v[80:81], v[56:57], v[34:35] op_sel_hi:[1,0,1]
	v_pk_fma_f32 v[36:37], v[82:83], v[56:57], v[36:37] op_sel_hi:[1,0,1]
	s_waitcnt lgkmcnt(3)
	v_pk_fma_f32 v[30:31], v[80:81], v[58:59], v[30:31] op_sel_hi:[1,0,1]
	v_pk_fma_f32 v[32:33], v[82:83], v[58:59], v[32:33] op_sel_hi:[1,0,1]
	v_pk_fma_f32 v[26:27], v[80:81], v[60:61], v[26:27] op_sel_hi:[1,0,1]
	v_pk_fma_f32 v[28:29], v[82:83], v[60:61], v[28:29] op_sel_hi:[1,0,1]
	s_waitcnt lgkmcnt(2)
	v_pk_fma_f32 v[18:19], v[80:81], v[62:63], v[18:19] op_sel_hi:[1,0,1]
	v_pk_fma_f32 v[20:21], v[82:83], v[62:63], v[20:21] op_sel_hi:[1,0,1]
	v_pk_fma_f32 v[14:15], v[80:81], v[64:65], v[14:15] op_sel_hi:[1,0,1]
	v_pk_fma_f32 v[16:17], v[82:83], v[64:65], v[16:17] op_sel_hi:[1,0,1]
	s_waitcnt lgkmcnt(1)
	v_pk_fma_f32 v[10:11], v[80:81], v[66:67], v[10:11] op_sel_hi:[1,0,1]
	v_pk_fma_f32 v[12:13], v[82:83], v[66:67], v[12:13] op_sel_hi:[1,0,1]
	v_pk_fma_f32 v[6:7], v[80:81], v[68:69], v[6:7] op_sel_hi:[1,0,1]
	v_pk_fma_f32 v[8:9], v[82:83], v[68:69], v[8:9] op_sel_hi:[1,0,1]
	s_waitcnt lgkmcnt(0)
	v_pk_fma_f32 v[2:3], v[80:81], v[70:71], v[2:3] op_sel_hi:[1,0,1]
	v_pk_fma_f32 v[4:5], v[82:83], v[70:71], v[4:5] op_sel_hi:[1,0,1]
	s_waitcnt vmcnt(28)
	v_pk_fma_f32 v[22:23], v[84:85], v[54:55], v[22:23] op_sel:[0,1,0]
	v_pk_fma_f32 v[24:25], v[86:87], v[54:55], v[24:25] op_sel:[0,1,0]
	v_pk_fma_f32 v[34:35], v[84:85], v[56:57], v[34:35] op_sel:[0,1,0]
	v_pk_fma_f32 v[36:37], v[86:87], v[56:57], v[36:37] op_sel:[0,1,0]
	v_pk_fma_f32 v[30:31], v[84:85], v[58:59], v[30:31] op_sel:[0,1,0]
	v_pk_fma_f32 v[32:33], v[86:87], v[58:59], v[32:33] op_sel:[0,1,0]
	v_pk_fma_f32 v[26:27], v[84:85], v[60:61], v[26:27] op_sel:[0,1,0]
	v_pk_fma_f32 v[28:29], v[86:87], v[60:61], v[28:29] op_sel:[0,1,0]
	v_pk_fma_f32 v[18:19], v[84:85], v[62:63], v[18:19] op_sel:[0,1,0]
	v_pk_fma_f32 v[20:21], v[86:87], v[62:63], v[20:21] op_sel:[0,1,0]
	v_pk_fma_f32 v[14:15], v[84:85], v[64:65], v[14:15] op_sel:[0,1,0]
	v_pk_fma_f32 v[16:17], v[86:87], v[64:65], v[16:17] op_sel:[0,1,0]
	v_pk_fma_f32 v[10:11], v[84:85], v[66:67], v[10:11] op_sel:[0,1,0]
	v_pk_fma_f32 v[12:13], v[86:87], v[66:67], v[12:13] op_sel:[0,1,0]
	v_pk_fma_f32 v[6:7], v[84:85], v[68:69], v[6:7] op_sel:[0,1,0]
	v_pk_fma_f32 v[8:9], v[86:87], v[68:69], v[8:9] op_sel:[0,1,0]
	v_pk_fma_f32 v[2:3], v[84:85], v[70:71], v[2:3] op_sel:[0,1,0]
	v_pk_fma_f32 v[4:5], v[86:87], v[70:71], v[4:5] op_sel:[0,1,0]
	ds_read2st64_b64 v[54:57], v41 offset1:8
	ds_read2st64_b64 v[58:61], v41 offset0:16 offset1:24
	ds_read2st64_b64 v[62:65], v41 offset0:32 offset1:40
	ds_read2st64_b64 v[66:69], v41 offset0:48 offset1:56
	ds_read_b64 v[70:71], v41 offset:32768
	v_add_u32_e32 v41, 8, v41
	s_waitcnt vmcnt(27) lgkmcnt(4)
	v_pk_fma_f32 v[22:23], v[88:89], v[54:55], v[22:23] op_sel_hi:[1,0,1]
	v_pk_fma_f32 v[24:25], v[90:91], v[54:55], v[24:25] op_sel_hi:[1,0,1]
	v_pk_fma_f32 v[34:35], v[88:89], v[56:57], v[34:35] op_sel_hi:[1,0,1]
	v_pk_fma_f32 v[36:37], v[90:91], v[56:57], v[36:37] op_sel_hi:[1,0,1]
	s_waitcnt lgkmcnt(3)
	v_pk_fma_f32 v[30:31], v[88:89], v[58:59], v[30:31] op_sel_hi:[1,0,1]
	v_pk_fma_f32 v[32:33], v[90:91], v[58:59], v[32:33] op_sel_hi:[1,0,1]
	v_pk_fma_f32 v[26:27], v[88:89], v[60:61], v[26:27] op_sel_hi:[1,0,1]
	v_pk_fma_f32 v[28:29], v[90:91], v[60:61], v[28:29] op_sel_hi:[1,0,1]
	s_waitcnt lgkmcnt(2)
	v_pk_fma_f32 v[18:19], v[88:89], v[62:63], v[18:19] op_sel_hi:[1,0,1]
	v_pk_fma_f32 v[20:21], v[90:91], v[62:63], v[20:21] op_sel_hi:[1,0,1]
	v_pk_fma_f32 v[14:15], v[88:89], v[64:65], v[14:15] op_sel_hi:[1,0,1]
	v_pk_fma_f32 v[16:17], v[90:91], v[64:65], v[16:17] op_sel_hi:[1,0,1]
	s_waitcnt lgkmcnt(1)
	v_pk_fma_f32 v[10:11], v[88:89], v[66:67], v[10:11] op_sel_hi:[1,0,1]
	v_pk_fma_f32 v[12:13], v[90:91], v[66:67], v[12:13] op_sel_hi:[1,0,1]
	v_pk_fma_f32 v[6:7], v[88:89], v[68:69], v[6:7] op_sel_hi:[1,0,1]
	v_pk_fma_f32 v[8:9], v[90:91], v[68:69], v[8:9] op_sel_hi:[1,0,1]
	s_waitcnt lgkmcnt(0)
	v_pk_fma_f32 v[2:3], v[88:89], v[70:71], v[2:3] op_sel_hi:[1,0,1]
	v_pk_fma_f32 v[4:5], v[90:91], v[70:71], v[4:5] op_sel_hi:[1,0,1]
	s_waitcnt vmcnt(26)
	v_pk_fma_f32 v[22:23], v[92:93], v[54:55], v[22:23] op_sel:[0,1,0]
	v_pk_fma_f32 v[24:25], v[94:95], v[54:55], v[24:25] op_sel:[0,1,0]
	v_pk_fma_f32 v[34:35], v[92:93], v[56:57], v[34:35] op_sel:[0,1,0]
	v_pk_fma_f32 v[36:37], v[94:95], v[56:57], v[36:37] op_sel:[0,1,0]
	v_pk_fma_f32 v[30:31], v[92:93], v[58:59], v[30:31] op_sel:[0,1,0]
	v_pk_fma_f32 v[32:33], v[94:95], v[58:59], v[32:33] op_sel:[0,1,0]
	v_pk_fma_f32 v[26:27], v[92:93], v[60:61], v[26:27] op_sel:[0,1,0]
	v_pk_fma_f32 v[28:29], v[94:95], v[60:61], v[28:29] op_sel:[0,1,0]
	v_pk_fma_f32 v[18:19], v[92:93], v[62:63], v[18:19] op_sel:[0,1,0]
	v_pk_fma_f32 v[20:21], v[94:95], v[62:63], v[20:21] op_sel:[0,1,0]
	v_pk_fma_f32 v[14:15], v[92:93], v[64:65], v[14:15] op_sel:[0,1,0]
	v_pk_fma_f32 v[16:17], v[94:95], v[64:65], v[16:17] op_sel:[0,1,0]
	v_pk_fma_f32 v[10:11], v[92:93], v[66:67], v[10:11] op_sel:[0,1,0]
	v_pk_fma_f32 v[12:13], v[94:95], v[66:67], v[12:13] op_sel:[0,1,0]
	v_pk_fma_f32 v[6:7], v[92:93], v[68:69], v[6:7] op_sel:[0,1,0]
	v_pk_fma_f32 v[8:9], v[94:95], v[68:69], v[8:9] op_sel:[0,1,0]
	v_pk_fma_f32 v[2:3], v[92:93], v[70:71], v[2:3] op_sel:[0,1,0]
	v_pk_fma_f32 v[4:5], v[94:95], v[70:71], v[4:5] op_sel:[0,1,0]
	ds_read2st64_b64 v[54:57], v41 offset1:8
	ds_read2st64_b64 v[58:61], v41 offset0:16 offset1:24
	ds_read2st64_b64 v[62:65], v41 offset0:32 offset1:40
	ds_read2st64_b64 v[66:69], v41 offset0:48 offset1:56
	ds_read_b64 v[70:71], v41 offset:32768
	v_add_u32_e32 v41, 8, v41
	s_waitcnt vmcnt(25) lgkmcnt(4)
	v_pk_fma_f32 v[22:23], v[96:97], v[54:55], v[22:23] op_sel_hi:[1,0,1]
	v_pk_fma_f32 v[24:25], v[98:99], v[54:55], v[24:25] op_sel_hi:[1,0,1]
	v_pk_fma_f32 v[34:35], v[96:97], v[56:57], v[34:35] op_sel_hi:[1,0,1]
	v_pk_fma_f32 v[36:37], v[98:99], v[56:57], v[36:37] op_sel_hi:[1,0,1]
	s_waitcnt lgkmcnt(3)
	v_pk_fma_f32 v[30:31], v[96:97], v[58:59], v[30:31] op_sel_hi:[1,0,1]
	v_pk_fma_f32 v[32:33], v[98:99], v[58:59], v[32:33] op_sel_hi:[1,0,1]
	v_pk_fma_f32 v[26:27], v[96:97], v[60:61], v[26:27] op_sel_hi:[1,0,1]
	v_pk_fma_f32 v[28:29], v[98:99], v[60:61], v[28:29] op_sel_hi:[1,0,1]
	s_waitcnt lgkmcnt(2)
	v_pk_fma_f32 v[18:19], v[96:97], v[62:63], v[18:19] op_sel_hi:[1,0,1]
	v_pk_fma_f32 v[20:21], v[98:99], v[62:63], v[20:21] op_sel_hi:[1,0,1]
	v_pk_fma_f32 v[14:15], v[96:97], v[64:65], v[14:15] op_sel_hi:[1,0,1]
	v_pk_fma_f32 v[16:17], v[98:99], v[64:65], v[16:17] op_sel_hi:[1,0,1]
	s_waitcnt lgkmcnt(1)
	v_pk_fma_f32 v[10:11], v[96:97], v[66:67], v[10:11] op_sel_hi:[1,0,1]
	v_pk_fma_f32 v[12:13], v[98:99], v[66:67], v[12:13] op_sel_hi:[1,0,1]
	v_pk_fma_f32 v[6:7], v[96:97], v[68:69], v[6:7] op_sel_hi:[1,0,1]
	v_pk_fma_f32 v[8:9], v[98:99], v[68:69], v[8:9] op_sel_hi:[1,0,1]
	s_waitcnt lgkmcnt(0)
	v_pk_fma_f32 v[2:3], v[96:97], v[70:71], v[2:3] op_sel_hi:[1,0,1]
	v_pk_fma_f32 v[4:5], v[98:99], v[70:71], v[4:5] op_sel_hi:[1,0,1]
	s_waitcnt vmcnt(24)
	v_pk_fma_f32 v[22:23], v[100:101], v[54:55], v[22:23] op_sel:[0,1,0]
	v_pk_fma_f32 v[24:25], v[102:103], v[54:55], v[24:25] op_sel:[0,1,0]
	v_pk_fma_f32 v[34:35], v[100:101], v[56:57], v[34:35] op_sel:[0,1,0]
	v_pk_fma_f32 v[36:37], v[102:103], v[56:57], v[36:37] op_sel:[0,1,0]
	v_pk_fma_f32 v[30:31], v[100:101], v[58:59], v[30:31] op_sel:[0,1,0]
	v_pk_fma_f32 v[32:33], v[102:103], v[58:59], v[32:33] op_sel:[0,1,0]
	v_pk_fma_f32 v[26:27], v[100:101], v[60:61], v[26:27] op_sel:[0,1,0]
	v_pk_fma_f32 v[28:29], v[102:103], v[60:61], v[28:29] op_sel:[0,1,0]
	v_pk_fma_f32 v[18:19], v[100:101], v[62:63], v[18:19] op_sel:[0,1,0]
	v_pk_fma_f32 v[20:21], v[102:103], v[62:63], v[20:21] op_sel:[0,1,0]
	v_pk_fma_f32 v[14:15], v[100:101], v[64:65], v[14:15] op_sel:[0,1,0]
	v_pk_fma_f32 v[16:17], v[102:103], v[64:65], v[16:17] op_sel:[0,1,0]
	v_pk_fma_f32 v[10:11], v[100:101], v[66:67], v[10:11] op_sel:[0,1,0]
	v_pk_fma_f32 v[12:13], v[102:103], v[66:67], v[12:13] op_sel:[0,1,0]
	v_pk_fma_f32 v[6:7], v[100:101], v[68:69], v[6:7] op_sel:[0,1,0]
	v_pk_fma_f32 v[8:9], v[102:103], v[68:69], v[8:9] op_sel:[0,1,0]
	v_pk_fma_f32 v[2:3], v[100:101], v[70:71], v[2:3] op_sel:[0,1,0]
	v_pk_fma_f32 v[4:5], v[102:103], v[70:71], v[4:5] op_sel:[0,1,0]
	ds_read2st64_b64 v[54:57], v41 offset1:8
	ds_read2st64_b64 v[58:61], v41 offset0:16 offset1:24
	ds_read2st64_b64 v[62:65], v41 offset0:32 offset1:40
	ds_read2st64_b64 v[66:69], v41 offset0:48 offset1:56
	ds_read_b64 v[70:71], v41 offset:32768
	v_add_u32_e32 v41, 8, v41
	s_waitcnt vmcnt(23) lgkmcnt(4)
	v_pk_fma_f32 v[22:23], v[104:105], v[54:55], v[22:23] op_sel_hi:[1,0,1]
	v_pk_fma_f32 v[24:25], v[106:107], v[54:55], v[24:25] op_sel_hi:[1,0,1]
	v_pk_fma_f32 v[34:35], v[104:105], v[56:57], v[34:35] op_sel_hi:[1,0,1]
	v_pk_fma_f32 v[36:37], v[106:107], v[56:57], v[36:37] op_sel_hi:[1,0,1]
	s_waitcnt lgkmcnt(3)
	v_pk_fma_f32 v[30:31], v[104:105], v[58:59], v[30:31] op_sel_hi:[1,0,1]
	v_pk_fma_f32 v[32:33], v[106:107], v[58:59], v[32:33] op_sel_hi:[1,0,1]
	v_pk_fma_f32 v[26:27], v[104:105], v[60:61], v[26:27] op_sel_hi:[1,0,1]
	v_pk_fma_f32 v[28:29], v[106:107], v[60:61], v[28:29] op_sel_hi:[1,0,1]
	s_waitcnt lgkmcnt(2)
	v_pk_fma_f32 v[18:19], v[104:105], v[62:63], v[18:19] op_sel_hi:[1,0,1]
	v_pk_fma_f32 v[20:21], v[106:107], v[62:63], v[20:21] op_sel_hi:[1,0,1]
	v_pk_fma_f32 v[14:15], v[104:105], v[64:65], v[14:15] op_sel_hi:[1,0,1]
	v_pk_fma_f32 v[16:17], v[106:107], v[64:65], v[16:17] op_sel_hi:[1,0,1]
	s_waitcnt lgkmcnt(1)
	v_pk_fma_f32 v[10:11], v[104:105], v[66:67], v[10:11] op_sel_hi:[1,0,1]
	v_pk_fma_f32 v[12:13], v[106:107], v[66:67], v[12:13] op_sel_hi:[1,0,1]
	v_pk_fma_f32 v[6:7], v[104:105], v[68:69], v[6:7] op_sel_hi:[1,0,1]
	v_pk_fma_f32 v[8:9], v[106:107], v[68:69], v[8:9] op_sel_hi:[1,0,1]
	s_waitcnt lgkmcnt(0)
	v_pk_fma_f32 v[2:3], v[104:105], v[70:71], v[2:3] op_sel_hi:[1,0,1]
	v_pk_fma_f32 v[4:5], v[106:107], v[70:71], v[4:5] op_sel_hi:[1,0,1]
	s_waitcnt vmcnt(22)
	v_pk_fma_f32 v[22:23], v[108:109], v[54:55], v[22:23] op_sel:[0,1,0]
	v_pk_fma_f32 v[24:25], v[110:111], v[54:55], v[24:25] op_sel:[0,1,0]
	v_pk_fma_f32 v[34:35], v[108:109], v[56:57], v[34:35] op_sel:[0,1,0]
	v_pk_fma_f32 v[36:37], v[110:111], v[56:57], v[36:37] op_sel:[0,1,0]
	v_pk_fma_f32 v[30:31], v[108:109], v[58:59], v[30:31] op_sel:[0,1,0]
	v_pk_fma_f32 v[32:33], v[110:111], v[58:59], v[32:33] op_sel:[0,1,0]
	v_pk_fma_f32 v[26:27], v[108:109], v[60:61], v[26:27] op_sel:[0,1,0]
	v_pk_fma_f32 v[28:29], v[110:111], v[60:61], v[28:29] op_sel:[0,1,0]
	v_pk_fma_f32 v[18:19], v[108:109], v[62:63], v[18:19] op_sel:[0,1,0]
	v_pk_fma_f32 v[20:21], v[110:111], v[62:63], v[20:21] op_sel:[0,1,0]
	v_pk_fma_f32 v[14:15], v[108:109], v[64:65], v[14:15] op_sel:[0,1,0]
	v_pk_fma_f32 v[16:17], v[110:111], v[64:65], v[16:17] op_sel:[0,1,0]
	v_pk_fma_f32 v[10:11], v[108:109], v[66:67], v[10:11] op_sel:[0,1,0]
	v_pk_fma_f32 v[12:13], v[110:111], v[66:67], v[12:13] op_sel:[0,1,0]
	v_pk_fma_f32 v[6:7], v[108:109], v[68:69], v[6:7] op_sel:[0,1,0]
	v_pk_fma_f32 v[8:9], v[110:111], v[68:69], v[8:9] op_sel:[0,1,0]
	v_pk_fma_f32 v[2:3], v[108:109], v[70:71], v[2:3] op_sel:[0,1,0]
	v_pk_fma_f32 v[4:5], v[110:111], v[70:71], v[4:5] op_sel:[0,1,0]
	ds_read2st64_b64 v[54:57], v41 offset1:8
	ds_read2st64_b64 v[58:61], v41 offset0:16 offset1:24
	ds_read2st64_b64 v[62:65], v41 offset0:32 offset1:40
	ds_read2st64_b64 v[66:69], v41 offset0:48 offset1:56
	ds_read_b64 v[70:71], v41 offset:32768
	v_add_u32_e32 v41, 8, v41
	s_waitcnt vmcnt(21) lgkmcnt(4)
	v_pk_fma_f32 v[22:23], v[112:113], v[54:55], v[22:23] op_sel_hi:[1,0,1]
	v_pk_fma_f32 v[24:25], v[114:115], v[54:55], v[24:25] op_sel_hi:[1,0,1]
	v_pk_fma_f32 v[34:35], v[112:113], v[56:57], v[34:35] op_sel_hi:[1,0,1]
	v_pk_fma_f32 v[36:37], v[114:115], v[56:57], v[36:37] op_sel_hi:[1,0,1]
	s_waitcnt lgkmcnt(3)
	v_pk_fma_f32 v[30:31], v[112:113], v[58:59], v[30:31] op_sel_hi:[1,0,1]
	v_pk_fma_f32 v[32:33], v[114:115], v[58:59], v[32:33] op_sel_hi:[1,0,1]
	v_pk_fma_f32 v[26:27], v[112:113], v[60:61], v[26:27] op_sel_hi:[1,0,1]
	v_pk_fma_f32 v[28:29], v[114:115], v[60:61], v[28:29] op_sel_hi:[1,0,1]
	s_waitcnt lgkmcnt(2)
	v_pk_fma_f32 v[18:19], v[112:113], v[62:63], v[18:19] op_sel_hi:[1,0,1]
	v_pk_fma_f32 v[20:21], v[114:115], v[62:63], v[20:21] op_sel_hi:[1,0,1]
	v_pk_fma_f32 v[14:15], v[112:113], v[64:65], v[14:15] op_sel_hi:[1,0,1]
	v_pk_fma_f32 v[16:17], v[114:115], v[64:65], v[16:17] op_sel_hi:[1,0,1]
	s_waitcnt lgkmcnt(1)
	v_pk_fma_f32 v[10:11], v[112:113], v[66:67], v[10:11] op_sel_hi:[1,0,1]
	v_pk_fma_f32 v[12:13], v[114:115], v[66:67], v[12:13] op_sel_hi:[1,0,1]
	v_pk_fma_f32 v[6:7], v[112:113], v[68:69], v[6:7] op_sel_hi:[1,0,1]
	v_pk_fma_f32 v[8:9], v[114:115], v[68:69], v[8:9] op_sel_hi:[1,0,1]
	s_waitcnt lgkmcnt(0)
	v_pk_fma_f32 v[2:3], v[112:113], v[70:71], v[2:3] op_sel_hi:[1,0,1]
	v_pk_fma_f32 v[4:5], v[114:115], v[70:71], v[4:5] op_sel_hi:[1,0,1]
	s_waitcnt vmcnt(20)
	v_pk_fma_f32 v[22:23], v[116:117], v[54:55], v[22:23] op_sel:[0,1,0]
	v_pk_fma_f32 v[24:25], v[118:119], v[54:55], v[24:25] op_sel:[0,1,0]
	v_pk_fma_f32 v[34:35], v[116:117], v[56:57], v[34:35] op_sel:[0,1,0]
	v_pk_fma_f32 v[36:37], v[118:119], v[56:57], v[36:37] op_sel:[0,1,0]
	v_pk_fma_f32 v[30:31], v[116:117], v[58:59], v[30:31] op_sel:[0,1,0]
	v_pk_fma_f32 v[32:33], v[118:119], v[58:59], v[32:33] op_sel:[0,1,0]
	v_pk_fma_f32 v[26:27], v[116:117], v[60:61], v[26:27] op_sel:[0,1,0]
	v_pk_fma_f32 v[28:29], v[118:119], v[60:61], v[28:29] op_sel:[0,1,0]
	v_pk_fma_f32 v[18:19], v[116:117], v[62:63], v[18:19] op_sel:[0,1,0]
	v_pk_fma_f32 v[20:21], v[118:119], v[62:63], v[20:21] op_sel:[0,1,0]
	v_pk_fma_f32 v[14:15], v[116:117], v[64:65], v[14:15] op_sel:[0,1,0]
	v_pk_fma_f32 v[16:17], v[118:119], v[64:65], v[16:17] op_sel:[0,1,0]
	v_pk_fma_f32 v[10:11], v[116:117], v[66:67], v[10:11] op_sel:[0,1,0]
	v_pk_fma_f32 v[12:13], v[118:119], v[66:67], v[12:13] op_sel:[0,1,0]
	v_pk_fma_f32 v[6:7], v[116:117], v[68:69], v[6:7] op_sel:[0,1,0]
	v_pk_fma_f32 v[8:9], v[118:119], v[68:69], v[8:9] op_sel:[0,1,0]
	v_pk_fma_f32 v[2:3], v[116:117], v[70:71], v[2:3] op_sel:[0,1,0]
	v_pk_fma_f32 v[4:5], v[118:119], v[70:71], v[4:5] op_sel:[0,1,0]
	ds_read2st64_b64 v[54:57], v41 offset1:8
	ds_read2st64_b64 v[58:61], v41 offset0:16 offset1:24
	ds_read2st64_b64 v[62:65], v41 offset0:32 offset1:40
	ds_read2st64_b64 v[66:69], v41 offset0:48 offset1:56
	ds_read_b64 v[70:71], v41 offset:32768
	v_add_u32_e32 v41, 8, v41
	s_waitcnt vmcnt(19) lgkmcnt(4)
	v_pk_fma_f32 v[22:23], v[120:121], v[54:55], v[22:23] op_sel_hi:[1,0,1]
	v_pk_fma_f32 v[24:25], v[122:123], v[54:55], v[24:25] op_sel_hi:[1,0,1]
	v_pk_fma_f32 v[34:35], v[120:121], v[56:57], v[34:35] op_sel_hi:[1,0,1]
	v_pk_fma_f32 v[36:37], v[122:123], v[56:57], v[36:37] op_sel_hi:[1,0,1]
	s_waitcnt lgkmcnt(3)
	v_pk_fma_f32 v[30:31], v[120:121], v[58:59], v[30:31] op_sel_hi:[1,0,1]
	v_pk_fma_f32 v[32:33], v[122:123], v[58:59], v[32:33] op_sel_hi:[1,0,1]
	v_pk_fma_f32 v[26:27], v[120:121], v[60:61], v[26:27] op_sel_hi:[1,0,1]
	v_pk_fma_f32 v[28:29], v[122:123], v[60:61], v[28:29] op_sel_hi:[1,0,1]
	s_waitcnt lgkmcnt(2)
	v_pk_fma_f32 v[18:19], v[120:121], v[62:63], v[18:19] op_sel_hi:[1,0,1]
	v_pk_fma_f32 v[20:21], v[122:123], v[62:63], v[20:21] op_sel_hi:[1,0,1]
	v_pk_fma_f32 v[14:15], v[120:121], v[64:65], v[14:15] op_sel_hi:[1,0,1]
	v_pk_fma_f32 v[16:17], v[122:123], v[64:65], v[16:17] op_sel_hi:[1,0,1]
	s_waitcnt lgkmcnt(1)
	v_pk_fma_f32 v[10:11], v[120:121], v[66:67], v[10:11] op_sel_hi:[1,0,1]
	v_pk_fma_f32 v[12:13], v[122:123], v[66:67], v[12:13] op_sel_hi:[1,0,1]
	v_pk_fma_f32 v[6:7], v[120:121], v[68:69], v[6:7] op_sel_hi:[1,0,1]
	v_pk_fma_f32 v[8:9], v[122:123], v[68:69], v[8:9] op_sel_hi:[1,0,1]
	s_waitcnt lgkmcnt(0)
	v_pk_fma_f32 v[2:3], v[120:121], v[70:71], v[2:3] op_sel_hi:[1,0,1]
	v_pk_fma_f32 v[4:5], v[122:123], v[70:71], v[4:5] op_sel_hi:[1,0,1]
	s_waitcnt vmcnt(18)
	v_pk_fma_f32 v[22:23], v[124:125], v[54:55], v[22:23] op_sel:[0,1,0]
	v_pk_fma_f32 v[24:25], v[126:127], v[54:55], v[24:25] op_sel:[0,1,0]
	v_pk_fma_f32 v[34:35], v[124:125], v[56:57], v[34:35] op_sel:[0,1,0]
	v_pk_fma_f32 v[36:37], v[126:127], v[56:57], v[36:37] op_sel:[0,1,0]
	v_pk_fma_f32 v[30:31], v[124:125], v[58:59], v[30:31] op_sel:[0,1,0]
	v_pk_fma_f32 v[32:33], v[126:127], v[58:59], v[32:33] op_sel:[0,1,0]
	v_pk_fma_f32 v[26:27], v[124:125], v[60:61], v[26:27] op_sel:[0,1,0]
	v_pk_fma_f32 v[28:29], v[126:127], v[60:61], v[28:29] op_sel:[0,1,0]
	v_pk_fma_f32 v[18:19], v[124:125], v[62:63], v[18:19] op_sel:[0,1,0]
	v_pk_fma_f32 v[20:21], v[126:127], v[62:63], v[20:21] op_sel:[0,1,0]
	v_pk_fma_f32 v[14:15], v[124:125], v[64:65], v[14:15] op_sel:[0,1,0]
	v_pk_fma_f32 v[16:17], v[126:127], v[64:65], v[16:17] op_sel:[0,1,0]
	v_pk_fma_f32 v[10:11], v[124:125], v[66:67], v[10:11] op_sel:[0,1,0]
	v_pk_fma_f32 v[12:13], v[126:127], v[66:67], v[12:13] op_sel:[0,1,0]
	v_pk_fma_f32 v[6:7], v[124:125], v[68:69], v[6:7] op_sel:[0,1,0]
	v_pk_fma_f32 v[8:9], v[126:127], v[68:69], v[8:9] op_sel:[0,1,0]
	v_pk_fma_f32 v[2:3], v[124:125], v[70:71], v[2:3] op_sel:[0,1,0]
	v_pk_fma_f32 v[4:5], v[126:127], v[70:71], v[4:5] op_sel:[0,1,0]
	ds_read2st64_b64 v[54:57], v41 offset1:8
	ds_read2st64_b64 v[58:61], v41 offset0:16 offset1:24
	ds_read2st64_b64 v[62:65], v41 offset0:32 offset1:40
	ds_read2st64_b64 v[66:69], v41 offset0:48 offset1:56
	ds_read_b64 v[70:71], v41 offset:32768
	v_add_u32_e32 v41, 8, v41
	s_waitcnt vmcnt(17) lgkmcnt(4)
	v_pk_fma_f32 v[22:23], v[128:129], v[54:55], v[22:23] op_sel_hi:[1,0,1]
	v_pk_fma_f32 v[24:25], v[130:131], v[54:55], v[24:25] op_sel_hi:[1,0,1]
	v_pk_fma_f32 v[34:35], v[128:129], v[56:57], v[34:35] op_sel_hi:[1,0,1]
	v_pk_fma_f32 v[36:37], v[130:131], v[56:57], v[36:37] op_sel_hi:[1,0,1]
	s_waitcnt lgkmcnt(3)
	v_pk_fma_f32 v[30:31], v[128:129], v[58:59], v[30:31] op_sel_hi:[1,0,1]
	v_pk_fma_f32 v[32:33], v[130:131], v[58:59], v[32:33] op_sel_hi:[1,0,1]
	v_pk_fma_f32 v[26:27], v[128:129], v[60:61], v[26:27] op_sel_hi:[1,0,1]
	v_pk_fma_f32 v[28:29], v[130:131], v[60:61], v[28:29] op_sel_hi:[1,0,1]
	s_waitcnt lgkmcnt(2)
	v_pk_fma_f32 v[18:19], v[128:129], v[62:63], v[18:19] op_sel_hi:[1,0,1]
	v_pk_fma_f32 v[20:21], v[130:131], v[62:63], v[20:21] op_sel_hi:[1,0,1]
	v_pk_fma_f32 v[14:15], v[128:129], v[64:65], v[14:15] op_sel_hi:[1,0,1]
	v_pk_fma_f32 v[16:17], v[130:131], v[64:65], v[16:17] op_sel_hi:[1,0,1]
	s_waitcnt lgkmcnt(1)
	v_pk_fma_f32 v[10:11], v[128:129], v[66:67], v[10:11] op_sel_hi:[1,0,1]
	v_pk_fma_f32 v[12:13], v[130:131], v[66:67], v[12:13] op_sel_hi:[1,0,1]
	v_pk_fma_f32 v[6:7], v[128:129], v[68:69], v[6:7] op_sel_hi:[1,0,1]
	v_pk_fma_f32 v[8:9], v[130:131], v[68:69], v[8:9] op_sel_hi:[1,0,1]
	s_waitcnt lgkmcnt(0)
	v_pk_fma_f32 v[2:3], v[128:129], v[70:71], v[2:3] op_sel_hi:[1,0,1]
	v_pk_fma_f32 v[4:5], v[130:131], v[70:71], v[4:5] op_sel_hi:[1,0,1]
	s_waitcnt vmcnt(16)
	v_pk_fma_f32 v[22:23], v[132:133], v[54:55], v[22:23] op_sel:[0,1,0]
	v_pk_fma_f32 v[24:25], v[134:135], v[54:55], v[24:25] op_sel:[0,1,0]
	v_pk_fma_f32 v[34:35], v[132:133], v[56:57], v[34:35] op_sel:[0,1,0]
	v_pk_fma_f32 v[36:37], v[134:135], v[56:57], v[36:37] op_sel:[0,1,0]
	v_pk_fma_f32 v[30:31], v[132:133], v[58:59], v[30:31] op_sel:[0,1,0]
	v_pk_fma_f32 v[32:33], v[134:135], v[58:59], v[32:33] op_sel:[0,1,0]
	v_pk_fma_f32 v[26:27], v[132:133], v[60:61], v[26:27] op_sel:[0,1,0]
	v_pk_fma_f32 v[28:29], v[134:135], v[60:61], v[28:29] op_sel:[0,1,0]
	v_pk_fma_f32 v[18:19], v[132:133], v[62:63], v[18:19] op_sel:[0,1,0]
	v_pk_fma_f32 v[20:21], v[134:135], v[62:63], v[20:21] op_sel:[0,1,0]
	v_pk_fma_f32 v[14:15], v[132:133], v[64:65], v[14:15] op_sel:[0,1,0]
	v_pk_fma_f32 v[16:17], v[134:135], v[64:65], v[16:17] op_sel:[0,1,0]
	v_pk_fma_f32 v[10:11], v[132:133], v[66:67], v[10:11] op_sel:[0,1,0]
	v_pk_fma_f32 v[12:13], v[134:135], v[66:67], v[12:13] op_sel:[0,1,0]
	v_pk_fma_f32 v[6:7], v[132:133], v[68:69], v[6:7] op_sel:[0,1,0]
	v_pk_fma_f32 v[8:9], v[134:135], v[68:69], v[8:9] op_sel:[0,1,0]
	v_pk_fma_f32 v[2:3], v[132:133], v[70:71], v[2:3] op_sel:[0,1,0]
	v_pk_fma_f32 v[4:5], v[134:135], v[70:71], v[4:5] op_sel:[0,1,0]
	ds_read2st64_b64 v[54:57], v41 offset1:8
	ds_read2st64_b64 v[58:61], v41 offset0:16 offset1:24
	ds_read2st64_b64 v[62:65], v41 offset0:32 offset1:40
	ds_read2st64_b64 v[66:69], v41 offset0:48 offset1:56
	ds_read_b64 v[70:71], v41 offset:32768
	v_add_u32_e32 v41, 8, v41
	s_waitcnt vmcnt(15) lgkmcnt(4)
	v_pk_fma_f32 v[22:23], v[136:137], v[54:55], v[22:23] op_sel_hi:[1,0,1]
	v_pk_fma_f32 v[24:25], v[138:139], v[54:55], v[24:25] op_sel_hi:[1,0,1]
	v_pk_fma_f32 v[34:35], v[136:137], v[56:57], v[34:35] op_sel_hi:[1,0,1]
	v_pk_fma_f32 v[36:37], v[138:139], v[56:57], v[36:37] op_sel_hi:[1,0,1]
	s_waitcnt lgkmcnt(3)
	v_pk_fma_f32 v[30:31], v[136:137], v[58:59], v[30:31] op_sel_hi:[1,0,1]
	v_pk_fma_f32 v[32:33], v[138:139], v[58:59], v[32:33] op_sel_hi:[1,0,1]
	v_pk_fma_f32 v[26:27], v[136:137], v[60:61], v[26:27] op_sel_hi:[1,0,1]
	v_pk_fma_f32 v[28:29], v[138:139], v[60:61], v[28:29] op_sel_hi:[1,0,1]
	s_waitcnt lgkmcnt(2)
	v_pk_fma_f32 v[18:19], v[136:137], v[62:63], v[18:19] op_sel_hi:[1,0,1]
	v_pk_fma_f32 v[20:21], v[138:139], v[62:63], v[20:21] op_sel_hi:[1,0,1]
	v_pk_fma_f32 v[14:15], v[136:137], v[64:65], v[14:15] op_sel_hi:[1,0,1]
	v_pk_fma_f32 v[16:17], v[138:139], v[64:65], v[16:17] op_sel_hi:[1,0,1]
	s_waitcnt lgkmcnt(1)
	v_pk_fma_f32 v[10:11], v[136:137], v[66:67], v[10:11] op_sel_hi:[1,0,1]
	v_pk_fma_f32 v[12:13], v[138:139], v[66:67], v[12:13] op_sel_hi:[1,0,1]
	v_pk_fma_f32 v[6:7], v[136:137], v[68:69], v[6:7] op_sel_hi:[1,0,1]
	v_pk_fma_f32 v[8:9], v[138:139], v[68:69], v[8:9] op_sel_hi:[1,0,1]
	s_waitcnt lgkmcnt(0)
	v_pk_fma_f32 v[2:3], v[136:137], v[70:71], v[2:3] op_sel_hi:[1,0,1]
	v_pk_fma_f32 v[4:5], v[138:139], v[70:71], v[4:5] op_sel_hi:[1,0,1]
	s_waitcnt vmcnt(14)
	v_pk_fma_f32 v[22:23], v[148:149], v[54:55], v[22:23] op_sel:[0,1,0]
	v_pk_fma_f32 v[24:25], v[150:151], v[54:55], v[24:25] op_sel:[0,1,0]
	v_pk_fma_f32 v[34:35], v[148:149], v[56:57], v[34:35] op_sel:[0,1,0]
	v_pk_fma_f32 v[36:37], v[150:151], v[56:57], v[36:37] op_sel:[0,1,0]
	v_pk_fma_f32 v[30:31], v[148:149], v[58:59], v[30:31] op_sel:[0,1,0]
	v_pk_fma_f32 v[32:33], v[150:151], v[58:59], v[32:33] op_sel:[0,1,0]
	v_pk_fma_f32 v[26:27], v[148:149], v[60:61], v[26:27] op_sel:[0,1,0]
	v_pk_fma_f32 v[28:29], v[150:151], v[60:61], v[28:29] op_sel:[0,1,0]
	v_pk_fma_f32 v[18:19], v[148:149], v[62:63], v[18:19] op_sel:[0,1,0]
	v_pk_fma_f32 v[20:21], v[150:151], v[62:63], v[20:21] op_sel:[0,1,0]
	v_pk_fma_f32 v[14:15], v[148:149], v[64:65], v[14:15] op_sel:[0,1,0]
	v_pk_fma_f32 v[16:17], v[150:151], v[64:65], v[16:17] op_sel:[0,1,0]
	v_pk_fma_f32 v[10:11], v[148:149], v[66:67], v[10:11] op_sel:[0,1,0]
	v_pk_fma_f32 v[12:13], v[150:151], v[66:67], v[12:13] op_sel:[0,1,0]
	v_pk_fma_f32 v[6:7], v[148:149], v[68:69], v[6:7] op_sel:[0,1,0]
	v_pk_fma_f32 v[8:9], v[150:151], v[68:69], v[8:9] op_sel:[0,1,0]
	v_pk_fma_f32 v[2:3], v[148:149], v[70:71], v[2:3] op_sel:[0,1,0]
	v_pk_fma_f32 v[4:5], v[150:151], v[70:71], v[4:5] op_sel:[0,1,0]
	ds_read2st64_b64 v[54:57], v41 offset1:8
	ds_read2st64_b64 v[58:61], v41 offset0:16 offset1:24
	ds_read2st64_b64 v[62:65], v41 offset0:32 offset1:40
	ds_read2st64_b64 v[66:69], v41 offset0:48 offset1:56
	ds_read_b64 v[70:71], v41 offset:32768
	v_add_u32_e32 v41, 8, v41
	s_waitcnt vmcnt(13) lgkmcnt(4)
	v_pk_fma_f32 v[22:23], v[152:153], v[54:55], v[22:23] op_sel_hi:[1,0,1]
	v_pk_fma_f32 v[24:25], v[154:155], v[54:55], v[24:25] op_sel_hi:[1,0,1]
	v_pk_fma_f32 v[34:35], v[152:153], v[56:57], v[34:35] op_sel_hi:[1,0,1]
	v_pk_fma_f32 v[36:37], v[154:155], v[56:57], v[36:37] op_sel_hi:[1,0,1]
	s_waitcnt lgkmcnt(3)
	v_pk_fma_f32 v[30:31], v[152:153], v[58:59], v[30:31] op_sel_hi:[1,0,1]
	v_pk_fma_f32 v[32:33], v[154:155], v[58:59], v[32:33] op_sel_hi:[1,0,1]
	v_pk_fma_f32 v[26:27], v[152:153], v[60:61], v[26:27] op_sel_hi:[1,0,1]
	v_pk_fma_f32 v[28:29], v[154:155], v[60:61], v[28:29] op_sel_hi:[1,0,1]
	s_waitcnt lgkmcnt(2)
	v_pk_fma_f32 v[18:19], v[152:153], v[62:63], v[18:19] op_sel_hi:[1,0,1]
	v_pk_fma_f32 v[20:21], v[154:155], v[62:63], v[20:21] op_sel_hi:[1,0,1]
	v_pk_fma_f32 v[14:15], v[152:153], v[64:65], v[14:15] op_sel_hi:[1,0,1]
	v_pk_fma_f32 v[16:17], v[154:155], v[64:65], v[16:17] op_sel_hi:[1,0,1]
	s_waitcnt lgkmcnt(1)
	v_pk_fma_f32 v[10:11], v[152:153], v[66:67], v[10:11] op_sel_hi:[1,0,1]
	v_pk_fma_f32 v[12:13], v[154:155], v[66:67], v[12:13] op_sel_hi:[1,0,1]
	v_pk_fma_f32 v[6:7], v[152:153], v[68:69], v[6:7] op_sel_hi:[1,0,1]
	v_pk_fma_f32 v[8:9], v[154:155], v[68:69], v[8:9] op_sel_hi:[1,0,1]
	s_waitcnt lgkmcnt(0)
	v_pk_fma_f32 v[2:3], v[152:153], v[70:71], v[2:3] op_sel_hi:[1,0,1]
	v_pk_fma_f32 v[4:5], v[154:155], v[70:71], v[4:5] op_sel_hi:[1,0,1]
	s_waitcnt vmcnt(12)
	v_pk_fma_f32 v[22:23], v[156:157], v[54:55], v[22:23] op_sel:[0,1,0]
	v_pk_fma_f32 v[24:25], v[158:159], v[54:55], v[24:25] op_sel:[0,1,0]
	v_pk_fma_f32 v[34:35], v[156:157], v[56:57], v[34:35] op_sel:[0,1,0]
	v_pk_fma_f32 v[36:37], v[158:159], v[56:57], v[36:37] op_sel:[0,1,0]
	v_pk_fma_f32 v[30:31], v[156:157], v[58:59], v[30:31] op_sel:[0,1,0]
	v_pk_fma_f32 v[32:33], v[158:159], v[58:59], v[32:33] op_sel:[0,1,0]
	v_pk_fma_f32 v[26:27], v[156:157], v[60:61], v[26:27] op_sel:[0,1,0]
	v_pk_fma_f32 v[28:29], v[158:159], v[60:61], v[28:29] op_sel:[0,1,0]
	v_pk_fma_f32 v[18:19], v[156:157], v[62:63], v[18:19] op_sel:[0,1,0]
	v_pk_fma_f32 v[20:21], v[158:159], v[62:63], v[20:21] op_sel:[0,1,0]
	v_pk_fma_f32 v[14:15], v[156:157], v[64:65], v[14:15] op_sel:[0,1,0]
	v_pk_fma_f32 v[16:17], v[158:159], v[64:65], v[16:17] op_sel:[0,1,0]
	v_pk_fma_f32 v[10:11], v[156:157], v[66:67], v[10:11] op_sel:[0,1,0]
	v_pk_fma_f32 v[12:13], v[158:159], v[66:67], v[12:13] op_sel:[0,1,0]
	v_pk_fma_f32 v[6:7], v[156:157], v[68:69], v[6:7] op_sel:[0,1,0]
	v_pk_fma_f32 v[8:9], v[158:159], v[68:69], v[8:9] op_sel:[0,1,0]
	v_pk_fma_f32 v[2:3], v[156:157], v[70:71], v[2:3] op_sel:[0,1,0]
	v_pk_fma_f32 v[4:5], v[158:159], v[70:71], v[4:5] op_sel:[0,1,0]
	ds_read2st64_b64 v[54:57], v41 offset1:8
	ds_read2st64_b64 v[58:61], v41 offset0:16 offset1:24
	ds_read2st64_b64 v[62:65], v41 offset0:32 offset1:40
	ds_read2st64_b64 v[66:69], v41 offset0:48 offset1:56
	ds_read_b64 v[70:71], v41 offset:32768
	v_add_u32_e32 v41, 8, v41
	s_waitcnt vmcnt(11) lgkmcnt(4)
	v_pk_fma_f32 v[22:23], v[160:161], v[54:55], v[22:23] op_sel_hi:[1,0,1]
	v_pk_fma_f32 v[24:25], v[162:163], v[54:55], v[24:25] op_sel_hi:[1,0,1]
	v_pk_fma_f32 v[34:35], v[160:161], v[56:57], v[34:35] op_sel_hi:[1,0,1]
	v_pk_fma_f32 v[36:37], v[162:163], v[56:57], v[36:37] op_sel_hi:[1,0,1]
	s_waitcnt lgkmcnt(3)
	v_pk_fma_f32 v[30:31], v[160:161], v[58:59], v[30:31] op_sel_hi:[1,0,1]
	v_pk_fma_f32 v[32:33], v[162:163], v[58:59], v[32:33] op_sel_hi:[1,0,1]
	v_pk_fma_f32 v[26:27], v[160:161], v[60:61], v[26:27] op_sel_hi:[1,0,1]
	v_pk_fma_f32 v[28:29], v[162:163], v[60:61], v[28:29] op_sel_hi:[1,0,1]
	s_waitcnt lgkmcnt(2)
	v_pk_fma_f32 v[18:19], v[160:161], v[62:63], v[18:19] op_sel_hi:[1,0,1]
	v_pk_fma_f32 v[20:21], v[162:163], v[62:63], v[20:21] op_sel_hi:[1,0,1]
	v_pk_fma_f32 v[14:15], v[160:161], v[64:65], v[14:15] op_sel_hi:[1,0,1]
	v_pk_fma_f32 v[16:17], v[162:163], v[64:65], v[16:17] op_sel_hi:[1,0,1]
	s_waitcnt lgkmcnt(1)
	v_pk_fma_f32 v[10:11], v[160:161], v[66:67], v[10:11] op_sel_hi:[1,0,1]
	v_pk_fma_f32 v[12:13], v[162:163], v[66:67], v[12:13] op_sel_hi:[1,0,1]
	v_pk_fma_f32 v[6:7], v[160:161], v[68:69], v[6:7] op_sel_hi:[1,0,1]
	v_pk_fma_f32 v[8:9], v[162:163], v[68:69], v[8:9] op_sel_hi:[1,0,1]
	s_waitcnt lgkmcnt(0)
	v_pk_fma_f32 v[2:3], v[160:161], v[70:71], v[2:3] op_sel_hi:[1,0,1]
	v_pk_fma_f32 v[4:5], v[162:163], v[70:71], v[4:5] op_sel_hi:[1,0,1]
	s_waitcnt vmcnt(10)
	v_pk_fma_f32 v[22:23], v[164:165], v[54:55], v[22:23] op_sel:[0,1,0]
	v_pk_fma_f32 v[24:25], v[166:167], v[54:55], v[24:25] op_sel:[0,1,0]
	v_pk_fma_f32 v[34:35], v[164:165], v[56:57], v[34:35] op_sel:[0,1,0]
	v_pk_fma_f32 v[36:37], v[166:167], v[56:57], v[36:37] op_sel:[0,1,0]
	v_pk_fma_f32 v[30:31], v[164:165], v[58:59], v[30:31] op_sel:[0,1,0]
	v_pk_fma_f32 v[32:33], v[166:167], v[58:59], v[32:33] op_sel:[0,1,0]
	v_pk_fma_f32 v[26:27], v[164:165], v[60:61], v[26:27] op_sel:[0,1,0]
	v_pk_fma_f32 v[28:29], v[166:167], v[60:61], v[28:29] op_sel:[0,1,0]
	v_pk_fma_f32 v[18:19], v[164:165], v[62:63], v[18:19] op_sel:[0,1,0]
	v_pk_fma_f32 v[20:21], v[166:167], v[62:63], v[20:21] op_sel:[0,1,0]
	v_pk_fma_f32 v[14:15], v[164:165], v[64:65], v[14:15] op_sel:[0,1,0]
	v_pk_fma_f32 v[16:17], v[166:167], v[64:65], v[16:17] op_sel:[0,1,0]
	v_pk_fma_f32 v[10:11], v[164:165], v[66:67], v[10:11] op_sel:[0,1,0]
	v_pk_fma_f32 v[12:13], v[166:167], v[66:67], v[12:13] op_sel:[0,1,0]
	v_pk_fma_f32 v[6:7], v[164:165], v[68:69], v[6:7] op_sel:[0,1,0]
	v_pk_fma_f32 v[8:9], v[166:167], v[68:69], v[8:9] op_sel:[0,1,0]
	v_pk_fma_f32 v[2:3], v[164:165], v[70:71], v[2:3] op_sel:[0,1,0]
	v_pk_fma_f32 v[4:5], v[166:167], v[70:71], v[4:5] op_sel:[0,1,0]
	ds_read2st64_b64 v[54:57], v41 offset1:8
	ds_read2st64_b64 v[58:61], v41 offset0:16 offset1:24
	ds_read2st64_b64 v[62:65], v41 offset0:32 offset1:40
	ds_read2st64_b64 v[66:69], v41 offset0:48 offset1:56
	ds_read_b64 v[70:71], v41 offset:32768
	v_add_u32_e32 v41, 8, v41
	s_waitcnt vmcnt(9) lgkmcnt(4)
	v_pk_fma_f32 v[22:23], v[168:169], v[54:55], v[22:23] op_sel_hi:[1,0,1]
	v_pk_fma_f32 v[24:25], v[170:171], v[54:55], v[24:25] op_sel_hi:[1,0,1]
	v_pk_fma_f32 v[34:35], v[168:169], v[56:57], v[34:35] op_sel_hi:[1,0,1]
	v_pk_fma_f32 v[36:37], v[170:171], v[56:57], v[36:37] op_sel_hi:[1,0,1]
	s_waitcnt lgkmcnt(3)
	v_pk_fma_f32 v[30:31], v[168:169], v[58:59], v[30:31] op_sel_hi:[1,0,1]
	v_pk_fma_f32 v[32:33], v[170:171], v[58:59], v[32:33] op_sel_hi:[1,0,1]
	v_pk_fma_f32 v[26:27], v[168:169], v[60:61], v[26:27] op_sel_hi:[1,0,1]
	v_pk_fma_f32 v[28:29], v[170:171], v[60:61], v[28:29] op_sel_hi:[1,0,1]
	s_waitcnt lgkmcnt(2)
	v_pk_fma_f32 v[18:19], v[168:169], v[62:63], v[18:19] op_sel_hi:[1,0,1]
	v_pk_fma_f32 v[20:21], v[170:171], v[62:63], v[20:21] op_sel_hi:[1,0,1]
	v_pk_fma_f32 v[14:15], v[168:169], v[64:65], v[14:15] op_sel_hi:[1,0,1]
	v_pk_fma_f32 v[16:17], v[170:171], v[64:65], v[16:17] op_sel_hi:[1,0,1]
	s_waitcnt lgkmcnt(1)
	v_pk_fma_f32 v[10:11], v[168:169], v[66:67], v[10:11] op_sel_hi:[1,0,1]
	v_pk_fma_f32 v[12:13], v[170:171], v[66:67], v[12:13] op_sel_hi:[1,0,1]
	v_pk_fma_f32 v[6:7], v[168:169], v[68:69], v[6:7] op_sel_hi:[1,0,1]
	v_pk_fma_f32 v[8:9], v[170:171], v[68:69], v[8:9] op_sel_hi:[1,0,1]
	s_waitcnt lgkmcnt(0)
	v_pk_fma_f32 v[2:3], v[168:169], v[70:71], v[2:3] op_sel_hi:[1,0,1]
	v_pk_fma_f32 v[4:5], v[170:171], v[70:71], v[4:5] op_sel_hi:[1,0,1]
	s_waitcnt vmcnt(8)
	v_pk_fma_f32 v[22:23], v[172:173], v[54:55], v[22:23] op_sel:[0,1,0]
	v_pk_fma_f32 v[24:25], v[174:175], v[54:55], v[24:25] op_sel:[0,1,0]
	v_pk_fma_f32 v[34:35], v[172:173], v[56:57], v[34:35] op_sel:[0,1,0]
	v_pk_fma_f32 v[36:37], v[174:175], v[56:57], v[36:37] op_sel:[0,1,0]
	v_pk_fma_f32 v[30:31], v[172:173], v[58:59], v[30:31] op_sel:[0,1,0]
	v_pk_fma_f32 v[32:33], v[174:175], v[58:59], v[32:33] op_sel:[0,1,0]
	v_pk_fma_f32 v[26:27], v[172:173], v[60:61], v[26:27] op_sel:[0,1,0]
	v_pk_fma_f32 v[28:29], v[174:175], v[60:61], v[28:29] op_sel:[0,1,0]
	v_pk_fma_f32 v[18:19], v[172:173], v[62:63], v[18:19] op_sel:[0,1,0]
	v_pk_fma_f32 v[20:21], v[174:175], v[62:63], v[20:21] op_sel:[0,1,0]
	v_pk_fma_f32 v[14:15], v[172:173], v[64:65], v[14:15] op_sel:[0,1,0]
	v_pk_fma_f32 v[16:17], v[174:175], v[64:65], v[16:17] op_sel:[0,1,0]
	v_pk_fma_f32 v[10:11], v[172:173], v[66:67], v[10:11] op_sel:[0,1,0]
	v_pk_fma_f32 v[12:13], v[174:175], v[66:67], v[12:13] op_sel:[0,1,0]
	v_pk_fma_f32 v[6:7], v[172:173], v[68:69], v[6:7] op_sel:[0,1,0]
	v_pk_fma_f32 v[8:9], v[174:175], v[68:69], v[8:9] op_sel:[0,1,0]
	v_pk_fma_f32 v[2:3], v[172:173], v[70:71], v[2:3] op_sel:[0,1,0]
	v_pk_fma_f32 v[4:5], v[174:175], v[70:71], v[4:5] op_sel:[0,1,0]
	ds_read2st64_b64 v[54:57], v41 offset1:8
	ds_read2st64_b64 v[58:61], v41 offset0:16 offset1:24
	ds_read2st64_b64 v[62:65], v41 offset0:32 offset1:40
	ds_read2st64_b64 v[66:69], v41 offset0:48 offset1:56
	ds_read_b64 v[70:71], v41 offset:32768
	v_add_u32_e32 v41, 8, v41
	s_waitcnt vmcnt(7) lgkmcnt(4)
	v_pk_fma_f32 v[22:23], v[176:177], v[54:55], v[22:23] op_sel_hi:[1,0,1]
	v_pk_fma_f32 v[24:25], v[178:179], v[54:55], v[24:25] op_sel_hi:[1,0,1]
	v_pk_fma_f32 v[34:35], v[176:177], v[56:57], v[34:35] op_sel_hi:[1,0,1]
	v_pk_fma_f32 v[36:37], v[178:179], v[56:57], v[36:37] op_sel_hi:[1,0,1]
	s_waitcnt lgkmcnt(3)
	v_pk_fma_f32 v[30:31], v[176:177], v[58:59], v[30:31] op_sel_hi:[1,0,1]
	v_pk_fma_f32 v[32:33], v[178:179], v[58:59], v[32:33] op_sel_hi:[1,0,1]
	v_pk_fma_f32 v[26:27], v[176:177], v[60:61], v[26:27] op_sel_hi:[1,0,1]
	v_pk_fma_f32 v[28:29], v[178:179], v[60:61], v[28:29] op_sel_hi:[1,0,1]
	s_waitcnt lgkmcnt(2)
	v_pk_fma_f32 v[18:19], v[176:177], v[62:63], v[18:19] op_sel_hi:[1,0,1]
	v_pk_fma_f32 v[20:21], v[178:179], v[62:63], v[20:21] op_sel_hi:[1,0,1]
	v_pk_fma_f32 v[14:15], v[176:177], v[64:65], v[14:15] op_sel_hi:[1,0,1]
	v_pk_fma_f32 v[16:17], v[178:179], v[64:65], v[16:17] op_sel_hi:[1,0,1]
	s_waitcnt lgkmcnt(1)
	v_pk_fma_f32 v[10:11], v[176:177], v[66:67], v[10:11] op_sel_hi:[1,0,1]
	v_pk_fma_f32 v[12:13], v[178:179], v[66:67], v[12:13] op_sel_hi:[1,0,1]
	v_pk_fma_f32 v[6:7], v[176:177], v[68:69], v[6:7] op_sel_hi:[1,0,1]
	v_pk_fma_f32 v[8:9], v[178:179], v[68:69], v[8:9] op_sel_hi:[1,0,1]
	s_waitcnt lgkmcnt(0)
	v_pk_fma_f32 v[2:3], v[176:177], v[70:71], v[2:3] op_sel_hi:[1,0,1]
	v_pk_fma_f32 v[4:5], v[178:179], v[70:71], v[4:5] op_sel_hi:[1,0,1]
	s_waitcnt vmcnt(6)
	v_pk_fma_f32 v[22:23], v[180:181], v[54:55], v[22:23] op_sel:[0,1,0]
	v_pk_fma_f32 v[24:25], v[182:183], v[54:55], v[24:25] op_sel:[0,1,0]
	v_pk_fma_f32 v[34:35], v[180:181], v[56:57], v[34:35] op_sel:[0,1,0]
	v_pk_fma_f32 v[36:37], v[182:183], v[56:57], v[36:37] op_sel:[0,1,0]
	v_pk_fma_f32 v[30:31], v[180:181], v[58:59], v[30:31] op_sel:[0,1,0]
	v_pk_fma_f32 v[32:33], v[182:183], v[58:59], v[32:33] op_sel:[0,1,0]
	v_pk_fma_f32 v[26:27], v[180:181], v[60:61], v[26:27] op_sel:[0,1,0]
	v_pk_fma_f32 v[28:29], v[182:183], v[60:61], v[28:29] op_sel:[0,1,0]
	v_pk_fma_f32 v[18:19], v[180:181], v[62:63], v[18:19] op_sel:[0,1,0]
	v_pk_fma_f32 v[20:21], v[182:183], v[62:63], v[20:21] op_sel:[0,1,0]
	v_pk_fma_f32 v[14:15], v[180:181], v[64:65], v[14:15] op_sel:[0,1,0]
	v_pk_fma_f32 v[16:17], v[182:183], v[64:65], v[16:17] op_sel:[0,1,0]
	v_pk_fma_f32 v[10:11], v[180:181], v[66:67], v[10:11] op_sel:[0,1,0]
	v_pk_fma_f32 v[12:13], v[182:183], v[66:67], v[12:13] op_sel:[0,1,0]
	v_pk_fma_f32 v[6:7], v[180:181], v[68:69], v[6:7] op_sel:[0,1,0]
	v_pk_fma_f32 v[8:9], v[182:183], v[68:69], v[8:9] op_sel:[0,1,0]
	v_pk_fma_f32 v[2:3], v[180:181], v[70:71], v[2:3] op_sel:[0,1,0]
	v_pk_fma_f32 v[4:5], v[182:183], v[70:71], v[4:5] op_sel:[0,1,0]
	ds_read2st64_b64 v[54:57], v41 offset1:8
	ds_read2st64_b64 v[58:61], v41 offset0:16 offset1:24
	ds_read2st64_b64 v[62:65], v41 offset0:32 offset1:40
	ds_read2st64_b64 v[66:69], v41 offset0:48 offset1:56
	ds_read_b64 v[70:71], v41 offset:32768
	v_add_u32_e32 v41, 8, v41
	s_waitcnt vmcnt(5) lgkmcnt(4)
	v_pk_fma_f32 v[22:23], v[184:185], v[54:55], v[22:23] op_sel_hi:[1,0,1]
	v_pk_fma_f32 v[24:25], v[186:187], v[54:55], v[24:25] op_sel_hi:[1,0,1]
	v_pk_fma_f32 v[34:35], v[184:185], v[56:57], v[34:35] op_sel_hi:[1,0,1]
	v_pk_fma_f32 v[36:37], v[186:187], v[56:57], v[36:37] op_sel_hi:[1,0,1]
	s_waitcnt lgkmcnt(3)
	v_pk_fma_f32 v[30:31], v[184:185], v[58:59], v[30:31] op_sel_hi:[1,0,1]
	v_pk_fma_f32 v[32:33], v[186:187], v[58:59], v[32:33] op_sel_hi:[1,0,1]
	v_pk_fma_f32 v[26:27], v[184:185], v[60:61], v[26:27] op_sel_hi:[1,0,1]
	v_pk_fma_f32 v[28:29], v[186:187], v[60:61], v[28:29] op_sel_hi:[1,0,1]
	s_waitcnt lgkmcnt(2)
	v_pk_fma_f32 v[18:19], v[184:185], v[62:63], v[18:19] op_sel_hi:[1,0,1]
	v_pk_fma_f32 v[20:21], v[186:187], v[62:63], v[20:21] op_sel_hi:[1,0,1]
	v_pk_fma_f32 v[14:15], v[184:185], v[64:65], v[14:15] op_sel_hi:[1,0,1]
	v_pk_fma_f32 v[16:17], v[186:187], v[64:65], v[16:17] op_sel_hi:[1,0,1]
	s_waitcnt lgkmcnt(1)
	v_pk_fma_f32 v[10:11], v[184:185], v[66:67], v[10:11] op_sel_hi:[1,0,1]
	v_pk_fma_f32 v[12:13], v[186:187], v[66:67], v[12:13] op_sel_hi:[1,0,1]
	v_pk_fma_f32 v[6:7], v[184:185], v[68:69], v[6:7] op_sel_hi:[1,0,1]
	v_pk_fma_f32 v[8:9], v[186:187], v[68:69], v[8:9] op_sel_hi:[1,0,1]
	s_waitcnt lgkmcnt(0)
	v_pk_fma_f32 v[2:3], v[184:185], v[70:71], v[2:3] op_sel_hi:[1,0,1]
	v_pk_fma_f32 v[4:5], v[186:187], v[70:71], v[4:5] op_sel_hi:[1,0,1]
	s_waitcnt vmcnt(4)
	v_pk_fma_f32 v[22:23], v[188:189], v[54:55], v[22:23] op_sel:[0,1,0]
	v_pk_fma_f32 v[24:25], v[190:191], v[54:55], v[24:25] op_sel:[0,1,0]
	v_pk_fma_f32 v[34:35], v[188:189], v[56:57], v[34:35] op_sel:[0,1,0]
	v_pk_fma_f32 v[36:37], v[190:191], v[56:57], v[36:37] op_sel:[0,1,0]
	v_pk_fma_f32 v[30:31], v[188:189], v[58:59], v[30:31] op_sel:[0,1,0]
	v_pk_fma_f32 v[32:33], v[190:191], v[58:59], v[32:33] op_sel:[0,1,0]
	v_pk_fma_f32 v[26:27], v[188:189], v[60:61], v[26:27] op_sel:[0,1,0]
	v_pk_fma_f32 v[28:29], v[190:191], v[60:61], v[28:29] op_sel:[0,1,0]
	v_pk_fma_f32 v[18:19], v[188:189], v[62:63], v[18:19] op_sel:[0,1,0]
	v_pk_fma_f32 v[20:21], v[190:191], v[62:63], v[20:21] op_sel:[0,1,0]
	v_pk_fma_f32 v[14:15], v[188:189], v[64:65], v[14:15] op_sel:[0,1,0]
	v_pk_fma_f32 v[16:17], v[190:191], v[64:65], v[16:17] op_sel:[0,1,0]
	v_pk_fma_f32 v[10:11], v[188:189], v[66:67], v[10:11] op_sel:[0,1,0]
	v_pk_fma_f32 v[12:13], v[190:191], v[66:67], v[12:13] op_sel:[0,1,0]
	v_pk_fma_f32 v[6:7], v[188:189], v[68:69], v[6:7] op_sel:[0,1,0]
	v_pk_fma_f32 v[8:9], v[190:191], v[68:69], v[8:9] op_sel:[0,1,0]
	v_pk_fma_f32 v[2:3], v[188:189], v[70:71], v[2:3] op_sel:[0,1,0]
	v_pk_fma_f32 v[4:5], v[190:191], v[70:71], v[4:5] op_sel:[0,1,0]
	ds_read2st64_b64 v[54:57], v41 offset1:8
	ds_read2st64_b64 v[58:61], v41 offset0:16 offset1:24
	ds_read2st64_b64 v[62:65], v41 offset0:32 offset1:40
	ds_read2st64_b64 v[66:69], v41 offset0:48 offset1:56
	ds_read_b64 v[70:71], v41 offset:32768
	v_add_u32_e32 v41, 8, v41
	s_waitcnt vmcnt(3) lgkmcnt(4)
	v_pk_fma_f32 v[22:23], v[206:207], v[54:55], v[22:23] op_sel_hi:[1,0,1]
	v_pk_fma_f32 v[24:25], v[208:209], v[54:55], v[24:25] op_sel_hi:[1,0,1]
	v_pk_fma_f32 v[34:35], v[206:207], v[56:57], v[34:35] op_sel_hi:[1,0,1]
	v_pk_fma_f32 v[36:37], v[208:209], v[56:57], v[36:37] op_sel_hi:[1,0,1]
	s_waitcnt lgkmcnt(3)
	v_pk_fma_f32 v[30:31], v[206:207], v[58:59], v[30:31] op_sel_hi:[1,0,1]
	v_pk_fma_f32 v[32:33], v[208:209], v[58:59], v[32:33] op_sel_hi:[1,0,1]
	v_pk_fma_f32 v[26:27], v[206:207], v[60:61], v[26:27] op_sel_hi:[1,0,1]
	v_pk_fma_f32 v[28:29], v[208:209], v[60:61], v[28:29] op_sel_hi:[1,0,1]
	s_waitcnt lgkmcnt(2)
	v_pk_fma_f32 v[18:19], v[206:207], v[62:63], v[18:19] op_sel_hi:[1,0,1]
	v_pk_fma_f32 v[20:21], v[208:209], v[62:63], v[20:21] op_sel_hi:[1,0,1]
	v_pk_fma_f32 v[14:15], v[206:207], v[64:65], v[14:15] op_sel_hi:[1,0,1]
	v_pk_fma_f32 v[16:17], v[208:209], v[64:65], v[16:17] op_sel_hi:[1,0,1]
	s_waitcnt lgkmcnt(1)
	v_pk_fma_f32 v[10:11], v[206:207], v[66:67], v[10:11] op_sel_hi:[1,0,1]
	v_pk_fma_f32 v[12:13], v[208:209], v[66:67], v[12:13] op_sel_hi:[1,0,1]
	v_pk_fma_f32 v[6:7], v[206:207], v[68:69], v[6:7] op_sel_hi:[1,0,1]
	v_pk_fma_f32 v[8:9], v[208:209], v[68:69], v[8:9] op_sel_hi:[1,0,1]
	s_waitcnt lgkmcnt(0)
	v_pk_fma_f32 v[2:3], v[206:207], v[70:71], v[2:3] op_sel_hi:[1,0,1]
	v_pk_fma_f32 v[4:5], v[208:209], v[70:71], v[4:5] op_sel_hi:[1,0,1]
	s_waitcnt vmcnt(2)
	v_pk_fma_f32 v[22:23], v[210:211], v[54:55], v[22:23] op_sel:[0,1,0]
	v_pk_fma_f32 v[24:25], v[212:213], v[54:55], v[24:25] op_sel:[0,1,0]
	v_pk_fma_f32 v[34:35], v[210:211], v[56:57], v[34:35] op_sel:[0,1,0]
	v_pk_fma_f32 v[36:37], v[212:213], v[56:57], v[36:37] op_sel:[0,1,0]
	v_pk_fma_f32 v[30:31], v[210:211], v[58:59], v[30:31] op_sel:[0,1,0]
	v_pk_fma_f32 v[32:33], v[212:213], v[58:59], v[32:33] op_sel:[0,1,0]
	v_pk_fma_f32 v[26:27], v[210:211], v[60:61], v[26:27] op_sel:[0,1,0]
	v_pk_fma_f32 v[28:29], v[212:213], v[60:61], v[28:29] op_sel:[0,1,0]
	v_pk_fma_f32 v[18:19], v[210:211], v[62:63], v[18:19] op_sel:[0,1,0]
	v_pk_fma_f32 v[20:21], v[212:213], v[62:63], v[20:21] op_sel:[0,1,0]
	v_pk_fma_f32 v[14:15], v[210:211], v[64:65], v[14:15] op_sel:[0,1,0]
	v_pk_fma_f32 v[16:17], v[212:213], v[64:65], v[16:17] op_sel:[0,1,0]
	v_pk_fma_f32 v[10:11], v[210:211], v[66:67], v[10:11] op_sel:[0,1,0]
	v_pk_fma_f32 v[12:13], v[212:213], v[66:67], v[12:13] op_sel:[0,1,0]
	v_pk_fma_f32 v[6:7], v[210:211], v[68:69], v[6:7] op_sel:[0,1,0]
	v_pk_fma_f32 v[8:9], v[212:213], v[68:69], v[8:9] op_sel:[0,1,0]
	v_pk_fma_f32 v[2:3], v[210:211], v[70:71], v[2:3] op_sel:[0,1,0]
	v_pk_fma_f32 v[4:5], v[212:213], v[70:71], v[4:5] op_sel:[0,1,0]
	ds_read2st64_b64 v[54:57], v41 offset1:8
	ds_read2st64_b64 v[58:61], v41 offset0:16 offset1:24
	ds_read2st64_b64 v[62:65], v41 offset0:32 offset1:40
	ds_read2st64_b64 v[66:69], v41 offset0:48 offset1:56
	ds_read_b64 v[70:71], v41 offset:32768
	v_add_u32_e32 v41, 8, v41
	s_waitcnt vmcnt(1) lgkmcnt(4)
	v_pk_fma_f32 v[22:23], v[214:215], v[54:55], v[22:23] op_sel_hi:[1,0,1]
	v_pk_fma_f32 v[24:25], v[216:217], v[54:55], v[24:25] op_sel_hi:[1,0,1]
	v_pk_fma_f32 v[34:35], v[214:215], v[56:57], v[34:35] op_sel_hi:[1,0,1]
	v_pk_fma_f32 v[36:37], v[216:217], v[56:57], v[36:37] op_sel_hi:[1,0,1]
	s_waitcnt lgkmcnt(3)
	v_pk_fma_f32 v[30:31], v[214:215], v[58:59], v[30:31] op_sel_hi:[1,0,1]
	v_pk_fma_f32 v[32:33], v[216:217], v[58:59], v[32:33] op_sel_hi:[1,0,1]
	v_pk_fma_f32 v[26:27], v[214:215], v[60:61], v[26:27] op_sel_hi:[1,0,1]
	v_pk_fma_f32 v[28:29], v[216:217], v[60:61], v[28:29] op_sel_hi:[1,0,1]
	s_waitcnt lgkmcnt(2)
	v_pk_fma_f32 v[18:19], v[214:215], v[62:63], v[18:19] op_sel_hi:[1,0,1]
	v_pk_fma_f32 v[20:21], v[216:217], v[62:63], v[20:21] op_sel_hi:[1,0,1]
	v_pk_fma_f32 v[14:15], v[214:215], v[64:65], v[14:15] op_sel_hi:[1,0,1]
	v_pk_fma_f32 v[16:17], v[216:217], v[64:65], v[16:17] op_sel_hi:[1,0,1]
	s_waitcnt lgkmcnt(1)
	v_pk_fma_f32 v[10:11], v[214:215], v[66:67], v[10:11] op_sel_hi:[1,0,1]
	v_pk_fma_f32 v[12:13], v[216:217], v[66:67], v[12:13] op_sel_hi:[1,0,1]
	v_pk_fma_f32 v[6:7], v[214:215], v[68:69], v[6:7] op_sel_hi:[1,0,1]
	v_pk_fma_f32 v[8:9], v[216:217], v[68:69], v[8:9] op_sel_hi:[1,0,1]
	s_waitcnt lgkmcnt(0)
	v_pk_fma_f32 v[2:3], v[214:215], v[70:71], v[2:3] op_sel_hi:[1,0,1]
	v_pk_fma_f32 v[4:5], v[216:217], v[70:71], v[4:5] op_sel_hi:[1,0,1]
	s_waitcnt vmcnt(0)
	v_pk_fma_f32 v[22:23], v[218:219], v[54:55], v[22:23] op_sel:[0,1,0]
	v_pk_fma_f32 v[24:25], v[220:221], v[54:55], v[24:25] op_sel:[0,1,0]
	v_pk_fma_f32 v[34:35], v[218:219], v[56:57], v[34:35] op_sel:[0,1,0]
	v_pk_fma_f32 v[36:37], v[220:221], v[56:57], v[36:37] op_sel:[0,1,0]
	v_pk_fma_f32 v[30:31], v[218:219], v[58:59], v[30:31] op_sel:[0,1,0]
	v_pk_fma_f32 v[32:33], v[220:221], v[58:59], v[32:33] op_sel:[0,1,0]
	v_pk_fma_f32 v[26:27], v[218:219], v[60:61], v[26:27] op_sel:[0,1,0]
	v_pk_fma_f32 v[28:29], v[220:221], v[60:61], v[28:29] op_sel:[0,1,0]
	v_pk_fma_f32 v[18:19], v[218:219], v[62:63], v[18:19] op_sel:[0,1,0]
	v_pk_fma_f32 v[20:21], v[220:221], v[62:63], v[20:21] op_sel:[0,1,0]
	v_pk_fma_f32 v[14:15], v[218:219], v[64:65], v[14:15] op_sel:[0,1,0]
	v_pk_fma_f32 v[16:17], v[220:221], v[64:65], v[16:17] op_sel:[0,1,0]
	v_pk_fma_f32 v[10:11], v[218:219], v[66:67], v[10:11] op_sel:[0,1,0]
	v_pk_fma_f32 v[12:13], v[220:221], v[66:67], v[12:13] op_sel:[0,1,0]
	v_pk_fma_f32 v[6:7], v[218:219], v[68:69], v[6:7] op_sel:[0,1,0]
	v_pk_fma_f32 v[8:9], v[220:221], v[68:69], v[8:9] op_sel:[0,1,0]
	v_pk_fma_f32 v[2:3], v[218:219], v[70:71], v[2:3] op_sel:[0,1,0]
	v_pk_fma_f32 v[4:5], v[220:221], v[70:71], v[4:5] op_sel:[0,1,0]
	v_lshlrev_b32_e32 v41, 4, v40
	v_mul_lo_u32 v38, v38, s36
	v_and_or_b32 v38, v41, s37, v38
	v_cmp_gt_i32_e32 vcc, s38, v40
	ds_write_b128 v38, v[22:25] offset:36864
	ds_write_b128 v38, v[34:37] offset:37120
	ds_write_b128 v38, v[30:33] offset:37376
	ds_write_b128 v38, v[26:29] offset:37632
	ds_write_b128 v38, v[18:21] offset:37888
	ds_write_b128 v38, v[14:17] offset:38144
	ds_write_b128 v38, v[10:13] offset:38400
	ds_write_b128 v38, v[6:9] offset:38656
	ds_write_b128 v38, v[2:5] offset:38912
	s_waitcnt lgkmcnt(0)
	s_barrier
	s_and_saveexec_b64 s[10:11], vcc
	s_cbranch_execz .LBB0_7
	v_readlane_b32 s18, v244, 4
	v_readlane_b32 s19, v244, 5
	s_add_u32 s8, s18, s8
	s_mul_i32 s7, s16, 0x1800
	s_addc_u32 s9, s19, s9
	s_add_i32 s7, s7, s6
	v_and_b32_e32 v4, 63, v40
	v_or_b32_e32 v2, s7, v4
	v_ashrrev_i32_e32 v3, 31, v2
	v_lshlrev_b32_e32 v38, 2, v4
	s_mul_i32 s16, s16, 9
	v_lshl_add_u64 v[2:3], v[2:3], 2, s[78:79]
	v_lshl_add_u64 v[4:5], s[8:9], 0, v[38:39]
	s_mov_b64 s[6:7], 0

.LBB0_52:
	s_or_saveexec_b64 s[20:21], s[20:21]
	s_lshl_b32 s19, s19, 10
	s_sub_i32 s28, 0, s19
	v_mov_b32_e32 v12, 0
	v_mov_b32_e32 v13, 0
	s_xor_b64 exec, exec, s[20:21]
	s_cbranch_execz .LBB0_49
	s_ashr_i32 s19, s18, 31
	v_lshl_add_u64 v[16:17], s[18:19], 2, v[4:5]
	s_add_i32 s19, s28, s26
	v_add_u32_e32 v12, s19, v8
	v_ashrrev_i32_e32 v13, 31, v12
	v_lshlrev_b64 v[12:13], 14, v[12:13]
	v_lshl_add_u64 v[12:13], v[16:17], 0, v[12:13]
	v_add_u32_e32 v18, s19, v10
	v_ashrrev_i32_e32 v19, 31, v18
	v_lshlrev_b64 v[18:19], 14, v[18:19]
	v_lshl_add_u64 v[18:19], v[16:17], 0, v[18:19]
	global_load_dwordx4 v[12:15], v[12:13], off
	global_load_dwordx4 v[20:23], v[18:19], off
	s_waitcnt vmcnt(1)
	v_cvt_pk_bf16_f32 v12, v12, v13
	v_cvt_pk_bf16_f32 v13, v14, v15
	ds_write_b16 v9, v12
	ds_write_b16_d16_hi v9, v12 offset:144
	ds_write_b16 v9, v13 offset:288
	ds_write_b16_d16_hi v9, v13 offset:432
	s_waitcnt vmcnt(0)
	v_cvt_pk_bf16_f32 v12, v20, v21
	v_cvt_pk_bf16_f32 v13, v22, v23
	s_branch .LBB0_49

.LBB0_59:
	s_or_saveexec_b64 s[10:11], s[10:11]
	s_lshl_b32 s7, s7, 6
	s_and_b32 s7, s7, 0xfffff000
	s_sub_i32 s20, 0, s7
	v_mov_b32_e32 v12, 0
	v_mov_b32_e32 v13, 0
	s_xor_b64 exec, exec, s[10:11]
	s_cbranch_execz .LBB0_56
	s_ashr_i32 s7, s6, 31
	v_lshl_add_u64 v[16:17], s[6:7], 2, v[4:5]
	s_add_i32 s7, s20, s18
	v_add_u32_e32 v12, s7, v8
	v_ashrrev_i32_e32 v13, 31, v12
	v_lshlrev_b64 v[12:13], 12, v[12:13]
	v_lshl_add_u64 v[12:13], v[16:17], 0, v[12:13]
	v_add_u32_e32 v18, s7, v10
	v_ashrrev_i32_e32 v19, 31, v18
	v_lshlrev_b64 v[18:19], 12, v[18:19]
	v_lshl_add_u64 v[18:19], v[16:17], 0, v[18:19]
	global_load_dwordx4 v[12:15], v[12:13], off
	global_load_dwordx4 v[20:23], v[18:19], off
	s_waitcnt vmcnt(1)
	v_cvt_pk_bf16_f32 v12, v12, v13
	v_cvt_pk_bf16_f32 v13, v14, v15
	ds_write_b16 v9, v12
	ds_write_b16_d16_hi v9, v12 offset:144
	ds_write_b16 v9, v13 offset:288
	ds_write_b16_d16_hi v9, v13 offset:432
	s_waitcnt vmcnt(0)
	v_cvt_pk_bf16_f32 v12, v20, v21
	v_cvt_pk_bf16_f32 v13, v22, v23
	s_branch .LBB0_56

.LBB0_316:
	s_mul_i32 s14, s8, 0x4c00
	v_add_u32_e32 v0, s14, v153
	ds_read_b128 v[158:161], v0
	ds_read_b128 v[162:165], v0 offset:4608
	ds_read_b128 v[166:169], v0 offset:32
	s_waitcnt lgkmcnt(2)
	v_mfma_f32_32x32x16_bf16 v[50:65], v[158:161], v[66:69], v[220:235]
	v_add_f32_e64 v90, v116, 0
	v_add_f32_e64 v91, v117, 0
	v_cvt_pk_bf16_f32 v102, v116, v117
	v_add_f32_e64 v90, v118, v90
	v_add_f32_e64 v91, v119, v91
	v_cvt_pk_bf16_f32 v103, v118, v119
	s_waitcnt lgkmcnt(1)
	v_mfma_f32_32x32x16_bf16 v[34:49], v[162:165], v[66:69], v[220:235]
	ds_read_b128 v[116:119], v0 offset:4640
	v_add_f32_e64 v90, v104, v90
	v_add_f32_e64 v91, v105, v91
	v_cvt_pk_bf16_f32 v104, v104, v105
	v_add_f32_e64 v90, v124, v90
	v_add_f32_e64 v91, v125, v91
	v_cvt_pk_bf16_f32 v105, v124, v125
	s_waitcnt lgkmcnt(1)
	v_mfma_f32_32x32x16_bf16 v[50:65], v[166:169], v[70:73], v[50:65]
	ds_read_b128 v[158:161], v0 offset:64
	v_add_f32_e64 v90, v126, v90
	v_add_f32_e64 v91, v127, v91
	v_cvt_pk_bf16_f32 v98, v126, v127
	v_add_f32_e64 v90, v128, v90
	v_add_f32_e64 v91, v129, v91
	v_cvt_pk_bf16_f32 v99, v128, v129
	s_waitcnt lgkmcnt(1)
	v_mfma_f32_32x32x16_bf16 v[34:49], v[116:119], v[70:73], v[34:49]
	ds_read_b128 v[124:127], v0 offset:4672
	v_add_f32_e64 v90, v100, v90
	v_add_f32_e64 v91, v101, v91
	v_cvt_pk_bf16_f32 v100, v100, v101
	v_add_f32_e64 v90, v130, v90
	v_add_f32_e64 v91, v131, v91
	v_cvt_pk_bf16_f32 v101, v130, v131
	s_waitcnt lgkmcnt(1)
	v_mfma_f32_32x32x16_bf16 v[50:65], v[158:161], v[74:77], v[50:65]
	ds_read_b128 v[116:119], v0 offset:96
	v_add_f32_e64 v90, v120, v90
	v_add_f32_e64 v91, v121, v91
	v_cvt_pk_bf16_f32 v94, v120, v121
	v_add_f32_e64 v90, v122, v90
	v_add_f32_e64 v91, v123, v91
	v_cvt_pk_bf16_f32 v95, v122, v123
	s_waitcnt lgkmcnt(1)
	v_mfma_f32_32x32x16_bf16 v[34:49], v[124:127], v[74:77], v[34:49]
	ds_read_b128 v[120:123], v0 offset:4704
	v_add_f32_e64 v90, v96, v90
	v_add_f32_e64 v91, v97, v91
	v_cvt_pk_bf16_f32 v96, v96, v97
	v_add_f32_e64 v90, v132, v90
	v_add_f32_e64 v91, v133, v91
	v_cvt_pk_bf16_f32 v97, v132, v133
	s_waitcnt lgkmcnt(1)
	v_mfma_f32_32x32x16_bf16 v[50:65], v[116:119], v[78:81], v[50:65]
	v_add_f32_e64 v116, v134, v90
	v_add_f32_e64 v117, v135, v91
	v_cvt_pk_bf16_f32 v90, v134, v135
	v_add_f32_e64 v116, v136, v116
	v_add_f32_e64 v117, v137, v117
	v_cvt_pk_bf16_f32 v91, v136, v137
	s_waitcnt lgkmcnt(0)
	v_mfma_f32_32x32x16_bf16 v[34:49], v[120:123], v[78:81], v[34:49]
	v_add_f32_e64 v116, v92, v116
	v_add_f32_e64 v117, v93, v117
	v_cvt_pk_bf16_f32 v92, v92, v93
	v_add_f32_e64 v116, v138, v116
	v_add_f32_e64 v117, v139, v117
	v_cvt_pk_bf16_f32 v93, v138, v139
	s_nop 0
	v_add_f32_e32 v0, v116, v117
	v_max_f32_e32 v116, v50, v51
	v_max3_f32 v116, v116, v52, v53
	v_max3_f32 v116, v116, v54, v55
	v_max3_f32 v116, v116, v56, v57
	v_max3_f32 v116, v116, v58, v59
	v_max3_f32 v116, v116, v60, v61
	v_max3_f32 v116, v116, v62, v63
	v_max3_f32 v116, v116, v64, v65
	v_max3_f32 v116, v116, v34, v35
	v_max3_f32 v116, v116, v36, v37
	v_max3_f32 v116, v116, v38, v39
	v_max3_f32 v116, v116, v40, v41
	v_max3_f32 v116, v116, v42, v43
	v_max3_f32 v116, v116, v44, v45
	v_max3_f32 v116, v116, v46, v47
	v_max3_f32 v116, v116, v48, v49
	v_add_f32_e32 v155, v155, v0
	ds_bpermute_b32 v0, v154, v116
	s_waitcnt lgkmcnt(0)
	v_max_f32_e32 v0, v116, v0
	v_cmp_lt_f32_e32 vcc, s33, v0
	s_cmp_lg_u64 vcc, 0
	s_cselect_b64 s[14:15], -1, 0
	s_cbranch_vccz .LBB0_318
	v_max_f32_e32 v0, v0, v0
	v_max_f32_e32 v116, 0, v0
	v_exp_f32_e64 v0, -v116
	v_add_f32_e32 v156, v156, v116
	v_xor_b32_e32 v220, 0x80000000, v156
	v_mov_b32_e32 v221, v220
	v_mov_b32_e32 v222, v220
	v_mov_b32_e32 v223, v220
	v_mov_b32_e32 v224, v220
	v_mov_b32_e32 v225, v220
	v_mov_b32_e32 v226, v220
	v_mov_b32_e32 v227, v220
	v_mov_b32_e32 v228, v220
	v_mov_b32_e32 v229, v220
	v_mov_b32_e32 v230, v220
	v_mov_b32_e32 v231, v220
	v_mov_b32_e32 v232, v220
	v_mov_b32_e32 v233, v220
	v_mov_b32_e32 v234, v220
	v_mov_b32_e32 v235, v220
	v_pk_add_f32 v[50:51], v[50:51], v[116:117] op_sel_hi:[1,0] neg_lo:[0,1] neg_hi:[0,1]
	v_pk_add_f32 v[34:35], v[34:35], v[116:117] op_sel_hi:[1,0] neg_lo:[0,1] neg_hi:[0,1]
	v_pk_add_f32 v[52:53], v[52:53], v[116:117] op_sel_hi:[1,0] neg_lo:[0,1] neg_hi:[0,1]
	v_pk_add_f32 v[36:37], v[36:37], v[116:117] op_sel_hi:[1,0] neg_lo:[0,1] neg_hi:[0,1]
	v_pk_add_f32 v[54:55], v[54:55], v[116:117] op_sel_hi:[1,0] neg_lo:[0,1] neg_hi:[0,1]
	v_pk_add_f32 v[38:39], v[38:39], v[116:117] op_sel_hi:[1,0] neg_lo:[0,1] neg_hi:[0,1]
	v_pk_add_f32 v[56:57], v[56:57], v[116:117] op_sel_hi:[1,0] neg_lo:[0,1] neg_hi:[0,1]
	v_pk_add_f32 v[40:41], v[40:41], v[116:117] op_sel_hi:[1,0] neg_lo:[0,1] neg_hi:[0,1]
	v_pk_add_f32 v[58:59], v[58:59], v[116:117] op_sel_hi:[1,0] neg_lo:[0,1] neg_hi:[0,1]
	v_pk_add_f32 v[42:43], v[42:43], v[116:117] op_sel_hi:[1,0] neg_lo:[0,1] neg_hi:[0,1]
	v_pk_add_f32 v[60:61], v[60:61], v[116:117] op_sel_hi:[1,0] neg_lo:[0,1] neg_hi:[0,1]
	v_pk_add_f32 v[44:45], v[44:45], v[116:117] op_sel_hi:[1,0] neg_lo:[0,1] neg_hi:[0,1]
	v_pk_add_f32 v[62:63], v[62:63], v[116:117] op_sel_hi:[1,0] neg_lo:[0,1] neg_hi:[0,1]
	v_pk_add_f32 v[46:47], v[46:47], v[116:117] op_sel_hi:[1,0] neg_lo:[0,1] neg_hi:[0,1]
	v_pk_add_f32 v[64:65], v[64:65], v[116:117] op_sel_hi:[1,0] neg_lo:[0,1] neg_hi:[0,1]
	v_pk_add_f32 v[48:49], v[48:49], v[116:117] op_sel_hi:[1,0] neg_lo:[0,1] neg_hi:[0,1]
	v_mul_f32_e32 v155, v155, v0
	s_branch .LBB0_319

.LBB0_332:
	v_add_f32_e32 v0, v116, v117
	v_add_f32_e32 v151, v151, v0
	v_max_f32_e32 v0, v50, v51
	v_max3_f32 v0, v0, v52, v53
	v_max3_f32 v0, v0, v54, v55
	v_max3_f32 v0, v0, v56, v57
	v_max3_f32 v0, v0, v58, v59
	v_max3_f32 v0, v0, v60, v61
	v_max3_f32 v0, v0, v62, v63
	v_max3_f32 v0, v0, v64, v65
	v_max3_f32 v0, v0, v34, v35
	v_max3_f32 v0, v0, v36, v37
	v_max3_f32 v0, v0, v38, v39
	v_max3_f32 v0, v0, v40, v41
	v_max3_f32 v0, v0, v42, v43
	v_max3_f32 v0, v0, v44, v45
	v_max3_f32 v0, v0, v46, v47
	v_max3_f32 v0, v0, v48, v49
	ds_bpermute_b32 v116, v154, v0
	s_waitcnt lgkmcnt(0)
	v_max_f32_e32 v0, v0, v116
	v_cmp_lt_f32_e32 vcc, s33, v0
	s_cmp_lg_u64 vcc, 0
	s_cselect_b64 s[6:7], -1, 0
	s_cbranch_vccz .LBB0_334
	v_max_f32_e32 v0, v0, v0
	v_max_f32_e32 v116, 0, v0
	v_exp_f32_e64 v0, -v116
	v_add_f32_e32 v155, v155, v116
	v_xor_b32_e32 v220, 0x80000000, v155
	v_mov_b32_e32 v221, v220
	v_mov_b32_e32 v222, v220
	v_mov_b32_e32 v223, v220
	v_mov_b32_e32 v224, v220
	v_mov_b32_e32 v225, v220
	v_mov_b32_e32 v226, v220
	v_mov_b32_e32 v227, v220
	v_mov_b32_e32 v228, v220
	v_mov_b32_e32 v229, v220
	v_mov_b32_e32 v230, v220
	v_mov_b32_e32 v231, v220
	v_mov_b32_e32 v232, v220
	v_mov_b32_e32 v233, v220
	v_mov_b32_e32 v234, v220
	v_mov_b32_e32 v235, v220
	v_pk_add_f32 v[50:51], v[50:51], v[116:117] op_sel_hi:[1,0] neg_lo:[0,1] neg_hi:[0,1]
	v_pk_add_f32 v[34:35], v[34:35], v[116:117] op_sel_hi:[1,0] neg_lo:[0,1] neg_hi:[0,1]
	v_pk_add_f32 v[52:53], v[52:53], v[116:117] op_sel_hi:[1,0] neg_lo:[0,1] neg_hi:[0,1]
	v_pk_add_f32 v[36:37], v[36:37], v[116:117] op_sel_hi:[1,0] neg_lo:[0,1] neg_hi:[0,1]
	v_pk_add_f32 v[54:55], v[54:55], v[116:117] op_sel_hi:[1,0] neg_lo:[0,1] neg_hi:[0,1]
	v_pk_add_f32 v[38:39], v[38:39], v[116:117] op_sel_hi:[1,0] neg_lo:[0,1] neg_hi:[0,1]
	v_pk_add_f32 v[56:57], v[56:57], v[116:117] op_sel_hi:[1,0] neg_lo:[0,1] neg_hi:[0,1]
	v_pk_add_f32 v[40:41], v[40:41], v[116:117] op_sel_hi:[1,0] neg_lo:[0,1] neg_hi:[0,1]
	v_pk_add_f32 v[58:59], v[58:59], v[116:117] op_sel_hi:[1,0] neg_lo:[0,1] neg_hi:[0,1]
	v_pk_add_f32 v[42:43], v[42:43], v[116:117] op_sel_hi:[1,0] neg_lo:[0,1] neg_hi:[0,1]
	v_pk_add_f32 v[60:61], v[60:61], v[116:117] op_sel_hi:[1,0] neg_lo:[0,1] neg_hi:[0,1]
	v_pk_add_f32 v[44:45], v[44:45], v[116:117] op_sel_hi:[1,0] neg_lo:[0,1] neg_hi:[0,1]
	v_pk_add_f32 v[62:63], v[62:63], v[116:117] op_sel_hi:[1,0] neg_lo:[0,1] neg_hi:[0,1]
	v_pk_add_f32 v[46:47], v[46:47], v[116:117] op_sel_hi:[1,0] neg_lo:[0,1] neg_hi:[0,1]
	v_pk_add_f32 v[64:65], v[64:65], v[116:117] op_sel_hi:[1,0] neg_lo:[0,1] neg_hi:[0,1]
	v_pk_add_f32 v[48:49], v[48:49], v[116:117] op_sel_hi:[1,0] neg_lo:[0,1] neg_hi:[0,1]
	v_mul_f32_e32 v151, v151, v0
	s_branch .LBB0_335

.LBB0_362:
	s_mul_i32 s13, s12, 0x5c00
	v_add_u32_e32 v0, s13, v173
	ds_read_b128 v[102:105], v0
	ds_read_b128 v[106:109], v0 offset:6656
	ds_read_b128 v[110:113], v0 offset:32
	s_waitcnt lgkmcnt(2)
	v_mfma_f32_32x32x16_bf16 v[50:65], v[102:105], v[66:69], v[220:235]
	v_cvt_pk_bf16_f32 v114, v136, v137
	v_add_f32_e64 v116, v136, 0
	v_add_f32_e64 v117, v137, 0
	s_waitcnt lgkmcnt(1)
	v_mfma_f32_32x32x16_bf16 v[34:49], v[106:109], v[66:69], v[220:235]
	ds_read_b128 v[102:105], v0 offset:6688
	v_cvt_pk_bf16_f32 v115, v134, v135
	v_add_f32_e64 v134, v134, v116
	v_add_f32_e64 v135, v135, v117
	s_waitcnt lgkmcnt(1)
	v_mfma_f32_32x32x16_bf16 v[50:65], v[110:113], v[70:73], v[50:65]
	ds_read_b128 v[106:109], v0 offset:64
	v_add_f32_e64 v110, v132, v134
	v_add_f32_e64 v111, v133, v135
	v_cvt_pk_bf16_f32 v116, v132, v133
	v_cvt_pk_bf16_f32 v117, v138, v139
	v_pk_add_f32 v[112:113], v[138:139], v[110:111]
	s_nop 0
	s_waitcnt lgkmcnt(1)
	v_mfma_f32_32x32x16_bf16 v[34:49], v[102:105], v[70:73], v[34:49]
	ds_read_b128 v[132:135], v0 offset:6720
	v_cvt_pk_bf16_f32 v110, v152, v153
	v_add_f32_e64 v112, v152, v112
	v_add_f32_e64 v113, v153, v113
	s_waitcnt lgkmcnt(1)
	v_mfma_f32_32x32x16_bf16 v[50:65], v[106:109], v[74:77], v[50:65]
	ds_read_b128 v[102:105], v0 offset:96
	v_cvt_pk_bf16_f32 v111, v150, v151
	v_add_f32_e64 v106, v150, v112
	v_add_f32_e64 v107, v151, v113
	s_waitcnt lgkmcnt(1)
	v_mfma_f32_32x32x16_bf16 v[34:49], v[132:135], v[74:77], v[34:49]
	ds_read_b128 v[136:139], v0 offset:6752
	v_add_f32_e64 v106, v156, v106
	v_add_f32_e64 v107, v157, v107
	v_cvt_pk_bf16_f32 v112, v156, v157
	v_cvt_pk_bf16_f32 v113, v160, v161
	v_pk_add_f32 v[108:109], v[160:161], v[106:107]
	s_nop 0
	s_waitcnt lgkmcnt(1)
	v_mfma_f32_32x32x16_bf16 v[50:65], v[102:105], v[78:81], v[50:65]
	ds_read_b128 v[132:135], v0 offset:128
	v_cvt_pk_bf16_f32 v106, v148, v149
	v_add_f32_e64 v108, v148, v108
	v_add_f32_e64 v109, v149, v109
	s_waitcnt lgkmcnt(1)
	v_mfma_f32_32x32x16_bf16 v[34:49], v[136:139], v[78:81], v[34:49]
	ds_read_b128 v[102:105], v0 offset:6784
	v_cvt_pk_bf16_f32 v107, v140, v141
	v_add_f32_e64 v140, v140, v108
	v_add_f32_e64 v141, v141, v109
	s_waitcnt lgkmcnt(1)
	v_mfma_f32_32x32x16_bf16 v[50:65], v[132:135], v[82:85], v[50:65]
	ds_read_b128 v[136:139], v0 offset:160
	v_add_f32_e64 v132, v154, v140
	v_add_f32_e64 v133, v155, v141
	v_cvt_pk_bf16_f32 v108, v154, v155
	v_cvt_pk_bf16_f32 v109, v158, v159
	v_pk_add_f32 v[140:141], v[158:159], v[132:133]
	s_nop 0
	s_waitcnt lgkmcnt(1)
	v_mfma_f32_32x32x16_bf16 v[34:49], v[102:105], v[82:85], v[34:49]
	ds_read_b128 v[132:135], v0 offset:6816
	v_cvt_pk_bf16_f32 v102, v162, v163
	v_add_f32_e64 v104, v162, v140
	v_add_f32_e64 v105, v163, v141
	s_waitcnt lgkmcnt(1)
	v_mfma_f32_32x32x16_bf16 v[50:65], v[136:139], v[86:89], v[50:65]
	v_cvt_pk_bf16_f32 v103, v164, v165
	v_add_f32_e64 v136, v164, v104
	v_add_f32_e64 v137, v165, v105
	s_waitcnt lgkmcnt(0)
	v_mfma_f32_32x32x16_bf16 v[34:49], v[132:135], v[86:89], v[34:49]
	v_add_f32_e64 v132, v166, v136
	v_add_f32_e64 v133, v167, v137
	v_cvt_pk_bf16_f32 v104, v166, v167
	v_cvt_pk_bf16_f32 v105, v168, v169
	v_add_f32_e64 v132, v168, v132
	v_add_f32_e64 v133, v169, v133
	s_nop 0
	v_max_f32_e32 v121, v50, v51
	v_max3_f32 v121, v121, v52, v53
	v_max3_f32 v121, v121, v54, v55
	v_max3_f32 v121, v121, v56, v57
	v_max3_f32 v121, v121, v58, v59
	v_max3_f32 v121, v121, v60, v61
	v_max3_f32 v121, v121, v62, v63
	v_max3_f32 v121, v121, v64, v65
	v_max3_f32 v121, v121, v34, v35
	v_max3_f32 v121, v121, v36, v37
	v_max3_f32 v121, v121, v38, v39
	v_max3_f32 v121, v121, v40, v41
	v_max3_f32 v121, v121, v42, v43
	v_max3_f32 v121, v121, v44, v45
	v_max3_f32 v121, v121, v46, v47
	v_add_f32_e32 v0, v132, v133
	v_max3_f32 v121, v121, v48, v49
	v_add_f32_e32 v174, v174, v0
	ds_bpermute_b32 v0, v125, v121
	s_waitcnt lgkmcnt(0)
	v_max_f32_e32 v0, v121, v0
	v_cmp_lt_f32_e32 vcc, s33, v0
	s_cmp_lg_u64 vcc, 0
	s_cselect_b64 s[10:11], -1, 0
	s_cbranch_vccz .LBB0_364
	v_max_f32_e32 v0, v0, v0
	v_max_f32_e32 v132, 0, v0
	v_exp_f32_e64 v0, -v132
	v_add_f32_e32 v176, v176, v132
	v_xor_b32_e32 v220, 0x80000000, v176
	v_mov_b32_e32 v221, v220
	v_mov_b32_e32 v222, v220
	v_mov_b32_e32 v223, v220
	v_mov_b32_e32 v224, v220
	v_mov_b32_e32 v225, v220
	v_mov_b32_e32 v226, v220
	v_mov_b32_e32 v227, v220
	v_mov_b32_e32 v228, v220
	v_mov_b32_e32 v229, v220
	v_mov_b32_e32 v230, v220
	v_mov_b32_e32 v231, v220
	v_mov_b32_e32 v232, v220
	v_mov_b32_e32 v233, v220
	v_mov_b32_e32 v234, v220
	v_mov_b32_e32 v235, v220
	v_pk_add_f32 v[50:51], v[50:51], v[132:133] op_sel_hi:[1,0] neg_lo:[0,1] neg_hi:[0,1]
	v_pk_add_f32 v[34:35], v[34:35], v[132:133] op_sel_hi:[1,0] neg_lo:[0,1] neg_hi:[0,1]
	v_pk_add_f32 v[52:53], v[52:53], v[132:133] op_sel_hi:[1,0] neg_lo:[0,1] neg_hi:[0,1]
	v_pk_add_f32 v[36:37], v[36:37], v[132:133] op_sel_hi:[1,0] neg_lo:[0,1] neg_hi:[0,1]
	v_pk_add_f32 v[54:55], v[54:55], v[132:133] op_sel_hi:[1,0] neg_lo:[0,1] neg_hi:[0,1]
	v_pk_add_f32 v[38:39], v[38:39], v[132:133] op_sel_hi:[1,0] neg_lo:[0,1] neg_hi:[0,1]
	v_pk_add_f32 v[56:57], v[56:57], v[132:133] op_sel_hi:[1,0] neg_lo:[0,1] neg_hi:[0,1]
	v_pk_add_f32 v[40:41], v[40:41], v[132:133] op_sel_hi:[1,0] neg_lo:[0,1] neg_hi:[0,1]
	v_pk_add_f32 v[58:59], v[58:59], v[132:133] op_sel_hi:[1,0] neg_lo:[0,1] neg_hi:[0,1]
	v_pk_add_f32 v[42:43], v[42:43], v[132:133] op_sel_hi:[1,0] neg_lo:[0,1] neg_hi:[0,1]
	v_pk_add_f32 v[60:61], v[60:61], v[132:133] op_sel_hi:[1,0] neg_lo:[0,1] neg_hi:[0,1]
	v_pk_add_f32 v[44:45], v[44:45], v[132:133] op_sel_hi:[1,0] neg_lo:[0,1] neg_hi:[0,1]
	v_pk_add_f32 v[62:63], v[62:63], v[132:133] op_sel_hi:[1,0] neg_lo:[0,1] neg_hi:[0,1]
	v_pk_add_f32 v[46:47], v[46:47], v[132:133] op_sel_hi:[1,0] neg_lo:[0,1] neg_hi:[0,1]
	v_pk_add_f32 v[64:65], v[64:65], v[132:133] op_sel_hi:[1,0] neg_lo:[0,1] neg_hi:[0,1]
	v_pk_add_f32 v[48:49], v[48:49], v[132:133] op_sel_hi:[1,0] neg_lo:[0,1] neg_hi:[0,1]
	v_mul_f32_e32 v174, v174, v0
	s_branch .LBB0_365

.LBB0_395:
	s_mul_i32 s14, s8, 0x4c00
	v_add_u32_e32 v0, s14, v155
	ds_read_b128 v[160:163], v0
	ds_read_b128 v[164:167], v0 offset:4608
	ds_read_b128 v[168:171], v0 offset:32
	s_waitcnt lgkmcnt(2)
	v_mfma_f32_32x32x16_bf16 v[50:65], v[160:163], v[66:69], v[220:235]
	v_add_f32_e64 v90, v116, 0
	v_add_f32_e64 v91, v117, 0
	v_cvt_pk_bf16_f32 v102, v116, v117
	v_add_f32_e64 v90, v118, v90
	v_add_f32_e64 v91, v119, v91
	v_cvt_pk_bf16_f32 v103, v118, v119
	s_waitcnt lgkmcnt(1)
	v_mfma_f32_32x32x16_bf16 v[34:49], v[164:167], v[66:69], v[220:235]
	ds_read_b128 v[116:119], v0 offset:4640
	v_add_f32_e64 v90, v104, v90
	v_add_f32_e64 v91, v105, v91
	v_cvt_pk_bf16_f32 v104, v104, v105
	v_add_f32_e64 v90, v124, v90
	v_add_f32_e64 v91, v125, v91
	v_cvt_pk_bf16_f32 v105, v124, v125
	s_waitcnt lgkmcnt(1)
	v_mfma_f32_32x32x16_bf16 v[50:65], v[168:171], v[70:73], v[50:65]
	ds_read_b128 v[160:163], v0 offset:64
	v_add_f32_e64 v90, v126, v90
	v_add_f32_e64 v91, v127, v91
	v_cvt_pk_bf16_f32 v98, v126, v127
	v_add_f32_e64 v90, v128, v90
	v_add_f32_e64 v91, v129, v91
	v_cvt_pk_bf16_f32 v99, v128, v129
	s_waitcnt lgkmcnt(1)
	v_mfma_f32_32x32x16_bf16 v[34:49], v[116:119], v[70:73], v[34:49]
	ds_read_b128 v[124:127], v0 offset:4672
	v_add_f32_e64 v90, v100, v90
	v_add_f32_e64 v91, v101, v91
	v_cvt_pk_bf16_f32 v100, v100, v101
	v_add_f32_e64 v90, v130, v90
	v_add_f32_e64 v91, v131, v91
	v_cvt_pk_bf16_f32 v101, v130, v131
	s_waitcnt lgkmcnt(1)
	v_mfma_f32_32x32x16_bf16 v[50:65], v[160:163], v[74:77], v[50:65]
	ds_read_b128 v[116:119], v0 offset:96
	v_add_f32_e64 v90, v120, v90
	v_add_f32_e64 v91, v121, v91
	v_cvt_pk_bf16_f32 v94, v120, v121
	v_add_f32_e64 v90, v122, v90
	v_add_f32_e64 v91, v123, v91
	v_cvt_pk_bf16_f32 v95, v122, v123
	s_waitcnt lgkmcnt(1)
	v_mfma_f32_32x32x16_bf16 v[34:49], v[124:127], v[74:77], v[34:49]
	ds_read_b128 v[120:123], v0 offset:4704
	v_add_f32_e64 v90, v96, v90
	v_add_f32_e64 v91, v97, v91
	v_cvt_pk_bf16_f32 v96, v96, v97
	v_add_f32_e64 v90, v132, v90
	v_add_f32_e64 v91, v133, v91
	v_cvt_pk_bf16_f32 v97, v132, v133
	s_waitcnt lgkmcnt(1)
	v_mfma_f32_32x32x16_bf16 v[50:65], v[116:119], v[78:81], v[50:65]
	v_add_f32_e64 v116, v134, v90
	v_add_f32_e64 v117, v135, v91
	v_cvt_pk_bf16_f32 v90, v134, v135
	v_add_f32_e64 v116, v136, v116
	v_add_f32_e64 v117, v137, v117
	v_cvt_pk_bf16_f32 v91, v136, v137
	s_waitcnt lgkmcnt(0)
	v_mfma_f32_32x32x16_bf16 v[34:49], v[120:123], v[78:81], v[34:49]
	v_add_f32_e64 v116, v92, v116
	v_add_f32_e64 v117, v93, v117
	v_cvt_pk_bf16_f32 v92, v92, v93
	v_add_f32_e64 v116, v138, v116
	v_add_f32_e64 v117, v139, v117
	v_cvt_pk_bf16_f32 v93, v138, v139
	s_nop 0
	v_add_f32_e32 v0, v116, v117
	v_max_f32_e32 v116, v50, v51
	v_max3_f32 v116, v116, v52, v53
	v_max3_f32 v116, v116, v54, v55
	v_max3_f32 v116, v116, v56, v57
	v_max3_f32 v116, v116, v58, v59
	v_max3_f32 v116, v116, v60, v61
	v_max3_f32 v116, v116, v62, v63
	v_max3_f32 v116, v116, v64, v65
	v_max3_f32 v116, v116, v34, v35
	v_max3_f32 v116, v116, v36, v37
	v_max3_f32 v116, v116, v38, v39
	v_max3_f32 v116, v116, v40, v41
	v_max3_f32 v116, v116, v42, v43
	v_max3_f32 v116, v116, v44, v45
	v_max3_f32 v116, v116, v46, v47
	v_max3_f32 v116, v116, v48, v49
	v_add_f32_e32 v157, v157, v0
	ds_bpermute_b32 v0, v156, v116
	s_waitcnt lgkmcnt(0)
	v_max_f32_e32 v0, v116, v0
	v_cmp_lt_f32_e32 vcc, s33, v0
	s_cmp_lg_u64 vcc, 0
	s_cselect_b64 s[14:15], -1, 0
	s_cbranch_vccz .LBB0_397
	v_max_f32_e32 v0, v0, v0
	v_max_f32_e32 v116, 0, v0
	v_exp_f32_e64 v0, -v116
	v_add_f32_e32 v158, v158, v116
	v_xor_b32_e32 v220, 0x80000000, v158
	v_mov_b32_e32 v221, v220
	v_mov_b32_e32 v222, v220
	v_mov_b32_e32 v223, v220
	v_mov_b32_e32 v224, v220
	v_mov_b32_e32 v225, v220
	v_mov_b32_e32 v226, v220
	v_mov_b32_e32 v227, v220
	v_mov_b32_e32 v228, v220
	v_mov_b32_e32 v229, v220
	v_mov_b32_e32 v230, v220
	v_mov_b32_e32 v231, v220
	v_mov_b32_e32 v232, v220
	v_mov_b32_e32 v233, v220
	v_mov_b32_e32 v234, v220
	v_mov_b32_e32 v235, v220
	v_pk_add_f32 v[50:51], v[50:51], v[116:117] op_sel_hi:[1,0] neg_lo:[0,1] neg_hi:[0,1]
	v_pk_add_f32 v[34:35], v[34:35], v[116:117] op_sel_hi:[1,0] neg_lo:[0,1] neg_hi:[0,1]
	v_pk_add_f32 v[52:53], v[52:53], v[116:117] op_sel_hi:[1,0] neg_lo:[0,1] neg_hi:[0,1]
	v_pk_add_f32 v[36:37], v[36:37], v[116:117] op_sel_hi:[1,0] neg_lo:[0,1] neg_hi:[0,1]
	v_pk_add_f32 v[54:55], v[54:55], v[116:117] op_sel_hi:[1,0] neg_lo:[0,1] neg_hi:[0,1]
	v_pk_add_f32 v[38:39], v[38:39], v[116:117] op_sel_hi:[1,0] neg_lo:[0,1] neg_hi:[0,1]
	v_pk_add_f32 v[56:57], v[56:57], v[116:117] op_sel_hi:[1,0] neg_lo:[0,1] neg_hi:[0,1]
	v_pk_add_f32 v[40:41], v[40:41], v[116:117] op_sel_hi:[1,0] neg_lo:[0,1] neg_hi:[0,1]
	v_pk_add_f32 v[58:59], v[58:59], v[116:117] op_sel_hi:[1,0] neg_lo:[0,1] neg_hi:[0,1]
	v_pk_add_f32 v[42:43], v[42:43], v[116:117] op_sel_hi:[1,0] neg_lo:[0,1] neg_hi:[0,1]
	v_pk_add_f32 v[60:61], v[60:61], v[116:117] op_sel_hi:[1,0] neg_lo:[0,1] neg_hi:[0,1]
	v_pk_add_f32 v[44:45], v[44:45], v[116:117] op_sel_hi:[1,0] neg_lo:[0,1] neg_hi:[0,1]
	v_pk_add_f32 v[62:63], v[62:63], v[116:117] op_sel_hi:[1,0] neg_lo:[0,1] neg_hi:[0,1]
	v_pk_add_f32 v[46:47], v[46:47], v[116:117] op_sel_hi:[1,0] neg_lo:[0,1] neg_hi:[0,1]
	v_pk_add_f32 v[64:65], v[64:65], v[116:117] op_sel_hi:[1,0] neg_lo:[0,1] neg_hi:[0,1]
	v_pk_add_f32 v[48:49], v[48:49], v[116:117] op_sel_hi:[1,0] neg_lo:[0,1] neg_hi:[0,1]
	v_mul_f32_e32 v157, v157, v0
	s_branch .LBB0_398

.LBB0_424:
	v_add_f32_e32 v0, v116, v117
	v_add_f32_e32 v111, v111, v0
	v_max_f32_e32 v0, v50, v51
	v_max3_f32 v0, v0, v52, v53
	v_max3_f32 v0, v0, v54, v55
	v_max3_f32 v0, v0, v56, v57
	v_max3_f32 v0, v0, v58, v59
	v_max3_f32 v0, v0, v60, v61
	v_max3_f32 v0, v0, v62, v63
	v_max3_f32 v0, v0, v64, v65
	v_max3_f32 v0, v0, v34, v35
	v_max3_f32 v0, v0, v36, v37
	v_max3_f32 v0, v0, v38, v39
	v_max3_f32 v0, v0, v40, v41
	v_max3_f32 v0, v0, v42, v43
	v_max3_f32 v0, v0, v44, v45
	v_max3_f32 v0, v0, v46, v47
	v_max3_f32 v0, v0, v48, v49
	ds_bpermute_b32 v116, v109, v0
	s_waitcnt lgkmcnt(0)
	v_max_f32_e32 v0, v0, v116
	v_cmp_lt_f32_e32 vcc, s25, v0
	s_cmp_lg_u64 vcc, 0
	s_cselect_b64 s[6:7], -1, 0
	s_cbranch_vccz .LBB0_426
	v_max_f32_e32 v0, v0, v0
	v_max_f32_e32 v116, 0, v0
	v_exp_f32_e64 v0, -v116
	v_add_f32_e32 v158, v158, v116
	v_xor_b32_e32 v220, 0x80000000, v158
	v_mov_b32_e32 v221, v220
	v_mov_b32_e32 v222, v220
	v_mov_b32_e32 v223, v220
	v_mov_b32_e32 v224, v220
	v_mov_b32_e32 v225, v220
	v_mov_b32_e32 v226, v220
	v_mov_b32_e32 v227, v220
	v_mov_b32_e32 v228, v220
	v_mov_b32_e32 v229, v220
	v_mov_b32_e32 v230, v220
	v_mov_b32_e32 v231, v220
	v_mov_b32_e32 v232, v220
	v_mov_b32_e32 v233, v220
	v_mov_b32_e32 v234, v220
	v_mov_b32_e32 v235, v220
	v_pk_add_f32 v[50:51], v[50:51], v[116:117] op_sel_hi:[1,0] neg_lo:[0,1] neg_hi:[0,1]
	v_pk_add_f32 v[34:35], v[34:35], v[116:117] op_sel_hi:[1,0] neg_lo:[0,1] neg_hi:[0,1]
	v_pk_add_f32 v[52:53], v[52:53], v[116:117] op_sel_hi:[1,0] neg_lo:[0,1] neg_hi:[0,1]
	v_pk_add_f32 v[36:37], v[36:37], v[116:117] op_sel_hi:[1,0] neg_lo:[0,1] neg_hi:[0,1]
	v_pk_add_f32 v[54:55], v[54:55], v[116:117] op_sel_hi:[1,0] neg_lo:[0,1] neg_hi:[0,1]
	v_pk_add_f32 v[38:39], v[38:39], v[116:117] op_sel_hi:[1,0] neg_lo:[0,1] neg_hi:[0,1]
	v_pk_add_f32 v[56:57], v[56:57], v[116:117] op_sel_hi:[1,0] neg_lo:[0,1] neg_hi:[0,1]
	v_pk_add_f32 v[40:41], v[40:41], v[116:117] op_sel_hi:[1,0] neg_lo:[0,1] neg_hi:[0,1]
	v_pk_add_f32 v[58:59], v[58:59], v[116:117] op_sel_hi:[1,0] neg_lo:[0,1] neg_hi:[0,1]
	v_pk_add_f32 v[42:43], v[42:43], v[116:117] op_sel_hi:[1,0] neg_lo:[0,1] neg_hi:[0,1]
	v_pk_add_f32 v[60:61], v[60:61], v[116:117] op_sel_hi:[1,0] neg_lo:[0,1] neg_hi:[0,1]
	v_pk_add_f32 v[44:45], v[44:45], v[116:117] op_sel_hi:[1,0] neg_lo:[0,1] neg_hi:[0,1]
	v_pk_add_f32 v[62:63], v[62:63], v[116:117] op_sel_hi:[1,0] neg_lo:[0,1] neg_hi:[0,1]
	v_pk_add_f32 v[46:47], v[46:47], v[116:117] op_sel_hi:[1,0] neg_lo:[0,1] neg_hi:[0,1]
	v_pk_add_f32 v[64:65], v[64:65], v[116:117] op_sel_hi:[1,0] neg_lo:[0,1] neg_hi:[0,1]
	v_pk_add_f32 v[48:49], v[48:49], v[116:117] op_sel_hi:[1,0] neg_lo:[0,1] neg_hi:[0,1]
	v_mul_f32_e32 v111, v111, v0
	s_branch .LBB0_427

.LBB0_445:
	s_mul_i32 s14, s8, 0x7400
	v_add_u32_e32 v0, s14, v208
	ds_read_b128 v[126:129], v0
	ds_read_b128 v[130:133], v0 offset:4608
	ds_read_b128 v[134:137], v0 offset:32
	s_waitcnt lgkmcnt(2)
	v_mfma_f32_32x32x16_bf16 v[82:97], v[126:129], v[98:101], v[220:235]
	v_add_f32_e64 v126, v158, 0
	v_add_f32_e64 v127, v159, 0
	v_cvt_pk_bf16_f32 v138, v158, v159
	v_add_f32_e64 v140, v160, v126
	v_add_f32_e64 v141, v161, v127
	v_cvt_pk_bf16_f32 v139, v160, v161
	s_waitcnt lgkmcnt(1)
	v_mfma_f32_32x32x16_bf16 v[66:81], v[130:133], v[98:101], v[220:235]
	ds_read_b128 v[126:129], v0 offset:4640
	v_add_f32_e64 v130, v162, v140
	v_add_f32_e64 v131, v163, v141
	v_cvt_pk_bf16_f32 v140, v162, v163
	v_add_f32_e64 v158, v164, v130
	v_add_f32_e64 v159, v165, v131
	v_cvt_pk_bf16_f32 v141, v164, v165
	s_waitcnt lgkmcnt(1)
	v_mfma_f32_32x32x16_bf16 v[82:97], v[134:137], v[102:105], v[82:97]
	ds_read_b128 v[130:133], v0 offset:64
	v_add_f32_e64 v136, v166, v158
	v_add_f32_e64 v137, v167, v159
	v_cvt_pk_bf16_f32 v134, v166, v167
	v_add_f32_e64 v136, v170, v136
	v_add_f32_e64 v137, v171, v137
	v_cvt_pk_bf16_f32 v135, v170, v171
	s_waitcnt lgkmcnt(1)
	v_mfma_f32_32x32x16_bf16 v[66:81], v[126:129], v[102:105], v[66:81]
	ds_read_b128 v[158:161], v0 offset:4672
	v_add_f32_e64 v126, v174, v136
	v_add_f32_e64 v127, v175, v137
	v_cvt_pk_bf16_f32 v136, v174, v175
	v_add_f32_e64 v162, v178, v126
	v_add_f32_e64 v163, v179, v127
	v_cvt_pk_bf16_f32 v137, v178, v179
	s_waitcnt lgkmcnt(1)
	v_mfma_f32_32x32x16_bf16 v[82:97], v[130:133], v[106:109], v[82:97]
	ds_read_b128 v[126:129], v0 offset:96
	v_add_f32_e64 v132, v168, v162
	v_add_f32_e64 v133, v169, v163
	v_cvt_pk_bf16_f32 v130, v168, v169
	v_add_f32_e64 v132, v172, v132
	v_add_f32_e64 v133, v173, v133
	v_cvt_pk_bf16_f32 v131, v172, v173
	s_waitcnt lgkmcnt(1)
	v_mfma_f32_32x32x16_bf16 v[66:81], v[158:161], v[106:109], v[66:81]
	ds_read_b128 v[162:165], v0 offset:4704
	v_add_f32_e64 v158, v176, v132
	v_add_f32_e64 v159, v177, v133
	v_cvt_pk_bf16_f32 v132, v176, v177
	v_add_f32_e64 v158, v180, v158
	v_add_f32_e64 v159, v181, v159
	v_cvt_pk_bf16_f32 v133, v180, v181
	s_waitcnt lgkmcnt(1)
	v_mfma_f32_32x32x16_bf16 v[82:97], v[126:129], v[110:113], v[82:97]
	v_add_f32_e64 v128, v182, v158
	v_add_f32_e64 v129, v183, v159
	v_cvt_pk_bf16_f32 v126, v182, v183
	v_add_f32_e64 v128, v184, v128
	v_add_f32_e64 v129, v185, v129
	v_cvt_pk_bf16_f32 v127, v184, v185
	s_waitcnt lgkmcnt(0)
	v_mfma_f32_32x32x16_bf16 v[66:81], v[162:165], v[110:113], v[66:81]
	v_add_f32_e64 v158, v186, v128
	v_add_f32_e64 v159, v187, v129
	v_cvt_pk_bf16_f32 v128, v186, v187
	v_add_f32_e64 v158, v188, v158
	v_add_f32_e64 v159, v189, v159
	v_cvt_pk_bf16_f32 v129, v188, v189
	s_nop 0
	v_add_f32_e32 v0, v158, v159
	v_max_f32_e32 v158, v82, v83
	v_max3_f32 v158, v158, v84, v85
	v_max3_f32 v158, v158, v86, v87
	v_max3_f32 v158, v158, v88, v89
	v_max3_f32 v158, v158, v90, v91
	v_max3_f32 v158, v158, v92, v93
	v_max3_f32 v158, v158, v94, v95
	v_max3_f32 v158, v158, v96, v97
	v_max3_f32 v158, v158, v66, v67
	v_max3_f32 v158, v158, v68, v69
	v_max3_f32 v158, v158, v70, v71
	v_max3_f32 v158, v158, v72, v73
	v_max3_f32 v158, v158, v74, v75
	v_max3_f32 v158, v158, v76, v77
	v_max3_f32 v158, v158, v78, v79
	v_max3_f32 v158, v158, v80, v81
	v_add_f32_e32 v206, v206, v0
	ds_bpermute_b32 v0, v190, v158
	s_waitcnt lgkmcnt(0)
	v_max_f32_e32 v0, v158, v0
	v_cmp_lt_f32_e32 vcc, s30, v0
	s_cmp_lg_u64 vcc, 0
	s_cselect_b64 s[12:13], -1, 0
	s_cbranch_vccz .LBB0_447
	v_max_f32_e32 v0, v0, v0
	v_max_f32_e32 v158, 0, v0
	v_exp_f32_e64 v0, -v158
	v_add_f32_e32 v210, v210, v158
	v_xor_b32_e32 v220, 0x80000000, v210
	v_mov_b32_e32 v221, v220
	v_mov_b32_e32 v222, v220
	v_mov_b32_e32 v223, v220
	v_mov_b32_e32 v224, v220
	v_mov_b32_e32 v225, v220
	v_mov_b32_e32 v226, v220
	v_mov_b32_e32 v227, v220
	v_mov_b32_e32 v228, v220
	v_mov_b32_e32 v229, v220
	v_mov_b32_e32 v230, v220
	v_mov_b32_e32 v231, v220
	v_mov_b32_e32 v232, v220
	v_mov_b32_e32 v233, v220
	v_mov_b32_e32 v234, v220
	v_mov_b32_e32 v235, v220
	v_pk_add_f32 v[82:83], v[82:83], v[158:159] op_sel_hi:[1,0] neg_lo:[0,1] neg_hi:[0,1]
	v_pk_add_f32 v[66:67], v[66:67], v[158:159] op_sel_hi:[1,0] neg_lo:[0,1] neg_hi:[0,1]
	v_pk_add_f32 v[84:85], v[84:85], v[158:159] op_sel_hi:[1,0] neg_lo:[0,1] neg_hi:[0,1]
	v_pk_add_f32 v[68:69], v[68:69], v[158:159] op_sel_hi:[1,0] neg_lo:[0,1] neg_hi:[0,1]
	v_pk_add_f32 v[86:87], v[86:87], v[158:159] op_sel_hi:[1,0] neg_lo:[0,1] neg_hi:[0,1]
	v_pk_add_f32 v[70:71], v[70:71], v[158:159] op_sel_hi:[1,0] neg_lo:[0,1] neg_hi:[0,1]
	v_pk_add_f32 v[88:89], v[88:89], v[158:159] op_sel_hi:[1,0] neg_lo:[0,1] neg_hi:[0,1]
	v_pk_add_f32 v[72:73], v[72:73], v[158:159] op_sel_hi:[1,0] neg_lo:[0,1] neg_hi:[0,1]
	v_pk_add_f32 v[90:91], v[90:91], v[158:159] op_sel_hi:[1,0] neg_lo:[0,1] neg_hi:[0,1]
	v_pk_add_f32 v[74:75], v[74:75], v[158:159] op_sel_hi:[1,0] neg_lo:[0,1] neg_hi:[0,1]
	v_pk_add_f32 v[92:93], v[92:93], v[158:159] op_sel_hi:[1,0] neg_lo:[0,1] neg_hi:[0,1]
	v_pk_add_f32 v[76:77], v[76:77], v[158:159] op_sel_hi:[1,0] neg_lo:[0,1] neg_hi:[0,1]
	v_pk_add_f32 v[94:95], v[94:95], v[158:159] op_sel_hi:[1,0] neg_lo:[0,1] neg_hi:[0,1]
	v_pk_add_f32 v[78:79], v[78:79], v[158:159] op_sel_hi:[1,0] neg_lo:[0,1] neg_hi:[0,1]
	v_pk_add_f32 v[96:97], v[96:97], v[158:159] op_sel_hi:[1,0] neg_lo:[0,1] neg_hi:[0,1]
	v_pk_add_f32 v[80:81], v[80:81], v[158:159] op_sel_hi:[1,0] neg_lo:[0,1] neg_hi:[0,1]
	v_mul_f32_e32 v206, v206, v0
	s_branch .LBB0_448

.LBB0_457:
	s_mul_i32 s11, s10, 0x7400
	v_add_u32_e32 v188, s11, v208
	ds_read_b128 v[126:129], v188
	ds_read_b128 v[130:133], v188 offset:4608
	ds_read_b128 v[134:137], v188 offset:32
	s_waitcnt lgkmcnt(2)
	v_mfma_f32_32x32x16_bf16 v[82:97], v[126:129], v[98:101], v[220:235]
	v_add_f32_e64 v126, v156, 0
	v_add_f32_e64 v127, v157, 0
	v_cvt_pk_bf16_f32 v138, v156, v157
	v_add_f32_e64 v140, v158, v126
	v_add_f32_e64 v141, v159, v127
	v_cvt_pk_bf16_f32 v139, v158, v159
	s_waitcnt lgkmcnt(1)
	v_mfma_f32_32x32x16_bf16 v[66:81], v[130:133], v[98:101], v[220:235]
	ds_read_b128 v[126:129], v188 offset:4640
	v_add_f32_e64 v130, v160, v140
	v_add_f32_e64 v131, v161, v141
	v_cvt_pk_bf16_f32 v140, v160, v161
	v_add_f32_e64 v156, v162, v130
	v_add_f32_e64 v157, v163, v131
	v_cvt_pk_bf16_f32 v141, v162, v163
	s_waitcnt lgkmcnt(1)
	v_mfma_f32_32x32x16_bf16 v[82:97], v[134:137], v[102:105], v[82:97]
	ds_read_b128 v[130:133], v188 offset:64
	v_add_f32_e64 v136, v164, v156
	v_add_f32_e64 v137, v165, v157
	v_cvt_pk_bf16_f32 v134, v164, v165
	v_add_f32_e64 v136, v168, v136
	v_add_f32_e64 v137, v169, v137
	v_cvt_pk_bf16_f32 v135, v168, v169
	s_waitcnt lgkmcnt(1)
	v_mfma_f32_32x32x16_bf16 v[66:81], v[126:129], v[102:105], v[66:81]
	ds_read_b128 v[156:159], v188 offset:4672
	v_add_f32_e64 v126, v172, v136
	v_add_f32_e64 v127, v173, v137
	v_cvt_pk_bf16_f32 v136, v172, v173
	v_add_f32_e64 v160, v176, v126
	v_add_f32_e64 v161, v177, v127
	v_cvt_pk_bf16_f32 v137, v176, v177
	s_waitcnt lgkmcnt(1)
	v_mfma_f32_32x32x16_bf16 v[82:97], v[130:133], v[106:109], v[82:97]
	ds_read_b128 v[126:129], v188 offset:96
	v_add_f32_e64 v132, v166, v160
	v_add_f32_e64 v133, v167, v161
	v_cvt_pk_bf16_f32 v130, v166, v167
	v_add_f32_e64 v132, v170, v132
	v_add_f32_e64 v133, v171, v133
	v_cvt_pk_bf16_f32 v131, v170, v171
	s_waitcnt lgkmcnt(1)
	v_mfma_f32_32x32x16_bf16 v[66:81], v[156:159], v[106:109], v[66:81]
	ds_read_b128 v[160:163], v188 offset:4704
	v_add_f32_e64 v156, v174, v132
	v_add_f32_e64 v157, v175, v133
	v_cvt_pk_bf16_f32 v132, v174, v175
	v_add_f32_e64 v156, v178, v156
	v_add_f32_e64 v157, v179, v157
	v_cvt_pk_bf16_f32 v133, v178, v179
	s_waitcnt lgkmcnt(1)
	v_mfma_f32_32x32x16_bf16 v[82:97], v[126:129], v[110:113], v[82:97]
	v_add_f32_e64 v128, v180, v156
	v_add_f32_e64 v129, v181, v157
	v_cvt_pk_bf16_f32 v126, v180, v181
	v_add_f32_e64 v128, v182, v128
	v_add_f32_e64 v129, v183, v129
	v_cvt_pk_bf16_f32 v127, v182, v183
	s_waitcnt lgkmcnt(0)
	v_mfma_f32_32x32x16_bf16 v[66:81], v[160:163], v[110:113], v[66:81]
	v_add_f32_e64 v156, v184, v128
	v_add_f32_e64 v157, v185, v129
	v_cvt_pk_bf16_f32 v128, v184, v185
	v_add_f32_e64 v156, v186, v156
	v_add_f32_e64 v157, v187, v157
	v_cvt_pk_bf16_f32 v129, v186, v187
	s_nop 0
	v_add_f32_e32 v156, v156, v157
	v_max_f32_e32 v157, v82, v83
	v_max3_f32 v157, v157, v84, v85
	v_max3_f32 v157, v157, v86, v87
	v_max3_f32 v157, v157, v88, v89
	v_max3_f32 v157, v157, v90, v91
	v_max3_f32 v157, v157, v92, v93
	v_max3_f32 v157, v157, v94, v95
	v_max3_f32 v157, v157, v96, v97
	v_max3_f32 v157, v157, v66, v67
	v_max3_f32 v157, v157, v68, v69
	v_max3_f32 v157, v157, v70, v71
	v_max3_f32 v157, v157, v72, v73
	v_max3_f32 v157, v157, v74, v75
	v_max3_f32 v157, v157, v76, v77
	v_max3_f32 v157, v157, v78, v79
	v_max3_f32 v157, v157, v80, v81
	v_add_f32_e32 v209, v209, v156
	ds_bpermute_b32 v156, v190, v157
	s_waitcnt lgkmcnt(0)
	v_max_f32_e32 v156, v157, v156
	v_cmp_lt_f32_e32 vcc, s30, v156
	s_cmp_lg_u64 vcc, 0
	s_cselect_b64 s[6:7], -1, 0
	s_cbranch_vccz .LBB0_459
	v_max_f32_e32 v156, v156, v156
	v_max_f32_e32 v156, 0, v156
	v_exp_f32_e64 v188, -v156
	v_add_f32_e32 v210, v210, v156
	v_xor_b32_e32 v220, 0x80000000, v210
	v_mov_b32_e32 v221, v220
	v_mov_b32_e32 v222, v220
	v_mov_b32_e32 v223, v220
	v_mov_b32_e32 v224, v220
	v_mov_b32_e32 v225, v220
	v_mov_b32_e32 v226, v220
	v_mov_b32_e32 v227, v220
	v_mov_b32_e32 v228, v220
	v_mov_b32_e32 v229, v220
	v_mov_b32_e32 v230, v220
	v_mov_b32_e32 v231, v220
	v_mov_b32_e32 v232, v220
	v_mov_b32_e32 v233, v220
	v_mov_b32_e32 v234, v220
	v_mov_b32_e32 v235, v220
	v_pk_add_f32 v[82:83], v[82:83], v[156:157] op_sel_hi:[1,0] neg_lo:[0,1] neg_hi:[0,1]
	v_pk_add_f32 v[66:67], v[66:67], v[156:157] op_sel_hi:[1,0] neg_lo:[0,1] neg_hi:[0,1]
	v_pk_add_f32 v[84:85], v[84:85], v[156:157] op_sel_hi:[1,0] neg_lo:[0,1] neg_hi:[0,1]
	v_pk_add_f32 v[68:69], v[68:69], v[156:157] op_sel_hi:[1,0] neg_lo:[0,1] neg_hi:[0,1]
	v_pk_add_f32 v[86:87], v[86:87], v[156:157] op_sel_hi:[1,0] neg_lo:[0,1] neg_hi:[0,1]
	v_pk_add_f32 v[70:71], v[70:71], v[156:157] op_sel_hi:[1,0] neg_lo:[0,1] neg_hi:[0,1]
	v_pk_add_f32 v[88:89], v[88:89], v[156:157] op_sel_hi:[1,0] neg_lo:[0,1] neg_hi:[0,1]
	v_pk_add_f32 v[72:73], v[72:73], v[156:157] op_sel_hi:[1,0] neg_lo:[0,1] neg_hi:[0,1]
	v_pk_add_f32 v[90:91], v[90:91], v[156:157] op_sel_hi:[1,0] neg_lo:[0,1] neg_hi:[0,1]
	v_pk_add_f32 v[74:75], v[74:75], v[156:157] op_sel_hi:[1,0] neg_lo:[0,1] neg_hi:[0,1]
	v_pk_add_f32 v[92:93], v[92:93], v[156:157] op_sel_hi:[1,0] neg_lo:[0,1] neg_hi:[0,1]
	v_pk_add_f32 v[76:77], v[76:77], v[156:157] op_sel_hi:[1,0] neg_lo:[0,1] neg_hi:[0,1]
	v_pk_add_f32 v[94:95], v[94:95], v[156:157] op_sel_hi:[1,0] neg_lo:[0,1] neg_hi:[0,1]
	v_pk_add_f32 v[78:79], v[78:79], v[156:157] op_sel_hi:[1,0] neg_lo:[0,1] neg_hi:[0,1]
	v_pk_add_f32 v[96:97], v[96:97], v[156:157] op_sel_hi:[1,0] neg_lo:[0,1] neg_hi:[0,1]
	v_pk_add_f32 v[80:81], v[80:81], v[156:157] op_sel_hi:[1,0] neg_lo:[0,1] neg_hi:[0,1]
	v_mul_f32_e32 v209, v209, v188
	s_branch .LBB0_460

.LBB0_511:
	s_or_b64 exec, exec, s[16:17]
	s_waitcnt vmcnt(20)
	v_lshlrev_b32_e32 v68, 16, v188
	v_and_b32_e32 v69, 0xffff0000, v188
	v_lshlrev_b32_e32 v76, 16, v184
	v_and_b32_e32 v77, 0xffff0000, v184
	s_waitcnt vmcnt(16)
	v_lshlrev_b32_e32 v66, 16, v190
	v_and_b32_e32 v67, 0xffff0000, v190
	v_lshlrev_b32_e32 v70, 16, v191
	v_lshlrev_b32_e32 v72, 16, v189
	v_and_b32_e32 v71, 0xffff0000, v191
	v_and_b32_e32 v73, 0xffff0000, v189
	v_lshlrev_b32_e32 v74, 16, v186
	v_and_b32_e32 v75, 0xffff0000, v186
	v_lshlrev_b32_e32 v80, 16, v185
	v_and_b32_e32 v81, 0xffff0000, v185
	v_lshlrev_b32_e32 v190, 16, v176
	v_and_b32_e32 v191, 0xffff0000, v176
	v_lshlrev_b32_e32 v176, 16, v177
	v_and_b32_e32 v177, 0xffff0000, v177
	v_pk_mul_f32 v[76:77], v[54:55], v[76:77]
	v_pk_mul_f32 v[68:69], v[34:35], v[68:69]
	v_lshlrev_b32_e32 v78, 16, v187
	v_and_b32_e32 v79, 0xffff0000, v187
	v_lshlrev_b32_e32 v186, 16, v180
	v_and_b32_e32 v187, 0xffff0000, v180
	v_lshlrev_b32_e32 v188, 16, v178
	v_and_b32_e32 v189, 0xffff0000, v178
	v_lshlrev_b32_e32 v178, 16, v179
	v_and_b32_e32 v179, 0xffff0000, v179
	v_pk_mul_f32 v[190:191], v[62:63], v[190:191]
	v_pk_mul_f32 v[176:177], v[64:65], v[176:177]
	v_pk_fma_f32 v[74:75], v[74:75], s[8:9], v[76:77] op_sel_hi:[1,0,1]
	v_pk_mul_f32 v[76:77], v[56:57], v[80:81]
	v_pk_fma_f32 v[66:67], v[66:67], s[8:9], v[68:69] op_sel_hi:[1,0,1]
	v_pk_mul_f32 v[68:69], v[36:37], v[72:73]
	v_lshlrev_b32_e32 v184, 16, v182
	v_and_b32_e32 v185, 0xffff0000, v182
	v_lshlrev_b32_e32 v180, 16, v181
	v_and_b32_e32 v181, 0xffff0000, v181
	v_pk_fma_f32 v[188:189], v[188:189], s[8:9], v[190:191] op_sel_hi:[1,0,1]
	v_pk_fma_f32 v[190:191], v[178:179], s[8:9], v[176:177] op_sel_hi:[1,0,1]
	v_pk_mul_f32 v[176:177], v[58:59], v[186:187]
	v_pk_fma_f32 v[76:77], v[78:79], s[8:9], v[76:77] op_sel_hi:[1,0,1]
	v_pk_fma_f32 v[68:69], v[70:71], s[8:9], v[68:69] op_sel_hi:[1,0,1]
	v_mov_b32_e32 v70, v75
	v_mov_b32_e32 v71, v67
	v_mov_b32_e32 v72, v74
	v_mov_b32_e32 v73, v66
	v_lshlrev_b32_e32 v182, 16, v183
	v_and_b32_e32 v183, 0xffff0000, v183
	v_pk_fma_f32 v[176:177], v[184:185], s[8:9], v[176:177] op_sel_hi:[1,0,1]
	v_pk_mul_f32 v[178:179], v[60:61], v[180:181]
	v_pk_add_f32 v[70:71], v[70:71], v[72:73]
	v_mov_b32_e32 v72, v76
	v_mov_b32_e32 v73, v68
	v_pk_fma_f32 v[178:179], v[182:183], s[8:9], v[178:179] op_sel_hi:[1,0,1]
	v_mov_b32_e32 v180, v189
	v_mov_b32_e32 v181, v177
	v_mov_b32_e32 v182, v188
	v_mov_b32_e32 v183, v176
	v_pk_add_f32 v[70:71], v[72:73], v[70:71]
	v_mov_b32_e32 v72, v77
	v_mov_b32_e32 v73, v69
	v_pk_add_f32 v[180:181], v[180:181], v[182:183]
	v_mov_b32_e32 v182, v190
	v_mov_b32_e32 v183, v178
	v_pk_add_f32 v[70:71], v[72:73], v[70:71]
	v_pk_add_f32 v[180:181], v[182:183], v[180:181]
	v_mov_b32_e32 v182, v191
	v_mov_b32_e32 v183, v179
	v_add_f32_e32 v0, 0, v71
	v_pk_add_f32 v[180:181], v[182:183], v[180:181]
	v_add_f32_e32 v0, v70, v0
	v_add_f32_e32 v0, v181, v0
	v_add_f32_e32 v0, v180, v0
	s_mov_b64 s[16:17], -1
	s_waitcnt lgkmcnt(0)
	v_mov_b32_e32 v70, v0
	s_nop 1
	v_permlane32_swap_b32_e32 v0, v70
	v_add_f32_e32 v0, v0, v70
	v_mov_b32_e32 v70, v0
	s_nop 1
	v_permlane16_swap_b32_e32 v0, v70
	v_add_f32_e32 v0, v0, v70
	s_nop 1
	v_add_f32_dpp v0, v0, v0 row_ror:8 row_mask:0xf bank_mask:0xf
	s_nop 1
	v_add_f32_dpp v0, v0, v0 row_half_mirror row_mask:0xf bank_mask:0xf
	s_nop 1
	v_add_f32_dpp v0, v0, v0 quad_perm:[2,3,0,1] row_mask:0xf bank_mask:0xf
	s_nop 1
	v_add_f32_dpp v0, v0, v0 quad_perm:[1,0,3,2] row_mask:0xf bank_mask:0xf
	v_mul_f32_e32 v0, 0x3a800000, v0
	v_pk_add_f32 v[66:67], v[66:67], v[0:1] op_sel_hi:[1,0] neg_lo:[0,1] neg_hi:[0,1]
	v_pk_add_f32 v[68:69], v[68:69], v[0:1] op_sel_hi:[1,0] neg_lo:[0,1] neg_hi:[0,1]
	v_pk_mul_f32 v[78:79], v[66:67], v[66:67]
	v_pk_mul_f32 v[80:81], v[68:69], v[68:69]
	v_pk_add_f32 v[180:181], v[74:75], v[0:1] op_sel_hi:[1,0] neg_lo:[0,1] neg_hi:[0,1]
	v_pk_add_f32 v[182:183], v[76:77], v[0:1] op_sel_hi:[1,0] neg_lo:[0,1] neg_hi:[0,1]
	v_pk_add_f32 v[176:177], v[176:177], v[0:1] op_sel_hi:[1,0] neg_lo:[0,1] neg_hi:[0,1]
	v_pk_add_f32 v[178:179], v[178:179], v[0:1] op_sel_hi:[1,0] neg_lo:[0,1] neg_hi:[0,1]
	v_pk_add_f32 v[70:71], v[188:189], v[0:1] op_sel_hi:[1,0] neg_lo:[0,1] neg_hi:[0,1]
	v_pk_add_f32 v[72:73], v[190:191], v[0:1] op_sel_hi:[1,0] neg_lo:[0,1] neg_hi:[0,1]
	v_add_f32_e32 v0, v78, v79
	v_add_f32_e32 v0, v80, v0
	v_pk_mul_f32 v[74:75], v[180:181], v[180:181]
	v_add_f32_e32 v0, v81, v0
	v_add_f32_e32 v0, v74, v0
	v_pk_mul_f32 v[76:77], v[182:183], v[182:183]
	v_add_f32_e32 v0, v75, v0
	v_add_f32_e32 v0, v76, v0
	v_pk_mul_f32 v[184:185], v[176:177], v[176:177]
	v_add_f32_e32 v0, v77, v0
	v_add_f32_e32 v0, v184, v0
	v_pk_mul_f32 v[186:187], v[178:179], v[178:179]
	v_add_f32_e32 v0, v185, v0
	v_add_f32_e32 v0, v186, v0
	v_pk_mul_f32 v[188:189], v[70:71], v[70:71]
	v_add_f32_e32 v0, v187, v0
	v_add_f32_e32 v0, v188, v0
	v_pk_mul_f32 v[190:191], v[72:73], v[72:73]
	v_add_f32_e32 v0, v189, v0
	v_add_f32_e32 v0, v190, v0
	v_add_f32_e32 v0, v191, v0
	v_lshl_add_u64 v[76:77], v[84:85], 0, v[98:99]
	s_waitcnt lgkmcnt(0)
	v_mov_b32_e32 v74, v0
	s_nop 1
	v_permlane32_swap_b32_e32 v0, v74
	v_add_f32_e32 v0, v0, v74
	v_mov_b32_e32 v74, v0
	s_nop 1
	v_permlane16_swap_b32_e32 v0, v74
	v_add_f32_e32 v0, v0, v74
	s_nop 1
	v_add_f32_dpp v0, v0, v0 row_ror:8 row_mask:0xf bank_mask:0xf
	s_nop 1
	v_add_f32_dpp v0, v0, v0 row_half_mirror row_mask:0xf bank_mask:0xf
	s_nop 1
	v_add_f32_dpp v0, v0, v0 quad_perm:[2,3,0,1] row_mask:0xf bank_mask:0xf
	s_nop 1
	v_add_f32_dpp v0, v0, v0 quad_perm:[1,0,3,2] row_mask:0xf bank_mask:0xf
	v_fmamk_f32 v0, v0, 0x3a800000, v146
	v_mul_f32_e32 v74, 0x4b800000, v0
	v_cmp_gt_f32_e32 vcc, s54, v0
	s_nop 1
	v_cndmask_b32_e32 v0, v0, v74, vcc
	v_rsq_f32_e32 v0, v0
	s_nop 0
	v_mul_f32_e32 v74, 0x45800000, v0
	v_cndmask_b32_e32 v80, v0, v74, vcc
	v_pk_mul_f32 v[66:67], v[66:67], v[80:81] op_sel_hi:[1,0]
	v_pk_mul_f32 v[68:69], v[68:69], v[80:81] op_sel_hi:[1,0]
	v_pk_fma_f32 v[66:67], v[2:3], v[66:67], v[10:11]
	v_pk_fma_f32 v[68:69], v[4:5], v[68:69], v[12:13]
	s_and_b64 vcc, exec, s[0:1]
	v_lshl_add_u64 v[74:75], v[100:101], 0, v[98:99]
	s_cbranch_vccnz .LBB0_513
	v_cvt_pk_bf16_f32 v78, v66, v67
	v_cvt_pk_bf16_f32 v79, v68, v69
	global_store_dwordx2 v[76:77], v[78:79], off nt
	v_pk_add_f32 v[78:79], v[46:47], 1.0 op_sel_hi:[1,0]
	v_pk_add_f32 v[184:185], v[48:49], 1.0 op_sel_hi:[1,0]
	v_pk_fma_f32 v[78:79], v[78:79], v[66:67], v[38:39]
	v_pk_fma_f32 v[184:185], v[184:185], v[68:69], v[40:41]
	v_cvt_pk_bf16_f32 v78, v78, v79
	v_cvt_pk_bf16_f32 v79, v184, v185
	v_add_co_u32_e32 v184, vcc, 0x14000000, v74
	s_mov_b64 s[16:17], 0
	s_nop 0
	v_addc_co_u32_e32 v185, vcc, 0, v75, vcc
	global_store_dwordx2 v[184:185], v[78:79], off

.LBB0_536:
	s_or_b64 exec, exec, s[18:19]
	v_lshlrev_b32_e32 v68, 16, v170
	v_and_b32_e32 v69, 0xffff0000, v170
	v_lshlrev_b32_e32 v76, 16, v166
	v_and_b32_e32 v77, 0xffff0000, v166
	v_lshlrev_b32_e32 v66, 16, v172
	v_and_b32_e32 v67, 0xffff0000, v172
	v_lshlrev_b32_e32 v70, 16, v173
	v_lshlrev_b32_e32 v72, 16, v171
	v_and_b32_e32 v71, 0xffff0000, v173
	v_and_b32_e32 v73, 0xffff0000, v171
	v_lshlrev_b32_e32 v74, 16, v168
	v_and_b32_e32 v75, 0xffff0000, v168
	v_lshlrev_b32_e32 v80, 16, v167
	v_and_b32_e32 v81, 0xffff0000, v167
	v_lshlrev_b32_e32 v172, 16, v158
	v_and_b32_e32 v173, 0xffff0000, v158
	v_lshlrev_b32_e32 v158, 16, v159
	v_and_b32_e32 v159, 0xffff0000, v159
	v_pk_mul_f32 v[76:77], v[54:55], v[76:77]
	v_pk_mul_f32 v[68:69], v[34:35], v[68:69]
	v_lshlrev_b32_e32 v78, 16, v169
	v_and_b32_e32 v79, 0xffff0000, v169
	v_lshlrev_b32_e32 v168, 16, v162
	v_and_b32_e32 v169, 0xffff0000, v162
	v_lshlrev_b32_e32 v170, 16, v160
	v_and_b32_e32 v171, 0xffff0000, v160
	v_lshlrev_b32_e32 v160, 16, v161
	v_and_b32_e32 v161, 0xffff0000, v161
	v_pk_mul_f32 v[172:173], v[62:63], v[172:173]
	v_pk_mul_f32 v[158:159], v[64:65], v[158:159]
	v_pk_fma_f32 v[74:75], v[74:75], s[8:9], v[76:77] op_sel_hi:[1,0,1]
	v_pk_mul_f32 v[76:77], v[56:57], v[80:81]
	v_pk_fma_f32 v[66:67], v[66:67], s[8:9], v[68:69] op_sel_hi:[1,0,1]
	v_pk_mul_f32 v[68:69], v[36:37], v[72:73]
	v_lshlrev_b32_e32 v166, 16, v164
	v_and_b32_e32 v167, 0xffff0000, v164
	v_lshlrev_b32_e32 v162, 16, v163
	v_and_b32_e32 v163, 0xffff0000, v163
	v_pk_fma_f32 v[170:171], v[170:171], s[8:9], v[172:173] op_sel_hi:[1,0,1]
	v_pk_fma_f32 v[172:173], v[160:161], s[8:9], v[158:159] op_sel_hi:[1,0,1]
	v_pk_mul_f32 v[158:159], v[58:59], v[168:169]
	v_pk_fma_f32 v[76:77], v[78:79], s[8:9], v[76:77] op_sel_hi:[1,0,1]
	v_pk_fma_f32 v[68:69], v[70:71], s[8:9], v[68:69] op_sel_hi:[1,0,1]
	v_mov_b32_e32 v70, v75
	v_mov_b32_e32 v71, v67
	v_mov_b32_e32 v72, v74
	v_mov_b32_e32 v73, v66
	v_lshlrev_b32_e32 v164, 16, v165
	v_and_b32_e32 v165, 0xffff0000, v165
	v_pk_fma_f32 v[158:159], v[166:167], s[8:9], v[158:159] op_sel_hi:[1,0,1]
	v_pk_mul_f32 v[160:161], v[60:61], v[162:163]
	v_pk_add_f32 v[70:71], v[70:71], v[72:73]
	v_mov_b32_e32 v72, v76
	v_mov_b32_e32 v73, v68
	v_pk_fma_f32 v[160:161], v[164:165], s[8:9], v[160:161] op_sel_hi:[1,0,1]
	v_mov_b32_e32 v162, v171
	v_mov_b32_e32 v163, v159
	v_mov_b32_e32 v164, v170
	v_mov_b32_e32 v165, v158
	v_pk_add_f32 v[70:71], v[72:73], v[70:71]
	v_mov_b32_e32 v72, v77
	v_mov_b32_e32 v73, v69
	v_pk_add_f32 v[162:163], v[162:163], v[164:165]
	v_mov_b32_e32 v164, v172
	v_mov_b32_e32 v165, v160
	v_pk_add_f32 v[70:71], v[72:73], v[70:71]
	v_pk_add_f32 v[162:163], v[164:165], v[162:163]
	v_mov_b32_e32 v164, v173
	v_mov_b32_e32 v165, v161
	v_add_f32_e32 v0, 0, v71
	v_pk_add_f32 v[162:163], v[164:165], v[162:163]
	v_add_f32_e32 v0, v70, v0
	v_add_f32_e32 v0, v163, v0
	v_add_f32_e32 v0, v162, v0
	v_ashrrev_i32_e32 v177, 31, v176
	s_mov_b64 s[18:19], -1
	s_waitcnt lgkmcnt(0)
	v_mov_b32_e32 v70, v0
	s_nop 1
	v_permlane32_swap_b32_e32 v0, v70
	v_add_f32_e32 v0, v0, v70
	v_mov_b32_e32 v70, v0
	s_nop 1
	v_permlane16_swap_b32_e32 v0, v70
	v_add_f32_e32 v0, v0, v70
	s_nop 1
	v_add_f32_dpp v0, v0, v0 row_ror:8 row_mask:0xf bank_mask:0xf
	s_nop 1
	v_add_f32_dpp v0, v0, v0 row_half_mirror row_mask:0xf bank_mask:0xf
	s_nop 1
	v_add_f32_dpp v0, v0, v0 quad_perm:[2,3,0,1] row_mask:0xf bank_mask:0xf
	s_nop 1
	v_add_f32_dpp v0, v0, v0 quad_perm:[1,0,3,2] row_mask:0xf bank_mask:0xf
	v_mul_f32_e32 v0, 0x3a800000, v0
	v_pk_add_f32 v[66:67], v[66:67], v[0:1] op_sel_hi:[1,0] neg_lo:[0,1] neg_hi:[0,1]
	v_pk_add_f32 v[68:69], v[68:69], v[0:1] op_sel_hi:[1,0] neg_lo:[0,1] neg_hi:[0,1]
	v_pk_mul_f32 v[70:71], v[66:67], v[66:67]
	v_pk_mul_f32 v[78:79], v[68:69], v[68:69]
	v_pk_add_f32 v[162:163], v[74:75], v[0:1] op_sel_hi:[1,0] neg_lo:[0,1] neg_hi:[0,1]
	v_pk_add_f32 v[164:165], v[76:77], v[0:1] op_sel_hi:[1,0] neg_lo:[0,1] neg_hi:[0,1]
	v_pk_add_f32 v[158:159], v[158:159], v[0:1] op_sel_hi:[1,0] neg_lo:[0,1] neg_hi:[0,1]
	v_pk_add_f32 v[160:161], v[160:161], v[0:1] op_sel_hi:[1,0] neg_lo:[0,1] neg_hi:[0,1]
	v_pk_add_f32 v[72:73], v[170:171], v[0:1] op_sel_hi:[1,0] neg_lo:[0,1] neg_hi:[0,1]
	v_pk_add_f32 v[74:75], v[172:173], v[0:1] op_sel_hi:[1,0] neg_lo:[0,1] neg_hi:[0,1]
	v_add_f32_e32 v0, v70, v71
	v_add_f32_e32 v0, v78, v0
	v_pk_mul_f32 v[80:81], v[162:163], v[162:163]
	v_add_f32_e32 v0, v79, v0
	v_add_f32_e32 v0, v80, v0
	v_pk_mul_f32 v[76:77], v[164:165], v[164:165]
	v_add_f32_e32 v0, v81, v0
	v_add_f32_e32 v0, v76, v0
	v_pk_mul_f32 v[166:167], v[158:159], v[158:159]
	v_add_f32_e32 v0, v77, v0
	v_add_f32_e32 v0, v166, v0
	v_pk_mul_f32 v[168:169], v[160:161], v[160:161]
	v_add_f32_e32 v0, v167, v0
	v_add_f32_e32 v0, v168, v0
	v_pk_mul_f32 v[170:171], v[72:73], v[72:73]
	v_add_f32_e32 v0, v169, v0
	v_add_f32_e32 v0, v170, v0
	v_pk_mul_f32 v[172:173], v[74:75], v[74:75]
	v_add_f32_e32 v0, v171, v0
	v_add_f32_e32 v0, v172, v0
	v_add_f32_e32 v0, v173, v0
	v_lshlrev_b64 v[76:77], 10, v[176:177]
	s_waitcnt lgkmcnt(0)
	v_mov_b32_e32 v70, v0
	s_nop 1
	v_permlane32_swap_b32_e32 v0, v70
	v_add_f32_e32 v0, v0, v70
	v_mov_b32_e32 v70, v0
	s_nop 1
	v_permlane16_swap_b32_e32 v0, v70
	v_add_f32_e32 v0, v0, v70
	s_nop 1
	v_add_f32_dpp v0, v0, v0 row_ror:8 row_mask:0xf bank_mask:0xf
	s_nop 1
	v_add_f32_dpp v0, v0, v0 row_half_mirror row_mask:0xf bank_mask:0xf
	s_nop 1
	v_add_f32_dpp v0, v0, v0 quad_perm:[2,3,0,1] row_mask:0xf bank_mask:0xf
	s_nop 1
	v_add_f32_dpp v0, v0, v0 quad_perm:[1,0,3,2] row_mask:0xf bank_mask:0xf
	v_fmamk_f32 v0, v0, 0x3a800000, v146
	v_mul_f32_e32 v70, 0x4b800000, v0
	v_cmp_gt_f32_e32 vcc, s54, v0
	s_nop 1
	v_cndmask_b32_e32 v0, v0, v70, vcc
	v_rsq_f32_e32 v0, v0
	v_lshlrev_b64 v[70:71], 12, v[176:177]
	v_lshl_add_u64 v[70:71], s[92:93], 0, v[70:71]
	v_mul_f32_e32 v78, 0x45800000, v0
	v_cndmask_b32_e32 v80, v0, v78, vcc
	v_pk_mul_f32 v[66:67], v[66:67], v[80:81] op_sel_hi:[1,0]
	v_pk_mul_f32 v[68:69], v[68:69], v[80:81] op_sel_hi:[1,0]
	v_pk_fma_f32 v[66:67], v[2:3], v[66:67], v[10:11]
	v_pk_fma_f32 v[68:69], v[4:5], v[68:69], v[12:13]
	s_and_b64 vcc, exec, s[0:1]
	v_lshlrev_b32_e32 v0, 1, v82
	s_cbranch_vccnz .LBB0_538
	v_cvt_pk_bf16_f32 v78, v66, v67
	v_cvt_pk_bf16_f32 v79, v68, v69
	v_lshl_add_u64 v[166:167], v[70:71], 0, v[0:1]
	global_store_dwordx2 v[166:167], v[78:79], off nt
	v_pk_add_f32 v[78:79], v[46:47], 1.0 op_sel_hi:[1,0]
	v_pk_add_f32 v[166:167], v[48:49], 1.0 op_sel_hi:[1,0]
	v_pk_fma_f32 v[78:79], v[78:79], v[66:67], v[38:39]
	v_pk_fma_f32 v[166:167], v[166:167], v[68:69], v[40:41]
	v_cvt_pk_bf16_f32 v78, v78, v79
	v_cvt_pk_bf16_f32 v79, v166, v167
	v_lshl_add_u64 v[166:167], v[76:77], 1, v[86:87]
	s_mov_b64 s[18:19], 0
	global_store_dwordx2 v[166:167], v[78:79], off

.LBB0_556:
	s_or_b64 exec, exec, s[12:13]
	v_lshlrev_b32_e32 v186, 16, v152
	v_and_b32_e32 v187, 0xffff0000, v152
	v_lshlrev_b32_e32 v152, 16, v153
	v_and_b32_e32 v153, 0xffff0000, v153
	v_lshlrev_b32_e32 v190, 16, v148
	v_and_b32_e32 v191, 0xffff0000, v148
	v_lshlrev_b32_e32 v184, 16, v154
	v_and_b32_e32 v185, 0xffff0000, v154
	v_lshlrev_b32_e32 v154, 16, v155
	v_and_b32_e32 v155, 0xffff0000, v155
	v_lshlrev_b32_e32 v188, 16, v150
	v_and_b32_e32 v189, 0xffff0000, v150
	v_pk_mul_f32 v[190:191], v[54:55], v[190:191]
	v_lshlrev_b32_e32 v148, 16, v149
	v_and_b32_e32 v149, 0xffff0000, v149
	v_pk_mul_f32 v[152:153], v[44:45], v[152:153]
	v_pk_fma_f32 v[188:189], v[188:189], s[14:15], v[190:191] op_sel_hi:[1,0,1]
	v_lshlrev_b32_e32 v150, 16, v151
	v_and_b32_e32 v151, 0xffff0000, v151
	v_pk_mul_f32 v[148:149], v[56:57], v[148:149]
	v_pk_fma_f32 v[152:153], v[154:155], s[14:15], v[152:153] op_sel_hi:[1,0,1]
	v_pk_mul_f32 v[154:155], v[42:43], v[186:187]
	v_pk_fma_f32 v[148:149], v[150:151], s[14:15], v[148:149] op_sel_hi:[1,0,1]
	v_add_f32_e32 v99, v189, v188
	v_pk_fma_f32 v[154:155], v[184:185], s[14:15], v[154:155] op_sel_hi:[1,0,1]
	v_add_f32_e32 v150, v148, v99
	v_add_f32_e32 v99, v155, v154
	v_add_f32_e32 v99, v152, v99
	v_add_f32_e32 v99, v153, v99
	v_add_f32_e32 v185, 0, v99
	v_lshlrev_b32_e32 v99, 16, v136
	v_and_b32_e32 v206, 0xffff0000, v134
	v_lshlrev_b32_e32 v207, 16, v139
	s_waitcnt vmcnt(2)
	v_pk_mov_b32 v[208:209], v[58:59], v[64:65] op_sel:[1,0]
	v_lshlrev_b32_e32 v192, 16, v138
	v_and_b32_e32 v193, 0xffff0000, v138
	v_mul_f32_e32 v138, 0x3fd744fd, v99
	v_lshlrev_b32_e32 v99, 16, v134
	v_and_b32_e32 v186, 0xffff0000, v136
	v_lshlrev_b32_e32 v187, 16, v141
	v_pk_mul_f32 v[206:207], v[208:209], v[206:207]
	v_lshlrev_b32_e32 v190, 16, v140
	v_and_b32_e32 v191, 0xffff0000, v140
	v_mul_f32_e32 v140, v58, v99
	v_pk_fma_f32 v[186:187], v[186:187], s[14:15], v[206:207] op_sel_hi:[1,0,1]
	v_lshlrev_b32_e32 v206, 16, v137
	v_and_b32_e32 v99, 0xffff0000, v137
	v_pk_mul_f32 v[136:137], v[62:63], v[192:193]
	v_and_b32_e32 v207, 0xffff0000, v141
	v_pk_fma_f32 v[136:137], v[190:191], s[14:15], v[136:137] op_sel_hi:[1,0,1]
	v_lshlrev_b32_e32 v208, 16, v135
	v_and_b32_e32 v209, 0xffff0000, v139
	v_mov_b32_e32 v210, v60
	v_mov_b32_e32 v211, v65
	v_mov_b32_e32 v139, v137
	v_mov_b32_e32 v141, v136
	v_pk_add_f32 v[150:151], v[148:149], v[150:151] op_sel_hi:[1,0]
	v_pk_mul_f32 v[208:209], v[210:211], v[208:209]
	v_mul_f32_e32 v184, 0x3fd744fd, v99
	v_and_b32_e32 v99, 0xffff0000, v135
	v_pk_add_f32 v[138:139], v[138:139], v[140:141]
	v_pk_fma_f32 v[206:207], v[206:207], s[14:15], v[208:209] op_sel_hi:[1,0,1]
	v_mul_f32_e32 v150, v61, v99
	v_pk_add_f32 v[140:141], v[186:187], v[138:139]
	v_pk_add_f32 v[134:135], v[184:185], v[150:151]
	v_pk_add_f32 v[140:141], v[206:207], v[140:141]
	v_mov_b32_e32 v139, v186
	v_pk_add_f32 v[140:141], v[140:141], v[134:135]
	v_ashrrev_i32_e32 v171, 31, v170
	v_add_f32_e32 v99, v140, v141
	v_mov_b32_e32 v140, v187
	v_mov_b32_e32 v141, v207
	v_mov_b32_e32 v207, v134
	s_waitcnt lgkmcnt(0)
	v_mov_b32_e32 v101, v99
	s_nop 1
	v_permlane32_swap_b32_e32 v99, v101
	v_add_f32_e32 v99, v99, v101
	v_mov_b32_e32 v101, v99
	s_nop 1
	v_permlane16_swap_b32_e32 v99, v101
	v_add_f32_e32 v99, v99, v101
	s_nop 1
	v_add_f32_dpp v99, v99, v99 row_ror:8 row_mask:0xf bank_mask:0xf
	s_nop 1
	v_add_f32_dpp v99, v99, v99 row_half_mirror row_mask:0xf bank_mask:0xf
	s_nop 1
	v_add_f32_dpp v99, v99, v99 quad_perm:[2,3,0,1] row_mask:0xf bank_mask:0xf
	s_nop 1
	v_add_f32_dpp v99, v99, v99 quad_perm:[1,0,3,2] row_mask:0xf bank_mask:0xf
	v_mul_f32_e32 v150, 0x3a800000, v99
	v_pk_add_f32 v[154:155], v[154:155], v[150:151] op_sel_hi:[1,0] neg_lo:[0,1] neg_hi:[0,1]
	v_pk_add_f32 v[152:153], v[152:153], v[150:151] op_sel_hi:[1,0] neg_lo:[0,1] neg_hi:[0,1]
	v_pk_mul_f32 v[184:185], v[154:155], v[154:155]
	v_pk_mul_f32 v[190:191], v[152:153], v[152:153]
	v_add_f32_e32 v99, v184, v185
	v_pk_add_f32 v[188:189], v[188:189], v[150:151] op_sel_hi:[1,0] neg_lo:[0,1] neg_hi:[0,1]
	v_add_f32_e32 v99, v190, v99
	v_pk_mul_f32 v[210:211], v[188:189], v[188:189]
	v_add_f32_e32 v99, v191, v99
	v_pk_add_f32 v[148:149], v[148:149], v[150:151] op_sel_hi:[1,0] neg_lo:[0,1] neg_hi:[0,1]
	v_add_f32_e32 v99, v210, v99
	v_pk_mul_f32 v[208:209], v[148:149], v[148:149]
	v_add_f32_e32 v99, v211, v99
	v_pk_add_f32 v[136:137], v[136:137], v[150:151] op_sel_hi:[1,0] neg_lo:[0,1] neg_hi:[0,1]
	v_add_f32_e32 v99, v208, v99
	v_pk_mul_f32 v[192:193], v[136:137], v[136:137]
	v_add_f32_e32 v99, v209, v99
	v_pk_add_f32 v[140:141], v[140:141], v[150:151] op_sel_hi:[1,0] neg_lo:[0,1] neg_hi:[0,1]
	v_add_f32_e32 v99, v192, v99
	v_pk_mul_f32 v[212:213], v[140:141], v[140:141]
	v_add_f32_e32 v99, v193, v99
	v_pk_add_f32 v[138:139], v[138:139], v[150:151] op_sel_hi:[1,0] neg_lo:[0,1] neg_hi:[0,1]
	v_add_f32_e32 v99, v212, v99
	v_pk_add_f32 v[134:135], v[206:207], v[150:151] op_sel_hi:[1,0] neg_lo:[0,1] neg_hi:[0,1]
	v_pk_mul_f32 v[150:151], v[138:139], v[138:139]
	v_add_f32_e32 v99, v213, v99
	v_add_f32_e32 v99, v150, v99
	v_pk_mul_f32 v[206:207], v[134:135], v[134:135]
	v_add_f32_e32 v99, v151, v99
	v_add_f32_e32 v99, v206, v99
	v_add_f32_e32 v99, v207, v99
	v_lshlrev_b64 v[150:151], 12, v[170:171]
	v_lshlrev_b64 v[170:171], 11, v[170:171]
	v_lshl_add_u64 v[184:185], v[88:89], 0, v[170:171]
	v_lshl_add_u64 v[170:171], s[46:47], 0, v[170:171]
	v_lshl_add_u64 v[150:151], v[90:91], 0, v[150:151]
	v_lshl_add_u64 v[186:187], v[170:171], 0, v[0:1]
	s_waitcnt lgkmcnt(0)
	v_mov_b32_e32 v101, v99
	s_nop 1
	v_permlane32_swap_b32_e32 v99, v101
	v_add_f32_e32 v99, v99, v101
	v_mov_b32_e32 v101, v99
	s_nop 1
	v_permlane16_swap_b32_e32 v99, v101
	v_add_f32_e32 v99, v99, v101
	s_nop 1
	v_add_f32_dpp v99, v99, v99 row_ror:8 row_mask:0xf bank_mask:0xf
	s_nop 1
	v_add_f32_dpp v99, v99, v99 row_half_mirror row_mask:0xf bank_mask:0xf
	s_nop 1
	v_add_f32_dpp v99, v99, v99 quad_perm:[2,3,0,1] row_mask:0xf bank_mask:0xf
	s_nop 1
	v_add_f32_dpp v99, v99, v99 quad_perm:[1,0,3,2] row_mask:0xf bank_mask:0xf
	v_fmamk_f32 v99, v99, 0x3a800000, v146
	v_mul_f32_e32 v101, 0x4b800000, v99
	v_cmp_gt_f32_e32 vcc, s54, v99
	s_nop 1
	v_cndmask_b32_e32 v99, v99, v101, vcc
	v_rsq_f32_e32 v101, v99
	v_mov_b32_e32 v99, v1
	v_lshl_add_u64 v[190:191], v[170:171], 0, v[98:99]
	v_mul_f32_e32 v99, 0x45800000, v101
	v_cndmask_b32_e32 v156, v101, v99, vcc
	v_pk_mul_f32 v[154:155], v[154:155], v[156:157] op_sel_hi:[1,0]
	v_pk_mul_f32 v[152:153], v[152:153], v[156:157] op_sel_hi:[1,0]
	v_pk_fma_f32 v[154:155], v[2:3], v[154:155], v[10:11]
	v_pk_fma_f32 v[152:153], v[4:5], v[152:153], v[12:13]
	v_cvt_pk_bf16_f32 v192, v154, v155
	v_cvt_pk_bf16_f32 v193, v152, v153
	v_pk_fma_f32 v[154:155], v[168:169], v[154:155], v[34:35]
	v_pk_fma_f32 v[152:153], v[166:167], v[152:153], v[36:37]
	v_cvt_pk_bf16_f32 v154, v154, v155
	v_cvt_pk_bf16_f32 v155, v152, v153
	v_pk_mul_f32 v[152:153], v[188:189], v[156:157] op_sel_hi:[1,0]
	v_pk_mul_f32 v[148:149], v[148:149], v[156:157] op_sel_hi:[1,0]
	v_pk_fma_f32 v[152:153], v[6:7], v[152:153], v[14:15]
	v_pk_fma_f32 v[148:149], v[8:9], v[148:149], v[16:17]
	v_pk_mul_f32 v[136:137], v[136:137], v[156:157] op_sel_hi:[1,0]
	v_pk_mul_f32 v[140:141], v[140:141], v[156:157] op_sel_hi:[1,0]
	global_store_dwordx2 v[150:151], v[192:193], off nt
	global_store_dwordx2 v[184:185], v[154:155], off
	v_cvt_pk_bf16_f32 v154, v152, v153
	v_cvt_pk_bf16_f32 v155, v148, v149
	v_pk_fma_f32 v[152:153], v[162:163], v[152:153], v[38:39]
	v_pk_fma_f32 v[148:149], v[164:165], v[148:149], v[40:41]
	v_pk_fma_f32 v[136:137], v[18:19], v[136:137], v[26:27]
	v_pk_fma_f32 v[140:141], v[20:21], v[140:141], v[28:29]
	v_cvt_pk_bf16_f32 v152, v152, v153
	v_cvt_pk_bf16_f32 v153, v148, v149
	v_cvt_pk_bf16_f32 v148, v136, v137
	v_cvt_pk_bf16_f32 v149, v140, v141
	s_waitcnt vmcnt(3)
	v_pk_fma_f32 v[136:137], v[160:161], v[136:137], v[70:71]
	v_pk_fma_f32 v[140:141], v[158:159], v[140:141], v[72:73]
	v_cvt_pk_bf16_f32 v136, v136, v137
	v_cvt_pk_bf16_f32 v137, v140, v141
	global_store_dwordx2 v[150:151], v[154:155], off offset:512 nt
	global_store_dwordx2 v[186:187], v[152:153], off
	global_store_dwordx2 v[150:151], v[148:149], off offset:1024 nt
	global_store_dwordx2 v[190:191], v[136:137], off
	v_pk_mul_f32 v[136:137], v[138:139], v[156:157] op_sel_hi:[1,0]
	v_pk_mul_f32 v[134:135], v[134:135], v[156:157] op_sel_hi:[1,0]
	v_pk_fma_f32 v[136:137], v[22:23], v[136:137], v[30:31]
	v_pk_fma_f32 v[134:135], v[24:25], v[134:135], v[32:33]
	v_cvt_pk_bf16_f32 v138, v136, v137
	v_cvt_pk_bf16_f32 v139, v134, v135
	s_waitcnt vmcnt(6)
	v_pk_fma_f32 v[136:137], v[172:173], v[136:137], v[74:75]
	v_pk_fma_f32 v[134:135], v[174:175], v[134:135], v[76:77]
	v_mov_b32_e32 v101, v1
	v_cvt_pk_bf16_f32 v136, v136, v137
	v_cvt_pk_bf16_f32 v137, v134, v135
	v_lshl_add_u64 v[134:135], v[170:171], 0, v[100:101]
	global_store_dwordx2 v[150:151], v[138:139], off offset:1536 nt
	global_store_dwordx2 v[134:135], v[136:137], off

.LBB0_560:
	s_or_b64 exec, exec, s[10:11]
	s_waitcnt vmcnt(20)
	v_lshlrev_b32_e32 v184, 16, v170
	v_and_b32_e32 v185, 0xffff0000, v170
	v_lshlrev_b32_e32 v170, 16, v171
	v_and_b32_e32 v171, 0xffff0000, v171
	v_lshlrev_b32_e32 v188, 16, v166
	v_and_b32_e32 v189, 0xffff0000, v166
	s_waitcnt vmcnt(16)
	v_lshlrev_b32_e32 v174, 16, v172
	v_and_b32_e32 v175, 0xffff0000, v172
	v_lshlrev_b32_e32 v172, 16, v173
	v_and_b32_e32 v173, 0xffff0000, v173
	v_lshlrev_b32_e32 v186, 16, v168
	v_and_b32_e32 v187, 0xffff0000, v168
	s_waitcnt vmcnt(6)
	v_pk_mul_f32 v[188:189], v[54:55], v[188:189]
	v_lshlrev_b32_e32 v166, 16, v167
	v_and_b32_e32 v167, 0xffff0000, v167
	v_pk_mul_f32 v[170:171], v[44:45], v[170:171]
	v_pk_fma_f32 v[186:187], v[186:187], s[14:15], v[188:189] op_sel_hi:[1,0,1]
	v_lshlrev_b32_e32 v168, 16, v169
	v_and_b32_e32 v169, 0xffff0000, v169
	v_pk_mul_f32 v[166:167], v[56:57], v[166:167]
	v_pk_fma_f32 v[170:171], v[172:173], s[14:15], v[170:171] op_sel_hi:[1,0,1]
	v_pk_mul_f32 v[172:173], v[42:43], v[184:185]
	v_pk_fma_f32 v[166:167], v[168:169], s[14:15], v[166:167] op_sel_hi:[1,0,1]
	v_add_f32_e32 v99, v187, v186
	v_pk_fma_f32 v[172:173], v[174:175], s[14:15], v[172:173] op_sel_hi:[1,0,1]
	v_add_f32_e32 v168, v166, v99
	v_add_f32_e32 v99, v173, v172
	v_add_f32_e32 v99, v170, v99
	v_add_f32_e32 v99, v171, v99
	v_add_f32_e32 v175, 0, v99
	v_lshlrev_b32_e32 v99, 16, v160
	v_and_b32_e32 v192, 0xffff0000, v158
	v_lshlrev_b32_e32 v193, 16, v163
	s_waitcnt vmcnt(4)
	v_pk_mov_b32 v[206:207], v[58:59], v[64:65] op_sel:[1,0]
	v_lshlrev_b32_e32 v190, 16, v162
	v_and_b32_e32 v191, 0xffff0000, v162
	v_mul_f32_e32 v162, 0x3fd744fd, v99
	v_lshlrev_b32_e32 v99, 16, v158
	v_and_b32_e32 v184, 0xffff0000, v160
	v_lshlrev_b32_e32 v185, 16, v165
	v_pk_mul_f32 v[192:193], v[206:207], v[192:193]
	v_lshlrev_b32_e32 v188, 16, v164
	v_and_b32_e32 v189, 0xffff0000, v164
	v_mul_f32_e32 v164, v58, v99
	v_pk_fma_f32 v[184:185], v[184:185], s[14:15], v[192:193] op_sel_hi:[1,0,1]
	v_lshlrev_b32_e32 v192, 16, v161
	v_and_b32_e32 v99, 0xffff0000, v161
	v_pk_mul_f32 v[160:161], v[62:63], v[190:191]
	v_and_b32_e32 v193, 0xffff0000, v165
	v_pk_fma_f32 v[160:161], v[188:189], s[14:15], v[160:161] op_sel_hi:[1,0,1]
	v_lshlrev_b32_e32 v206, 16, v159
	v_and_b32_e32 v207, 0xffff0000, v163
	v_mov_b32_e32 v208, v60
	v_mov_b32_e32 v209, v65
	v_mov_b32_e32 v163, v161
	v_mov_b32_e32 v165, v160
	v_pk_add_f32 v[168:169], v[166:167], v[168:169] op_sel_hi:[1,0]
	v_pk_mul_f32 v[206:207], v[208:209], v[206:207]
	v_mul_f32_e32 v174, 0x3fd744fd, v99
	v_and_b32_e32 v99, 0xffff0000, v159
	v_pk_add_f32 v[162:163], v[162:163], v[164:165]
	v_pk_fma_f32 v[192:193], v[192:193], s[14:15], v[206:207] op_sel_hi:[1,0,1]
	v_mul_f32_e32 v168, v61, v99
	v_pk_add_f32 v[164:165], v[184:185], v[162:163]
	v_pk_add_f32 v[158:159], v[174:175], v[168:169]
	v_pk_add_f32 v[164:165], v[192:193], v[164:165]
	v_mov_b32_e32 v163, v184
	v_pk_add_f32 v[164:165], v[164:165], v[158:159]
	s_brev_b32 s2, 40
	v_add_f32_e32 v99, v164, v165
	v_mov_b32_e32 v164, v185
	v_mov_b32_e32 v165, v193
	v_mov_b32_e32 v193, v158
	s_waitcnt lgkmcnt(0)
	v_mov_b32_e32 v101, v99
	s_nop 1
	v_permlane32_swap_b32_e32 v99, v101
	v_add_f32_e32 v99, v99, v101
	v_mov_b32_e32 v101, v99
	s_nop 1
	v_permlane16_swap_b32_e32 v99, v101
	v_add_f32_e32 v99, v99, v101
	s_nop 1
	v_add_f32_dpp v99, v99, v99 row_ror:8 row_mask:0xf bank_mask:0xf
	s_nop 1
	v_add_f32_dpp v99, v99, v99 row_half_mirror row_mask:0xf bank_mask:0xf
	s_nop 1
	v_add_f32_dpp v99, v99, v99 quad_perm:[2,3,0,1] row_mask:0xf bank_mask:0xf
	s_nop 1
	v_add_f32_dpp v99, v99, v99 quad_perm:[1,0,3,2] row_mask:0xf bank_mask:0xf
	v_mul_f32_e32 v168, 0x3a800000, v99
	v_pk_add_f32 v[172:173], v[172:173], v[168:169] op_sel_hi:[1,0] neg_lo:[0,1] neg_hi:[0,1]
	v_pk_add_f32 v[170:171], v[170:171], v[168:169] op_sel_hi:[1,0] neg_lo:[0,1] neg_hi:[0,1]
	v_pk_mul_f32 v[174:175], v[172:173], v[172:173]
	v_pk_mul_f32 v[188:189], v[170:171], v[170:171]
	v_add_f32_e32 v99, v174, v175
	v_pk_add_f32 v[186:187], v[186:187], v[168:169] op_sel_hi:[1,0] neg_lo:[0,1] neg_hi:[0,1]
	v_add_f32_e32 v99, v188, v99
	v_pk_mul_f32 v[208:209], v[186:187], v[186:187]
	v_add_f32_e32 v99, v189, v99
	v_pk_add_f32 v[206:207], v[166:167], v[168:169] op_sel_hi:[1,0] neg_lo:[0,1] neg_hi:[0,1]
	v_add_f32_e32 v99, v208, v99
	v_pk_mul_f32 v[166:167], v[206:207], v[206:207]
	v_add_f32_e32 v99, v209, v99
	v_pk_add_f32 v[190:191], v[160:161], v[168:169] op_sel_hi:[1,0] neg_lo:[0,1] neg_hi:[0,1]
	v_add_f32_e32 v99, v166, v99
	v_pk_mul_f32 v[160:161], v[190:191], v[190:191]
	v_add_f32_e32 v99, v167, v99
	v_pk_add_f32 v[210:211], v[164:165], v[168:169] op_sel_hi:[1,0] neg_lo:[0,1] neg_hi:[0,1]
	v_add_f32_e32 v99, v160, v99
	v_pk_mul_f32 v[164:165], v[210:211], v[210:211]
	v_add_f32_e32 v99, v161, v99
	v_pk_add_f32 v[184:185], v[162:163], v[168:169] op_sel_hi:[1,0] neg_lo:[0,1] neg_hi:[0,1]
	v_add_f32_e32 v99, v164, v99
	v_pk_mul_f32 v[162:163], v[184:185], v[184:185]
	v_add_f32_e32 v99, v165, v99
	v_pk_add_f32 v[192:193], v[192:193], v[168:169] op_sel_hi:[1,0] neg_lo:[0,1] neg_hi:[0,1]
	v_add_f32_e32 v99, v162, v99
	v_pk_mul_f32 v[158:159], v[192:193], v[192:193]
	v_add_f32_e32 v99, v163, v99
	v_add_f32_e32 v99, v158, v99
	v_add_f32_e32 v99, v159, v99
	v_pk_add_f32 v[168:169], v[46:47], 1.0 op_sel_hi:[1,0]
	v_pk_add_f32 v[166:167], v[48:49], 1.0 op_sel_hi:[1,0]
	v_lshl_add_u64 v[188:189], v[84:85], 0, v[96:97]
	v_lshl_add_u64 v[174:175], v[86:87], 0, v[96:97]
	v_pk_add_f32 v[162:163], v[50:51], 1.0 op_sel_hi:[1,0]
	v_pk_add_f32 v[164:165], v[52:53], 1.0 op_sel_hi:[1,0]
	s_waitcnt vmcnt(1)
	v_pk_add_f32 v[160:161], v[66:67], 1.0 op_sel_hi:[1,0]
	v_pk_add_f32 v[158:159], v[68:69], 1.0 op_sel_hi:[1,0]
	s_waitcnt lgkmcnt(0)
	v_mov_b32_e32 v101, v99
	s_nop 1
	v_permlane32_swap_b32_e32 v99, v101
	v_add_f32_e32 v99, v99, v101
	v_mov_b32_e32 v101, v99
	s_nop 1
	v_permlane16_swap_b32_e32 v99, v101
	v_add_f32_e32 v99, v99, v101
	s_nop 1
	v_add_f32_dpp v99, v99, v99 row_ror:8 row_mask:0xf bank_mask:0xf
	s_nop 1
	v_add_f32_dpp v99, v99, v99 row_half_mirror row_mask:0xf bank_mask:0xf
	s_nop 1
	v_add_f32_dpp v99, v99, v99 quad_perm:[2,3,0,1] row_mask:0xf bank_mask:0xf
	s_nop 1
	v_add_f32_dpp v99, v99, v99 quad_perm:[1,0,3,2] row_mask:0xf bank_mask:0xf
	v_fmamk_f32 v99, v99, 0x3a800000, v146
	v_mul_f32_e32 v101, 0x4b800000, v99
	v_cmp_gt_f32_e32 vcc, s54, v99
	s_nop 1
	v_cndmask_b32_e32 v99, v99, v101, vcc
	v_rsq_f32_e32 v99, v99
	s_nop 0
	v_mul_f32_e32 v101, 0x45800000, v99
	v_cndmask_b32_e32 v208, v99, v101, vcc
	v_pk_mul_f32 v[172:173], v[172:173], v[208:209] op_sel_hi:[1,0]
	v_pk_mul_f32 v[170:171], v[170:171], v[208:209] op_sel_hi:[1,0]
	v_pk_fma_f32 v[172:173], v[2:3], v[172:173], v[10:11]
	v_pk_fma_f32 v[170:171], v[4:5], v[170:171], v[12:13]
	v_cvt_pk_bf16_f32 v212, v172, v173
	v_cvt_pk_bf16_f32 v213, v170, v171
	v_pk_fma_f32 v[172:173], v[168:169], v[172:173], v[34:35]
	v_pk_fma_f32 v[170:171], v[166:167], v[170:171], v[36:37]
	v_cvt_pk_bf16_f32 v172, v172, v173
	v_cvt_pk_bf16_f32 v173, v170, v171
	v_add_co_u32_e32 v170, vcc, s2, v188
	global_store_dwordx2 v[174:175], v[212:213], off nt
	s_nop 0
	v_addc_co_u32_e32 v171, vcc, 0, v189, vcc
	global_store_dwordx2 v[170:171], v[172:173], off
	v_pk_mul_f32 v[172:173], v[186:187], v[208:209] op_sel_hi:[1,0]
	v_pk_mul_f32 v[186:187], v[206:207], v[208:209] op_sel_hi:[1,0]
	v_pk_fma_f32 v[172:173], v[6:7], v[172:173], v[14:15]
	v_pk_fma_f32 v[186:187], v[8:9], v[186:187], v[16:17]
	v_cvt_pk_bf16_f32 v188, v172, v173
	v_cvt_pk_bf16_f32 v189, v186, v187
	v_pk_fma_f32 v[172:173], v[162:163], v[172:173], v[38:39]
	v_pk_fma_f32 v[186:187], v[164:165], v[186:187], v[40:41]
	v_cvt_pk_bf16_f32 v172, v172, v173
	v_cvt_pk_bf16_f32 v173, v186, v187
	global_store_dwordx2 v[174:175], v[188:189], off offset:512 nt
	global_store_dwordx2 v[170:171], v[172:173], off offset:512
	v_pk_mul_f32 v[172:173], v[190:191], v[208:209] op_sel_hi:[1,0]
	v_pk_mul_f32 v[186:187], v[210:211], v[208:209] op_sel_hi:[1,0]
	v_pk_fma_f32 v[172:173], v[18:19], v[172:173], v[26:27]
	v_pk_fma_f32 v[186:187], v[20:21], v[186:187], v[28:29]
	v_cvt_pk_bf16_f32 v188, v172, v173
	v_cvt_pk_bf16_f32 v189, v186, v187
	v_pk_fma_f32 v[172:173], v[160:161], v[172:173], v[70:71]
	v_pk_fma_f32 v[186:187], v[158:159], v[186:187], v[72:73]
	v_cvt_pk_bf16_f32 v172, v172, v173
	v_cvt_pk_bf16_f32 v173, v186, v187
	global_store_dwordx2 v[174:175], v[188:189], off offset:1024 nt
	global_store_dwordx2 v[170:171], v[172:173], off offset:1024
	v_pk_mul_f32 v[172:173], v[184:185], v[208:209] op_sel_hi:[1,0]
	s_nop 0
	v_pk_fma_f32 v[184:185], v[22:23], v[172:173], v[30:31]
	v_pk_mul_f32 v[172:173], v[192:193], v[208:209] op_sel_hi:[1,0]
	s_nop 0
	v_pk_fma_f32 v[186:187], v[24:25], v[172:173], v[32:33]
	v_cvt_pk_bf16_f32 v172, v184, v185
	v_cvt_pk_bf16_f32 v173, v186, v187
	global_store_dwordx2 v[174:175], v[172:173], off offset:1536 nt
	s_waitcnt vmcnt(7)
	v_pk_add_f32 v[172:173], v[78:79], 1.0 op_sel_hi:[1,0]
	s_nop 0
	v_pk_fma_f32 v[174:175], v[172:173], v[184:185], v[74:75]
	s_nop 0
	v_cvt_pk_bf16_f32 v184, v174, v175
	v_pk_add_f32 v[174:175], v[80:81], 1.0 op_sel_hi:[1,0]
	s_nop 0
	v_pk_fma_f32 v[186:187], v[174:175], v[186:187], v[76:77]
	s_nop 0
	v_cvt_pk_bf16_f32 v185, v186, v187
	global_store_dwordx2 v[170:171], v[184:185], off offset:1536
	v_add_u32_e32 v170, 1, v156
	v_cmp_lt_i32_e32 vcc, v170, v83
	s_and_saveexec_b64 s[10:11], vcc
	s_cbranch_execz .LBB0_557
	v_add_u32_e32 v99, 0xffffe001, v156
	v_lshrrev_b32_e32 v99, 12, v99
	s_movk_i32 s2, 0x1ffe
	v_add_u32_e32 v99, 1, v99
	v_cmp_lt_i32_e32 vcc, s2, v156
	s_nop 1
	v_cndmask_b32_e32 v99, 0, v99, vcc
	v_cmp_ne_u32_e32 vcc, v99, v183
	s_and_saveexec_b64 s[12:13], vcc
	s_cbranch_execz .LBB0_556
	v_mul_hi_u32_u24_e32 v35, 0x1800, v99
	v_mul_u32_u24_e32 v34, 0x1800, v99
	v_lshlrev_b64 v[34:35], 2, v[34:35]
	v_lshl_add_u64 v[58:59], v[94:95], 0, v[34:35]
	v_lshl_add_u64 v[34:35], s[6:7], 0, v[34:35]
	v_lshlrev_b32_e32 v36, 2, v82
	v_mov_b32_e32 v37, v1
	v_lshl_add_u64 v[74:75], v[34:35], 0, v[36:37]
	s_movk_i32 s2, 0x1000
	v_add_co_u32_e32 v60, vcc, s2, v74
	v_mov_b32_e32 v183, v99
	s_nop 0
	v_addc_co_u32_e32 v61, vcc, 0, v75, vcc
	global_load_dwordx4 v[34:37], v[74:75], off
	global_load_dwordx4 v[38:41], v[74:75], off offset:1024
	global_load_dwordx4 v[46:49], v[60:61], off
	global_load_dwordx4 v[50:53], v[60:61], off offset:1024
	global_load_dwordx4 v[42:45], v[58:59], off
	global_load_dwordx4 v[54:57], v[58:59], off offset:1024
	global_load_dwordx4 v[66:69], v[60:61], off offset:2048
	global_load_dwordx4 v[78:81], v[60:61], off offset:3072
	global_load_dwordx4 v[62:65], v[58:59], off offset:2048
	s_nop 0
	global_load_dwordx4 v[58:61], v[58:59], off offset:3072
	s_nop 0
	global_load_dwordx4 v[70:73], v[74:75], off offset:2048
	s_nop 0
	global_load_dwordx4 v[74:77], v[74:75], off offset:3072
	s_waitcnt vmcnt(9)
	v_pk_add_f32 v[168:169], v[46:47], 1.0 op_sel_hi:[1,0]
	v_pk_add_f32 v[166:167], v[48:49], 1.0 op_sel_hi:[1,0]
	s_waitcnt vmcnt(8)
	v_pk_add_f32 v[162:163], v[50:51], 1.0 op_sel_hi:[1,0]
	v_pk_add_f32 v[164:165], v[52:53], 1.0 op_sel_hi:[1,0]
	s_waitcnt vmcnt(5)
	v_pk_add_f32 v[160:161], v[66:67], 1.0 op_sel_hi:[1,0]
	v_pk_add_f32 v[158:159], v[68:69], 1.0 op_sel_hi:[1,0]
	s_waitcnt vmcnt(4)
	v_pk_add_f32 v[172:173], v[78:79], 1.0 op_sel_hi:[1,0]
	v_pk_add_f32 v[174:175], v[80:81], 1.0 op_sel_hi:[1,0]
	s_branch .LBB0_556

.LBB0_651:
	v_or_b32_e32 v0, 0x10000, v165
	v_add_u32_e32 v126, 0x10400, v165
	ds_read_b128 v[122:125], v0
	ds_read_b128 v[126:129], v126
	v_add_u32_e32 v0, 0x10800, v165
	v_add_u32_e32 v160, 0x10c00, v165
	s_add_i32 s38, s10, 2
	ds_read_b128 v[156:159], v0
	ds_read_b128 v[160:163], v160
	s_add_u32 s36, s0, 0x80
	s_addc_u32 s11, s1, 0
	s_cmp_eq_u32 s76, s10
	s_cselect_b32 s10, s92, s36
	s_cselect_b32 s11, s93, s11
	s_cselect_b32 s37, s95, s7
	s_cselect_b32 s36, s94, s6
	s_mov_b32 m0, s31
	v_lshl_add_u64 v[192:193], s[0:1], 0, v[152:153]
	ds_read_b128 v[168:171], v164
	ds_read_b128 v[172:175], v164 offset:1024
	ds_read_b128 v[176:179], v164 offset:2048
	ds_read_b128 v[180:183], v164 offset:3072
	ds_read_b128 v[184:187], v164 offset:4096
	ds_read_b128 v[188:191], v164 offset:5120
	ds_read_b128 v[206:209], v164 offset:6144
	ds_read_b128 v[210:213], v164 offset:7168
	global_load_lds_dwordx4 v[192:193], off
	v_lshl_add_u64 v[192:193], s[0:1], 0, v[154:155]
	s_mov_b32 m0, s90
	s_nop 0
	global_load_lds_dwordx4 v[192:193], off
	s_waitcnt lgkmcnt(8)
	s_barrier
	s_waitcnt lgkmcnt(0)
	s_setprio 1
	s_waitcnt lgkmcnt(0)
	v_mfma_f32_16x16x32_bf16 v[114:117], v[122:125], v[168:171], v[114:117]
	v_mfma_f32_16x16x32_bf16 v[118:121], v[156:159], v[168:171], v[118:121]
	v_mfma_f32_16x16x32_bf16 v[98:101], v[122:125], v[176:179], v[98:101]
	v_mfma_f32_16x16x32_bf16 v[102:105], v[156:159], v[176:179], v[102:105]
	v_mfma_f32_16x16x32_bf16 v[82:85], v[122:125], v[184:187], v[82:85]
	v_mfma_f32_16x16x32_bf16 v[86:89], v[156:159], v[184:187], v[86:89]
	v_mfma_f32_16x16x32_bf16 v[66:69], v[122:125], v[206:209], v[66:69]
	v_mfma_f32_16x16x32_bf16 v[70:73], v[156:159], v[206:209], v[70:73]
	v_mfma_f32_16x16x32_bf16 v[114:117], v[126:129], v[172:175], v[114:117]
	v_mfma_f32_16x16x32_bf16 v[118:121], v[160:163], v[172:175], v[118:121]
	v_mfma_f32_16x16x32_bf16 v[98:101], v[126:129], v[180:183], v[98:101]
	v_mfma_f32_16x16x32_bf16 v[102:105], v[160:163], v[180:183], v[102:105]
	v_mfma_f32_16x16x32_bf16 v[82:85], v[126:129], v[188:191], v[82:85]
	v_mfma_f32_16x16x32_bf16 v[86:89], v[160:163], v[188:191], v[86:89]
	v_mfma_f32_16x16x32_bf16 v[66:69], v[126:129], v[210:213], v[66:69]
	v_mfma_f32_16x16x32_bf16 v[70:73], v[160:163], v[210:213], v[70:73]
	s_setprio 0
	s_barrier
	v_or_b32_e32 v0, 0x14000, v165
	s_mov_b32 m0, s28
	v_add_u32_e32 v167, 0x14400, v165
	ds_read_b128 v[214:217], v0
	ds_read_b128 v[218:221], v167
	v_add_u32_e32 v0, 0x14800, v165
	v_lshl_add_u64 v[192:193], s[36:37], 0, v[140:141]
	v_add_u32_e32 v167, 0x14c00, v165
	ds_read_b128 v[222:225], v0
	ds_read_b128 v[226:229], v167
	global_load_lds_dwordx4 v[192:193], off
	v_lshl_add_u64 v[230:231], s[36:37], 0, v[150:151]
	s_mov_b32 m0, s29
	s_nop 0
	global_load_lds_dwordx4 v[230:231], off
	s_barrier
	s_waitcnt lgkmcnt(0)
	s_setprio 1
	s_waitcnt lgkmcnt(0)
	v_mfma_f32_16x16x32_bf16 v[106:109], v[214:217], v[168:171], v[106:109]
	v_mfma_f32_16x16x32_bf16 v[110:113], v[222:225], v[168:171], v[110:113]
	v_mfma_f32_16x16x32_bf16 v[90:93], v[214:217], v[176:179], v[90:93]
	v_mfma_f32_16x16x32_bf16 v[94:97], v[222:225], v[176:179], v[94:97]
	v_mfma_f32_16x16x32_bf16 v[74:77], v[214:217], v[184:187], v[74:77]
	v_mfma_f32_16x16x32_bf16 v[78:81], v[222:225], v[184:187], v[78:81]
	v_mfma_f32_16x16x32_bf16 v[58:61], v[214:217], v[206:209], v[58:61]
	v_mfma_f32_16x16x32_bf16 v[62:65], v[222:225], v[206:209], v[62:65]
	v_mfma_f32_16x16x32_bf16 v[106:109], v[218:221], v[172:175], v[106:109]
	v_mfma_f32_16x16x32_bf16 v[110:113], v[226:229], v[172:175], v[110:113]
	v_mfma_f32_16x16x32_bf16 v[90:93], v[218:221], v[180:183], v[90:93]
	v_mfma_f32_16x16x32_bf16 v[94:97], v[226:229], v[180:183], v[94:97]
	v_mfma_f32_16x16x32_bf16 v[74:77], v[218:221], v[188:191], v[74:77]
	v_mfma_f32_16x16x32_bf16 v[78:81], v[226:229], v[188:191], v[78:81]
	v_mfma_f32_16x16x32_bf16 v[58:61], v[218:221], v[210:213], v[58:61]
	v_mfma_f32_16x16x32_bf16 v[62:65], v[226:229], v[210:213], v[62:65]
	s_setprio 0
	s_mov_b32 m0, s25
	v_lshl_add_u64 v[232:233], s[10:11], 0, v[138:139]
	s_barrier
	ds_read_b128 v[168:171], v164 offset:16384
	ds_read_b128 v[172:175], v164 offset:17408
	ds_read_b128 v[176:179], v164 offset:18432
	ds_read_b128 v[180:183], v164 offset:19456
	ds_read_b128 v[184:187], v164 offset:20480
	ds_read_b128 v[188:191], v164 offset:21504
	ds_read_b128 v[206:209], v164 offset:22528
	ds_read_b128 v[210:213], v164 offset:23552
	global_load_lds_dwordx4 v[232:233], off
	v_lshl_add_u64 v[234:235], s[10:11], 0, v[148:149]
	s_mov_b32 m0, s14
	s_nop 0
	global_load_lds_dwordx4 v[234:235], off
	s_barrier
	s_waitcnt lgkmcnt(0)
	s_setprio 1
	s_waitcnt lgkmcnt(0)
	v_mfma_f32_16x16x32_bf16 v[50:53], v[122:125], v[168:171], v[50:53]
	v_mfma_f32_16x16x32_bf16 v[54:57], v[156:159], v[168:171], v[54:57]
	v_mfma_f32_16x16x32_bf16 v[34:37], v[122:125], v[176:179], v[34:37]
	v_mfma_f32_16x16x32_bf16 v[38:41], v[156:159], v[176:179], v[38:41]
	v_mfma_f32_16x16x32_bf16 v[18:21], v[122:125], v[184:187], v[18:21]
	v_mfma_f32_16x16x32_bf16 v[22:25], v[156:159], v[184:187], v[22:25]
	v_mfma_f32_16x16x32_bf16 v[2:5], v[122:125], v[206:209], v[2:5]
	v_mfma_f32_16x16x32_bf16 v[6:9], v[156:159], v[206:209], v[6:9]
	v_mfma_f32_16x16x32_bf16 v[50:53], v[126:129], v[172:175], v[50:53]
	v_mfma_f32_16x16x32_bf16 v[54:57], v[160:163], v[172:175], v[54:57]
	v_mfma_f32_16x16x32_bf16 v[34:37], v[126:129], v[180:183], v[34:37]
	v_mfma_f32_16x16x32_bf16 v[38:41], v[160:163], v[180:183], v[38:41]
	v_mfma_f32_16x16x32_bf16 v[18:21], v[126:129], v[188:191], v[18:21]
	v_mfma_f32_16x16x32_bf16 v[22:25], v[160:163], v[188:191], v[22:25]
	v_mfma_f32_16x16x32_bf16 v[2:5], v[126:129], v[210:213], v[2:5]
	v_mfma_f32_16x16x32_bf16 v[6:9], v[160:163], v[210:213], v[6:9]
	s_setprio 0
	s_barrier
	s_add_u32 s36, s36, s72
	s_addc_u32 s37, s37, 0
	s_mov_b32 m0, s15
	v_lshl_add_u64 v[236:237], s[36:37], 0, v[140:141]
	global_load_lds_dwordx4 v[236:237], off
	v_lshl_add_u64 v[238:239], s[36:37], 0, v[150:151]
	s_mov_b32 m0, s88
	s_nop 0
	global_load_lds_dwordx4 v[238:239], off
	s_waitcnt vmcnt(6)
	s_barrier
	s_setprio 1
	v_mfma_f32_16x16x32_bf16 v[42:45], v[214:217], v[168:171], v[42:45]
	v_mfma_f32_16x16x32_bf16 v[46:49], v[222:225], v[168:171], v[46:49]
	v_mfma_f32_16x16x32_bf16 v[26:29], v[214:217], v[176:179], v[26:29]
	v_mfma_f32_16x16x32_bf16 v[30:33], v[222:225], v[176:179], v[30:33]
	v_mfma_f32_16x16x32_bf16 v[10:13], v[214:217], v[184:187], v[10:13]
	v_mfma_f32_16x16x32_bf16 v[14:17], v[222:225], v[184:187], v[14:17]
	v_mfma_f32_16x16x32_bf16 v[42:45], v[218:221], v[172:175], v[42:45]
	v_mfma_f32_16x16x32_bf16 v[46:49], v[226:229], v[172:175], v[46:49]
	v_mfma_f32_16x16x32_bf16 v[26:29], v[218:221], v[180:183], v[26:29]
	v_mfma_f32_16x16x32_bf16 v[30:33], v[226:229], v[180:183], v[30:33]
	v_mfma_f32_16x16x32_bf16 v[10:13], v[218:221], v[188:191], v[10:13]
	v_mfma_f32_16x16x32_bf16 v[14:17], v[226:229], v[188:191], v[14:17]
	v_mfma_f32_16x16x32_bf16 v[122:125], v[214:217], v[206:209], v[134:137]
	v_mfma_f32_16x16x32_bf16 v[126:129], v[222:225], v[206:209], v[130:133]
	v_mfma_f32_16x16x32_bf16 v[122:125], v[218:221], v[210:213], v[122:125]
	v_mfma_f32_16x16x32_bf16 v[126:129], v[226:229], v[210:213], v[126:129]
	s_setprio 0
	v_or_b32_e32 v0, 0x18000, v165
	v_add_u32_e32 v134, 0x18400, v165
	s_barrier
	ds_read_b128 v[130:133], v0
	ds_read_b128 v[134:137], v134
	v_add_u32_e32 v0, 0x18800, v165
	v_add_u32_e32 v160, 0x18c00, v165
	ds_read_b128 v[156:159], v0
	ds_read_b128 v[160:163], v160
	s_add_u32 s10, s10, s72
	s_addc_u32 s11, s11, 0
	s_mov_b32 m0, s89
	v_lshl_add_u64 v[214:215], s[10:11], 0, v[138:139]
	ds_read_b128 v[168:171], v164 offset:32768
	ds_read_b128 v[172:175], v164 offset:33792
	ds_read_b128 v[176:179], v164 offset:34816
	ds_read_b128 v[180:183], v164 offset:35840
	ds_read_b128 v[184:187], v164 offset:36864
	ds_read_b128 v[188:191], v164 offset:37888
	ds_read_b128 v[206:209], v164 offset:38912
	ds_read_b128 v[210:213], v164 offset:39936
	global_load_lds_dwordx4 v[214:215], off
	v_lshl_add_u64 v[214:215], s[10:11], 0, v[148:149]
	s_mov_b32 m0, s60
	s_nop 0
	global_load_lds_dwordx4 v[214:215], off
	s_waitcnt lgkmcnt(8)
	s_barrier
	s_waitcnt lgkmcnt(0)
	s_setprio 1
	s_waitcnt lgkmcnt(0)
	v_mfma_f32_16x16x32_bf16 v[114:117], v[130:133], v[168:171], v[114:117]
	v_mfma_f32_16x16x32_bf16 v[118:121], v[156:159], v[168:171], v[118:121]
	v_mfma_f32_16x16x32_bf16 v[98:101], v[130:133], v[176:179], v[98:101]
	v_mfma_f32_16x16x32_bf16 v[102:105], v[156:159], v[176:179], v[102:105]
	v_mfma_f32_16x16x32_bf16 v[82:85], v[130:133], v[184:187], v[82:85]
	v_mfma_f32_16x16x32_bf16 v[86:89], v[156:159], v[184:187], v[86:89]
	v_mfma_f32_16x16x32_bf16 v[66:69], v[130:133], v[206:209], v[66:69]
	v_mfma_f32_16x16x32_bf16 v[70:73], v[156:159], v[206:209], v[70:73]
	v_mfma_f32_16x16x32_bf16 v[114:117], v[134:137], v[172:175], v[114:117]
	v_mfma_f32_16x16x32_bf16 v[118:121], v[160:163], v[172:175], v[118:121]
	v_mfma_f32_16x16x32_bf16 v[98:101], v[134:137], v[180:183], v[98:101]
	v_mfma_f32_16x16x32_bf16 v[102:105], v[160:163], v[180:183], v[102:105]
	v_mfma_f32_16x16x32_bf16 v[82:85], v[134:137], v[188:191], v[82:85]
	v_mfma_f32_16x16x32_bf16 v[86:89], v[160:163], v[188:191], v[86:89]
	v_mfma_f32_16x16x32_bf16 v[66:69], v[134:137], v[210:213], v[66:69]
	v_mfma_f32_16x16x32_bf16 v[70:73], v[160:163], v[210:213], v[70:73]
	s_setprio 0
	s_barrier
	v_or_b32_e32 v0, 0x1c000, v165
	s_mov_b32 m0, s50
	v_add_u32_e32 v167, 0x1c400, v165
	ds_read_b128 v[214:217], v0
	ds_read_b128 v[218:221], v167
	v_add_u32_e32 v0, 0x1c800, v165
	v_lshl_add_u64 v[192:193], v[192:193], 0, s[48:49]
	v_add_u32_e32 v167, 0x1cc00, v165
	ds_read_b128 v[222:225], v0
	ds_read_b128 v[226:229], v167
	global_load_lds_dwordx4 v[192:193], off
	v_lshl_add_u64 v[192:193], v[230:231], 0, s[48:49]
	s_mov_b32 m0, s51
	s_nop 0
	global_load_lds_dwordx4 v[192:193], off
	s_barrier
	s_waitcnt lgkmcnt(0)
	s_setprio 1
	s_waitcnt lgkmcnt(0)
	v_mfma_f32_16x16x32_bf16 v[106:109], v[214:217], v[168:171], v[106:109]
	v_mfma_f32_16x16x32_bf16 v[110:113], v[222:225], v[168:171], v[110:113]
	v_mfma_f32_16x16x32_bf16 v[90:93], v[214:217], v[176:179], v[90:93]
	v_mfma_f32_16x16x32_bf16 v[94:97], v[222:225], v[176:179], v[94:97]
	v_mfma_f32_16x16x32_bf16 v[74:77], v[214:217], v[184:187], v[74:77]
	v_mfma_f32_16x16x32_bf16 v[78:81], v[222:225], v[184:187], v[78:81]
	v_mfma_f32_16x16x32_bf16 v[58:61], v[214:217], v[206:209], v[58:61]
	v_mfma_f32_16x16x32_bf16 v[62:65], v[222:225], v[206:209], v[62:65]
	v_mfma_f32_16x16x32_bf16 v[106:109], v[218:221], v[172:175], v[106:109]
	v_mfma_f32_16x16x32_bf16 v[110:113], v[226:229], v[172:175], v[110:113]
	v_mfma_f32_16x16x32_bf16 v[90:93], v[218:221], v[180:183], v[90:93]
	v_mfma_f32_16x16x32_bf16 v[94:97], v[226:229], v[180:183], v[94:97]
	v_mfma_f32_16x16x32_bf16 v[74:77], v[218:221], v[188:191], v[74:77]
	v_mfma_f32_16x16x32_bf16 v[78:81], v[226:229], v[188:191], v[78:81]
	v_mfma_f32_16x16x32_bf16 v[58:61], v[218:221], v[210:213], v[58:61]
	v_mfma_f32_16x16x32_bf16 v[62:65], v[226:229], v[210:213], v[62:65]
	s_setprio 0
	s_mov_b32 m0, s52
	v_lshl_add_u64 v[192:193], v[232:233], 0, s[48:49]
	s_barrier
	ds_read_b128 v[168:171], v164 offset:49152
	ds_read_b128 v[172:175], v164 offset:50176
	ds_read_b128 v[176:179], v164 offset:51200
	ds_read_b128 v[180:183], v164 offset:52224
	ds_read_b128 v[184:187], v164 offset:53248
	ds_read_b128 v[188:191], v164 offset:54272
	ds_read_b128 v[206:209], v164 offset:55296
	ds_read_b128 v[210:213], v164 offset:56320
	global_load_lds_dwordx4 v[192:193], off
	v_lshl_add_u64 v[192:193], v[234:235], 0, s[48:49]
	s_mov_b32 m0, s53
	s_nop 0
	global_load_lds_dwordx4 v[192:193], off
	s_barrier
	s_waitcnt lgkmcnt(0)
	s_setprio 1
	s_waitcnt lgkmcnt(0)
	v_mfma_f32_16x16x32_bf16 v[50:53], v[130:133], v[168:171], v[50:53]
	v_mfma_f32_16x16x32_bf16 v[54:57], v[156:159], v[168:171], v[54:57]
	v_mfma_f32_16x16x32_bf16 v[34:37], v[130:133], v[176:179], v[34:37]
	v_mfma_f32_16x16x32_bf16 v[38:41], v[156:159], v[176:179], v[38:41]
	v_mfma_f32_16x16x32_bf16 v[18:21], v[130:133], v[184:187], v[18:21]
	v_mfma_f32_16x16x32_bf16 v[22:25], v[156:159], v[184:187], v[22:25]
	v_mfma_f32_16x16x32_bf16 v[2:5], v[130:133], v[206:209], v[2:5]
	v_mfma_f32_16x16x32_bf16 v[6:9], v[156:159], v[206:209], v[6:9]
	v_mfma_f32_16x16x32_bf16 v[50:53], v[134:137], v[172:175], v[50:53]
	v_mfma_f32_16x16x32_bf16 v[54:57], v[160:163], v[172:175], v[54:57]
	v_mfma_f32_16x16x32_bf16 v[34:37], v[134:137], v[180:183], v[34:37]
	v_mfma_f32_16x16x32_bf16 v[38:41], v[160:163], v[180:183], v[38:41]
	v_mfma_f32_16x16x32_bf16 v[18:21], v[134:137], v[188:191], v[18:21]
	v_mfma_f32_16x16x32_bf16 v[22:25], v[160:163], v[188:191], v[22:25]
	v_mfma_f32_16x16x32_bf16 v[2:5], v[134:137], v[210:213], v[2:5]
	v_mfma_f32_16x16x32_bf16 v[6:9], v[160:163], v[210:213], v[6:9]
	s_setprio 0
	s_barrier
	s_mov_b32 m0, s80
	v_lshl_add_u64 v[130:131], v[236:237], 0, s[48:49]
	global_load_lds_dwordx4 v[130:131], off
	v_lshl_add_u64 v[130:131], v[238:239], 0, s[48:49]
	s_mov_b32 m0, s58
	s_nop 0
	global_load_lds_dwordx4 v[130:131], off
	s_waitcnt vmcnt(6)
	s_barrier
	s_setprio 1
	v_mfma_f32_16x16x32_bf16 v[122:125], v[214:217], v[206:209], v[122:125]
	v_mfma_f32_16x16x32_bf16 v[42:45], v[214:217], v[168:171], v[42:45]
	v_mfma_f32_16x16x32_bf16 v[46:49], v[222:225], v[168:171], v[46:49]
	v_mfma_f32_16x16x32_bf16 v[26:29], v[214:217], v[176:179], v[26:29]
	v_mfma_f32_16x16x32_bf16 v[30:33], v[222:225], v[176:179], v[30:33]
	v_mfma_f32_16x16x32_bf16 v[10:13], v[214:217], v[184:187], v[10:13]
	v_mfma_f32_16x16x32_bf16 v[14:17], v[222:225], v[184:187], v[14:17]
	v_mfma_f32_16x16x32_bf16 v[134:137], v[218:221], v[210:213], v[122:125]
	v_mfma_f32_16x16x32_bf16 v[122:125], v[222:225], v[206:209], v[126:129]
	v_mfma_f32_16x16x32_bf16 v[42:45], v[218:221], v[172:175], v[42:45]
	v_mfma_f32_16x16x32_bf16 v[46:49], v[226:229], v[172:175], v[46:49]
	v_mfma_f32_16x16x32_bf16 v[26:29], v[218:221], v[180:183], v[26:29]
	v_mfma_f32_16x16x32_bf16 v[30:33], v[226:229], v[180:183], v[30:33]
	v_mfma_f32_16x16x32_bf16 v[10:13], v[218:221], v[188:191], v[10:13]
	v_mfma_f32_16x16x32_bf16 v[14:17], v[226:229], v[188:191], v[14:17]
	v_mfma_f32_16x16x32_bf16 v[130:133], v[226:229], v[210:213], v[122:125]
	s_setprio 0
	s_add_u32 s0, s0, 0x100
	s_addc_u32 s1, s1, 0
	s_add_u32 s6, s6, 0x100
	s_addc_u32 s7, s7, 0
	s_cmp_ge_u32 s38, s59
	s_mov_b32 s10, s38
	s_barrier
	s_cbranch_scc0 .LBB0_651
	v_mov_b32_e32 v160, v166
	s_andn2_b64 vcc, exec, s[74:75]
	v_and_b32_e32 v168, 15, v160
	v_ashrrev_i32_e32 v161, 4, v160
	s_mov_b64 s[0:1], -1
	s_cbranch_vccnz .LBB0_702
	v_cndmask_b32_e64 v0, 0, 1, s[78:79]
	v_cmp_ne_u32_e64 s[0:1], 1, v0
	s_andn2_b64 vcc, exec, s[78:79]
	s_cbranch_vccnz .LBB0_655
	v_max_f32_e32 v122, 0, v114
	v_max_f32_e32 v123, 0, v115
	v_max_f32_e32 v126, 0, v116
	v_max_f32_e32 v127, 0, v117
	v_max_f32_e32 v128, 0, v118
	v_max_f32_e32 v129, 0, v119
	v_max_f32_e32 v156, 0, v120
	v_max_f32_e32 v157, 0, v121
	v_pk_mul_f32 v[124:125], v[122:123], v[122:123]
	v_pk_mul_f32 v[126:127], v[126:127], v[126:127]
	v_pk_mul_f32 v[128:129], v[128:129], v[128:129]
	v_pk_mul_f32 v[156:157], v[156:157], v[156:157]
	s_branch .LBB0_656

.LBB0_656:
	s_lshl_b32 s6, s40, 8
	s_add_i32 s6, s6, s86
	v_or_b32_e32 v0, s6, v168
	s_ashr_i32 s6, s6, 31
	s_mul_i32 s10, s16, s6
	v_mul_lo_u32 v158, s17, v0
	v_mad_u64_u32 v[122:123], s[6:7], s16, v0, 0
	v_add3_u32 v123, v123, s10, v158
	s_lshl_b32 s6, s91, 8
	v_lshl_add_u64 v[122:123], v[122:123], 1, s[56:57]
	s_ashr_i32 s7, s6, 31
	v_lshl_add_u64 v[122:123], s[6:7], 1, v[122:123]
	v_lshlrev_b32_e32 v158, 3, v161
	v_lshl_add_u64 v[122:123], v[122:123], 0, s[8:9]
	v_ashrrev_i32_e32 v159, 31, v158
	v_lshl_add_u64 v[122:123], v[158:159], 1, v[122:123]
	v_cvt_pk_bf16_f32 v124, v124, v125
	v_cvt_pk_bf16_f32 v125, v126, v127
	v_cvt_pk_bf16_f32 v126, v128, v129
	v_cvt_pk_bf16_f32 v127, v156, v157
	s_and_b64 vcc, exec, s[0:1]
	global_store_dwordx4 v[122:123], v[124:127], off
	s_cbranch_vccnz .LBB0_658
	v_max_f32_e32 v124, 0, v106
	v_max_f32_e32 v125, 0, v107
	v_max_f32_e32 v126, 0, v108
	v_max_f32_e32 v127, 0, v109
	v_max_f32_e32 v128, 0, v110
	v_max_f32_e32 v129, 0, v111
	v_max_f32_e32 v156, 0, v112
	v_max_f32_e32 v157, 0, v113
	v_pk_mul_f32 v[124:125], v[124:125], v[124:125]
	v_pk_mul_f32 v[126:127], v[126:127], v[126:127]
	v_pk_mul_f32 v[128:129], v[128:129], v[128:129]
	v_pk_mul_f32 v[156:157], v[156:157], v[156:157]
	s_branch .LBB0_659

.LBB0_659:
	v_cvt_pk_bf16_f32 v124, v124, v125
	v_cvt_pk_bf16_f32 v125, v126, v127
	v_cvt_pk_bf16_f32 v126, v128, v129
	v_cvt_pk_bf16_f32 v127, v156, v157
	s_and_b64 vcc, exec, s[0:1]
	global_store_dwordx4 v[122:123], v[124:127], off offset:256
	s_cbranch_vccnz .LBB0_661
	v_max_f32_e32 v124, 0, v98
	v_max_f32_e32 v125, 0, v99
	v_max_f32_e32 v126, 0, v100
	v_max_f32_e32 v127, 0, v101
	v_max_f32_e32 v128, 0, v102
	v_max_f32_e32 v129, 0, v103
	v_max_f32_e32 v156, 0, v104
	v_max_f32_e32 v157, 0, v105
	v_pk_mul_f32 v[124:125], v[124:125], v[124:125]
	v_pk_mul_f32 v[126:127], v[126:127], v[126:127]
	v_pk_mul_f32 v[128:129], v[128:129], v[128:129]
	v_pk_mul_f32 v[156:157], v[156:157], v[156:157]
	s_branch .LBB0_662

.LBB0_662:
	v_cvt_pk_bf16_f32 v124, v124, v125
	v_cvt_pk_bf16_f32 v125, v126, v127
	v_cvt_pk_bf16_f32 v126, v128, v129
	v_cvt_pk_bf16_f32 v127, v156, v157
	v_lshl_add_u64 v[122:123], v[122:123], 0, s[82:83]
	s_and_b64 vcc, exec, s[0:1]
	global_store_dwordx4 v[122:123], v[124:127], off
	s_cbranch_vccnz .LBB0_664
	v_max_f32_e32 v124, 0, v90
	v_max_f32_e32 v125, 0, v91
	v_max_f32_e32 v126, 0, v92
	v_max_f32_e32 v127, 0, v93
	v_max_f32_e32 v128, 0, v94
	v_max_f32_e32 v129, 0, v95
	v_max_f32_e32 v156, 0, v96
	v_max_f32_e32 v157, 0, v97
	v_pk_mul_f32 v[124:125], v[124:125], v[124:125]
	v_pk_mul_f32 v[126:127], v[126:127], v[126:127]
	v_pk_mul_f32 v[128:129], v[128:129], v[128:129]
	v_pk_mul_f32 v[156:157], v[156:157], v[156:157]
	s_branch .LBB0_665

.LBB0_665:
	v_cvt_pk_bf16_f32 v124, v124, v125
	v_cvt_pk_bf16_f32 v125, v126, v127
	v_cvt_pk_bf16_f32 v126, v128, v129
	v_cvt_pk_bf16_f32 v127, v156, v157
	s_and_b64 vcc, exec, s[0:1]
	global_store_dwordx4 v[122:123], v[124:127], off offset:256
	s_cbranch_vccnz .LBB0_667
	v_max_f32_e32 v124, 0, v82
	v_max_f32_e32 v125, 0, v83
	v_max_f32_e32 v126, 0, v84
	v_max_f32_e32 v127, 0, v85
	v_max_f32_e32 v128, 0, v86
	v_max_f32_e32 v129, 0, v87
	v_max_f32_e32 v156, 0, v88
	v_max_f32_e32 v157, 0, v89
	v_pk_mul_f32 v[124:125], v[124:125], v[124:125]
	v_pk_mul_f32 v[126:127], v[126:127], v[126:127]
	v_pk_mul_f32 v[128:129], v[128:129], v[128:129]
	v_pk_mul_f32 v[156:157], v[156:157], v[156:157]
	s_branch .LBB0_668

.LBB0_668:
	v_cvt_pk_bf16_f32 v124, v124, v125
	v_cvt_pk_bf16_f32 v125, v126, v127
	v_cvt_pk_bf16_f32 v126, v128, v129
	v_cvt_pk_bf16_f32 v127, v156, v157
	v_lshl_add_u64 v[122:123], v[122:123], 0, s[82:83]
	s_and_b64 vcc, exec, s[0:1]
	global_store_dwordx4 v[122:123], v[124:127], off
	s_cbranch_vccnz .LBB0_670
	v_max_f32_e32 v124, 0, v74
	v_max_f32_e32 v125, 0, v75
	v_max_f32_e32 v126, 0, v76
	v_max_f32_e32 v127, 0, v77
	v_max_f32_e32 v128, 0, v78
	v_max_f32_e32 v129, 0, v79
	v_max_f32_e32 v156, 0, v80
	v_max_f32_e32 v157, 0, v81
	v_pk_mul_f32 v[124:125], v[124:125], v[124:125]
	v_pk_mul_f32 v[126:127], v[126:127], v[126:127]
	v_pk_mul_f32 v[128:129], v[128:129], v[128:129]
	v_pk_mul_f32 v[156:157], v[156:157], v[156:157]
	s_branch .LBB0_671

.LBB0_671:
	v_cvt_pk_bf16_f32 v124, v124, v125
	v_cvt_pk_bf16_f32 v125, v126, v127
	v_cvt_pk_bf16_f32 v126, v128, v129
	v_cvt_pk_bf16_f32 v127, v156, v157
	s_and_b64 vcc, exec, s[0:1]
	global_store_dwordx4 v[122:123], v[124:127], off offset:256
	s_cbranch_vccnz .LBB0_673
	v_max_f32_e32 v124, 0, v66
	v_max_f32_e32 v125, 0, v67
	v_max_f32_e32 v126, 0, v68
	v_max_f32_e32 v127, 0, v69
	v_max_f32_e32 v128, 0, v70
	v_max_f32_e32 v129, 0, v71
	v_max_f32_e32 v156, 0, v72
	v_max_f32_e32 v157, 0, v73
	v_pk_mul_f32 v[124:125], v[124:125], v[124:125]
	v_pk_mul_f32 v[126:127], v[126:127], v[126:127]
	v_pk_mul_f32 v[128:129], v[128:129], v[128:129]
	v_pk_mul_f32 v[156:157], v[156:157], v[156:157]
	s_branch .LBB0_674

.LBB0_674:
	v_cvt_pk_bf16_f32 v124, v124, v125
	v_cvt_pk_bf16_f32 v125, v126, v127
	v_cvt_pk_bf16_f32 v126, v128, v129
	v_cvt_pk_bf16_f32 v127, v156, v157
	v_lshl_add_u64 v[122:123], v[122:123], 0, s[82:83]
	s_and_b64 vcc, exec, s[0:1]
	global_store_dwordx4 v[122:123], v[124:127], off
	s_cbranch_vccnz .LBB0_676
	v_max_f32_e32 v124, 0, v58
	v_max_f32_e32 v125, 0, v59
	v_max_f32_e32 v126, 0, v60
	v_max_f32_e32 v127, 0, v61
	v_max_f32_e32 v128, 0, v62
	v_max_f32_e32 v129, 0, v63
	v_max_f32_e32 v156, 0, v64
	v_max_f32_e32 v157, 0, v65
	v_pk_mul_f32 v[124:125], v[124:125], v[124:125]
	v_pk_mul_f32 v[126:127], v[126:127], v[126:127]
	v_pk_mul_f32 v[128:129], v[128:129], v[128:129]
	v_pk_mul_f32 v[156:157], v[156:157], v[156:157]
	s_branch .LBB0_677

.LBB0_677:
	v_cvt_pk_bf16_f32 v124, v124, v125
	v_cvt_pk_bf16_f32 v125, v126, v127
	v_cvt_pk_bf16_f32 v126, v128, v129
	v_cvt_pk_bf16_f32 v127, v156, v157
	s_and_b64 vcc, exec, s[0:1]
	global_store_dwordx4 v[122:123], v[124:127], off offset:256
	s_cbranch_vccnz .LBB0_679
	v_max_f32_e32 v124, 0, v50
	v_max_f32_e32 v125, 0, v51
	v_max_f32_e32 v126, 0, v52
	v_max_f32_e32 v127, 0, v53
	v_max_f32_e32 v128, 0, v54
	v_max_f32_e32 v129, 0, v55
	v_max_f32_e32 v156, 0, v56
	v_max_f32_e32 v157, 0, v57
	v_pk_mul_f32 v[124:125], v[124:125], v[124:125]
	v_pk_mul_f32 v[126:127], v[126:127], v[126:127]
	v_pk_mul_f32 v[128:129], v[128:129], v[128:129]
	v_pk_mul_f32 v[156:157], v[156:157], v[156:157]
	s_branch .LBB0_680

.LBB0_680:
	v_readlane_b32 s6, v240, 10
	v_readlane_b32 s7, v240, 11
	v_cvt_pk_bf16_f32 v124, v124, v125
	v_cvt_pk_bf16_f32 v125, v126, v127
	v_cvt_pk_bf16_f32 v126, v128, v129
	v_cvt_pk_bf16_f32 v127, v156, v157
	v_lshl_add_u64 v[122:123], v[122:123], 0, s[6:7]
	s_and_b64 vcc, exec, s[0:1]
	global_store_dwordx4 v[122:123], v[124:127], off
	s_cbranch_vccnz .LBB0_682
	v_max_f32_e32 v124, 0, v42
	v_max_f32_e32 v125, 0, v43
	v_max_f32_e32 v126, 0, v44
	v_max_f32_e32 v127, 0, v45
	v_max_f32_e32 v128, 0, v46
	v_max_f32_e32 v129, 0, v47
	v_max_f32_e32 v156, 0, v48
	v_max_f32_e32 v157, 0, v49
	v_pk_mul_f32 v[124:125], v[124:125], v[124:125]
	v_pk_mul_f32 v[126:127], v[126:127], v[126:127]
	v_pk_mul_f32 v[128:129], v[128:129], v[128:129]
	v_pk_mul_f32 v[156:157], v[156:157], v[156:157]
	s_branch .LBB0_683

.LBB0_683:
	v_cvt_pk_bf16_f32 v124, v124, v125
	v_cvt_pk_bf16_f32 v125, v126, v127
	v_cvt_pk_bf16_f32 v126, v128, v129
	v_cvt_pk_bf16_f32 v127, v156, v157
	s_and_b64 vcc, exec, s[0:1]
	global_store_dwordx4 v[122:123], v[124:127], off offset:256
	s_cbranch_vccnz .LBB0_685
	v_max_f32_e32 v124, 0, v34
	v_max_f32_e32 v125, 0, v35
	v_max_f32_e32 v126, 0, v36
	v_max_f32_e32 v127, 0, v37
	v_max_f32_e32 v128, 0, v38
	v_max_f32_e32 v129, 0, v39
	v_max_f32_e32 v156, 0, v40
	v_max_f32_e32 v157, 0, v41
	v_pk_mul_f32 v[124:125], v[124:125], v[124:125]
	v_pk_mul_f32 v[126:127], v[126:127], v[126:127]
	v_pk_mul_f32 v[128:129], v[128:129], v[128:129]
	v_pk_mul_f32 v[156:157], v[156:157], v[156:157]
	s_branch .LBB0_686

.LBB0_686:
	v_cvt_pk_bf16_f32 v124, v124, v125
	v_cvt_pk_bf16_f32 v125, v126, v127
	v_cvt_pk_bf16_f32 v126, v128, v129
	v_cvt_pk_bf16_f32 v127, v156, v157
	v_lshl_add_u64 v[122:123], v[122:123], 0, s[82:83]
	s_and_b64 vcc, exec, s[0:1]
	global_store_dwordx4 v[122:123], v[124:127], off
	s_cbranch_vccnz .LBB0_688
	v_max_f32_e32 v124, 0, v26
	v_max_f32_e32 v125, 0, v27
	v_max_f32_e32 v126, 0, v28
	v_max_f32_e32 v127, 0, v29
	v_max_f32_e32 v128, 0, v30
	v_max_f32_e32 v129, 0, v31
	v_max_f32_e32 v156, 0, v32
	v_max_f32_e32 v157, 0, v33
	v_pk_mul_f32 v[124:125], v[124:125], v[124:125]
	v_pk_mul_f32 v[126:127], v[126:127], v[126:127]
	v_pk_mul_f32 v[128:129], v[128:129], v[128:129]
	v_pk_mul_f32 v[156:157], v[156:157], v[156:157]
	s_branch .LBB0_689

.LBB0_689:
	v_cvt_pk_bf16_f32 v124, v124, v125
	v_cvt_pk_bf16_f32 v125, v126, v127
	v_cvt_pk_bf16_f32 v126, v128, v129
	v_cvt_pk_bf16_f32 v127, v156, v157
	s_and_b64 vcc, exec, s[0:1]
	global_store_dwordx4 v[122:123], v[124:127], off offset:256
	s_cbranch_vccnz .LBB0_691
	v_max_f32_e32 v124, 0, v18
	v_max_f32_e32 v125, 0, v19
	v_max_f32_e32 v126, 0, v20
	v_max_f32_e32 v127, 0, v21
	v_max_f32_e32 v128, 0, v22
	v_max_f32_e32 v129, 0, v23
	v_max_f32_e32 v156, 0, v24
	v_max_f32_e32 v157, 0, v25
	v_pk_mul_f32 v[124:125], v[124:125], v[124:125]
	v_pk_mul_f32 v[126:127], v[126:127], v[126:127]
	v_pk_mul_f32 v[128:129], v[128:129], v[128:129]
	v_pk_mul_f32 v[156:157], v[156:157], v[156:157]
	s_branch .LBB0_692

.LBB0_692:
	v_cvt_pk_bf16_f32 v124, v124, v125
	v_cvt_pk_bf16_f32 v125, v126, v127
	v_cvt_pk_bf16_f32 v126, v128, v129
	v_cvt_pk_bf16_f32 v127, v156, v157
	v_lshl_add_u64 v[122:123], v[122:123], 0, s[82:83]
	s_and_b64 vcc, exec, s[0:1]
	global_store_dwordx4 v[122:123], v[124:127], off
	s_cbranch_vccnz .LBB0_694
	v_max_f32_e32 v124, 0, v10
	v_max_f32_e32 v125, 0, v11
	v_max_f32_e32 v126, 0, v12
	v_max_f32_e32 v127, 0, v13
	v_max_f32_e32 v128, 0, v14
	v_max_f32_e32 v129, 0, v15
	v_max_f32_e32 v156, 0, v16
	v_max_f32_e32 v157, 0, v17
	v_pk_mul_f32 v[124:125], v[124:125], v[124:125]
	v_pk_mul_f32 v[126:127], v[126:127], v[126:127]
	v_pk_mul_f32 v[128:129], v[128:129], v[128:129]
	v_pk_mul_f32 v[156:157], v[156:157], v[156:157]
	s_branch .LBB0_695

.LBB0_695:
	v_cvt_pk_bf16_f32 v124, v124, v125
	v_cvt_pk_bf16_f32 v125, v126, v127
	v_cvt_pk_bf16_f32 v126, v128, v129
	v_cvt_pk_bf16_f32 v127, v156, v157
	s_and_b64 vcc, exec, s[0:1]
	global_store_dwordx4 v[122:123], v[124:127], off offset:256
	s_cbranch_vccnz .LBB0_697
	v_max_f32_e32 v124, 0, v2
	v_max_f32_e32 v125, 0, v3
	v_max_f32_e32 v126, 0, v4
	v_max_f32_e32 v127, 0, v5
	v_max_f32_e32 v128, 0, v6
	v_max_f32_e32 v129, 0, v7
	v_max_f32_e32 v156, 0, v8
	v_max_f32_e32 v157, 0, v9
	v_pk_mul_f32 v[124:125], v[124:125], v[124:125]
	v_pk_mul_f32 v[126:127], v[126:127], v[126:127]
	v_pk_mul_f32 v[128:129], v[128:129], v[128:129]
	v_pk_mul_f32 v[156:157], v[156:157], v[156:157]
	s_branch .LBB0_698

.LBB0_698:
	v_cvt_pk_bf16_f32 v124, v124, v125
	v_cvt_pk_bf16_f32 v125, v126, v127
	v_cvt_pk_bf16_f32 v126, v128, v129
	v_cvt_pk_bf16_f32 v127, v156, v157
	v_lshl_add_u64 v[122:123], v[122:123], 0, s[82:83]
	s_and_b64 vcc, exec, s[0:1]
	global_store_dwordx4 v[122:123], v[124:127], off
	s_cbranch_vccnz .LBB0_700
	v_max_f32_e32 v124, 0, v134
	v_max_f32_e32 v125, 0, v135
	v_max_f32_e32 v126, 0, v136
	v_max_f32_e32 v127, 0, v137
	v_max_f32_e32 v128, 0, v130
	v_max_f32_e32 v129, 0, v131
	v_max_f32_e32 v156, 0, v132
	v_max_f32_e32 v157, 0, v133
	v_pk_mul_f32 v[124:125], v[124:125], v[124:125]
	v_pk_mul_f32 v[126:127], v[126:127], v[126:127]
	v_pk_mul_f32 v[128:129], v[128:129], v[128:129]
	v_pk_mul_f32 v[156:157], v[156:157], v[156:157]
	s_branch .LBB0_701
